# v42
# speedup vs baseline: 1.0317x; 1.0165x over previous
; #define WAIT_V(n) asm volatile("s_waitcnt vmcnt(" #n ")" ::: "memory")
; #define WAIT_L(n) asm volatile("s_waitcnt lgkmcnt(" #n ")" ::: "memory")
; #define BAR __builtin_amdgcn_s_barrier()
; #define SCHED __builtin_amdgcn_sched_barrier(0)
; template <int EPI>
; __device__ __forceinline__ void gemm_tile(const Params& p, const bf16* __restrict__ A, const bf16* __restrict__ Bt, const int K,
;                                           const int nt, const int brow, const int bcol, int pm, int pn) {
;     ...
;   for (int t = 0; t < nt - 2; t += 2) {
;     LDB(B0, 0, 0); SCHED; LDA(At, 0, 0); STAGE(SA(1, 1), A, brow + HALF, t + 1);
;     WAIT_L(8); BAR; WAIT_L(0); MMA(0, 0, At, B0); BAR; SCHED;
;     LDB(B1, 0, 1); STAGE(SB(0, 0), Bt, bcol, t + 2);
;     BAR; WAIT_L(0); MMA(0, 1, At, B1); BAR;
;     LDA(At, 0, 1); STAGE(SA(0, 0), A, brow, t + 2);
;     BAR; WAIT_L(0); MMA(1, 0, At, B0); BAR; SCHED;
;     STAGE(SB(0, 1), Bt, bcol + HALF, t + 2);
;     WAIT_V(6); BAR; MMA(1, 1, At, B1); BAR;
;     LDB(B0, 1, 0); SCHED; LDA(At, 1, 0); STAGE(SA(0, 1), A, brow + HALF, t + 2);
;     WAIT_L(8); BAR; WAIT_L(0); MMA(0, 0, At, B0); BAR; SCHED;
;     LDB(B1, 1, 1); STAGE(SB(1, 0), Bt, bcol, t + 3);
;     BAR; WAIT_L(0); MMA(0, 1, At, B1); BAR;
;     LDA(At, 1, 1); STAGE(SA(1, 0), A, brow, t + 3);
;     BAR; WAIT_L(0); MMA(1, 0, At, B0); BAR; SCHED;
;     STAGE(SB(1, 1), Bt, bcol + HALF, t + 3);
;     WAIT_V(6); BAR; MMA(1, 1, At, B1); BAR;
;   }
.LBB0_116:
	ds_read_b128 v[156:159], v153
	ds_read_b128 v[160:163], v153 offset:1024
	ds_read_b128 v[164:167], v153 offset:2048
	ds_read_b128 v[168:171], v153 offset:3072
	v_readfirstlane_b32 s11, v154
	v_lshl_add_u64 v[204:205], v[130:131], 0, s[8:9]
	s_mov_b32 m0, s11
	v_readfirstlane_b32 s11, v155
	ds_read_b128 v[172:175], v135
	ds_read_b128 v[176:179], v135 offset:1024
	ds_read_b128 v[180:183], v134
	ds_read_b128 v[184:187], v134 offset:1024
	ds_read_b128 v[188:191], v133
	ds_read_b128 v[192:195], v133 offset:1024
	ds_read_b128 v[196:199], v132
	ds_read_b128 v[200:203], v132 offset:1024
	global_load_lds_dwordx4 v[204:205], off
	v_lshl_add_u64 v[204:205], v[130:131], 0, s[12:13]
	s_mov_b32 m0, s11
	s_nop 0
	global_load_lds_dwordx4 v[204:205], off
	s_waitcnt lgkmcnt(8)
	s_setprio 1
	s_barrier
	s_waitcnt lgkmcnt(0)
	v_mfma_f32_16x16x32_bf16 v[124:127], v[172:175], v[156:159], v[124:127]
	v_mfma_f32_16x16x32_bf16 v[120:123], v[172:175], v[164:167], v[120:123]
	v_mfma_f32_16x16x32_bf16 v[116:119], v[180:183], v[156:159], v[116:119]
	v_mfma_f32_16x16x32_bf16 v[112:115], v[180:183], v[164:167], v[112:115]
	v_mfma_f32_16x16x32_bf16 v[108:111], v[188:191], v[156:159], v[108:111]
	v_mfma_f32_16x16x32_bf16 v[104:107], v[188:191], v[164:167], v[104:107]
	v_mfma_f32_16x16x32_bf16 v[100:103], v[196:199], v[156:159], v[100:103]
	v_mfma_f32_16x16x32_bf16 v[96:99], v[196:199], v[164:167], v[96:99]
	v_mfma_f32_16x16x32_bf16 v[124:127], v[176:179], v[160:163], v[124:127]
	v_mfma_f32_16x16x32_bf16 v[120:123], v[176:179], v[168:171], v[120:123]
	v_mfma_f32_16x16x32_bf16 v[116:119], v[184:187], v[160:163], v[116:119]
	v_mfma_f32_16x16x32_bf16 v[112:115], v[184:187], v[168:171], v[112:115]
	v_mfma_f32_16x16x32_bf16 v[108:111], v[192:195], v[160:163], v[108:111]
	v_mfma_f32_16x16x32_bf16 v[104:107], v[192:195], v[168:171], v[104:107]
	v_mfma_f32_16x16x32_bf16 v[100:103], v[200:203], v[160:163], v[100:103]
	v_mfma_f32_16x16x32_bf16 v[96:99], v[200:203], v[168:171], v[96:99]
	s_barrier
	s_setprio 0
	v_lshl_add_u64 v[204:205], v[130:131], 0, s[4:5]
	v_readfirstlane_b32 s11, v137
	v_lshl_add_u64 v[224:225], v[204:205], 0, s[14:15]
	s_mov_b32 m0, s11
	v_readfirstlane_b32 s11, v138
	ds_read_b128 v[208:211], v151
	ds_read_b128 v[212:215], v151 offset:1024
	ds_read_b128 v[216:219], v151 offset:2048
	ds_read_b128 v[220:223], v151 offset:3072
	global_load_lds_dwordx4 v[224:225], off
	v_lshl_add_u64 v[224:225], v[204:205], 0, s[16:17]
	s_mov_b32 m0, s11
	s_nop 0
	global_load_lds_dwordx4 v[224:225], off
	s_setprio 1
	s_barrier
	s_waitcnt lgkmcnt(0)
	v_mfma_f32_16x16x32_bf16 v[92:95], v[172:175], v[208:211], v[92:95]
	v_mfma_f32_16x16x32_bf16 v[88:91], v[172:175], v[216:219], v[88:91]
	v_mfma_f32_16x16x32_bf16 v[84:87], v[180:183], v[208:211], v[84:87]
	v_mfma_f32_16x16x32_bf16 v[80:83], v[180:183], v[216:219], v[80:83]
	v_mfma_f32_16x16x32_bf16 v[76:79], v[188:191], v[208:211], v[76:79]
	v_mfma_f32_16x16x32_bf16 v[72:75], v[188:191], v[216:219], v[72:75]
	v_mfma_f32_16x16x32_bf16 v[68:71], v[196:199], v[208:211], v[68:71]
	v_mfma_f32_16x16x32_bf16 v[64:67], v[196:199], v[216:219], v[64:67]
	v_mfma_f32_16x16x32_bf16 v[92:95], v[176:179], v[212:215], v[92:95]
	v_mfma_f32_16x16x32_bf16 v[88:91], v[176:179], v[220:223], v[88:91]
	v_mfma_f32_16x16x32_bf16 v[84:87], v[184:187], v[212:215], v[84:87]
	v_mfma_f32_16x16x32_bf16 v[80:83], v[184:187], v[220:223], v[80:83]
	v_mfma_f32_16x16x32_bf16 v[76:79], v[192:195], v[212:215], v[76:79]
	v_mfma_f32_16x16x32_bf16 v[72:75], v[192:195], v[220:223], v[72:75]
	v_mfma_f32_16x16x32_bf16 v[68:71], v[200:203], v[212:215], v[68:71]
	v_mfma_f32_16x16x32_bf16 v[64:67], v[200:203], v[220:223], v[64:67]
	s_barrier
	s_setprio 0
	v_readfirstlane_b32 s11, v136
	s_mov_b32 m0, s11
	v_readfirstlane_b32 s11, v140
	ds_read_b128 v[172:175], v135 offset:16384
	ds_read_b128 v[176:179], v135 offset:17408
	ds_read_b128 v[180:183], v134 offset:16384
	ds_read_b128 v[184:187], v134 offset:17408
	ds_read_b128 v[188:191], v133 offset:16384
	ds_read_b128 v[192:195], v133 offset:17408
	ds_read_b128 v[196:199], v132 offset:16384
	ds_read_b128 v[200:203], v132 offset:17408
	global_load_lds_dwordx4 v[130:131], off
	v_lshl_add_u64 v[224:225], v[130:131], 0, s[18:19]
	s_mov_b32 m0, s11
	s_nop 0
	global_load_lds_dwordx4 v[224:225], off
	s_setprio 1
	s_barrier
	s_waitcnt lgkmcnt(0)
	v_mfma_f32_16x16x32_bf16 v[60:63], v[172:175], v[156:159], v[60:63]
	v_mfma_f32_16x16x32_bf16 v[56:59], v[172:175], v[164:167], v[56:59]
	v_mfma_f32_16x16x32_bf16 v[52:55], v[180:183], v[156:159], v[52:55]
	v_mfma_f32_16x16x32_bf16 v[48:51], v[180:183], v[164:167], v[48:51]
	v_mfma_f32_16x16x32_bf16 v[44:47], v[188:191], v[156:159], v[44:47]
	v_mfma_f32_16x16x32_bf16 v[40:43], v[188:191], v[164:167], v[40:43]
	v_mfma_f32_16x16x32_bf16 v[36:39], v[196:199], v[156:159], v[36:39]
	v_mfma_f32_16x16x32_bf16 v[32:35], v[196:199], v[164:167], v[32:35]
	v_mfma_f32_16x16x32_bf16 v[60:63], v[176:179], v[160:163], v[60:63]
	v_mfma_f32_16x16x32_bf16 v[56:59], v[176:179], v[168:171], v[56:59]
	v_mfma_f32_16x16x32_bf16 v[52:55], v[184:187], v[160:163], v[52:55]
	v_mfma_f32_16x16x32_bf16 v[48:51], v[184:187], v[168:171], v[48:51]
	v_mfma_f32_16x16x32_bf16 v[44:47], v[192:195], v[160:163], v[44:47]
	v_mfma_f32_16x16x32_bf16 v[40:43], v[192:195], v[168:171], v[40:43]
	v_mfma_f32_16x16x32_bf16 v[36:39], v[200:203], v[160:163], v[36:39]
	v_mfma_f32_16x16x32_bf16 v[32:35], v[200:203], v[168:171], v[32:35]
	s_barrier
	s_setprio 0
	v_readfirstlane_b32 s11, v141
	v_lshl_add_u64 v[156:157], v[204:205], 0, s[20:21]
	s_mov_b32 m0, s11
	v_readfirstlane_b32 s11, v142
	global_load_lds_dwordx4 v[156:157], off
	v_lshl_add_u64 v[156:157], v[204:205], 0, s[22:23]
	s_mov_b32 m0, s11
	s_nop 0
	global_load_lds_dwordx4 v[156:157], off
	s_waitcnt vmcnt(6)
	s_setprio 1
	s_barrier
; #define WAIT_V(n) asm volatile("s_waitcnt vmcnt(" #n ")" ::: "memory")
; #define WAIT_L(n) asm volatile("s_waitcnt lgkmcnt(" #n ")" ::: "memory")
; #define BAR __builtin_amdgcn_s_barrier()
; #define SCHED __builtin_amdgcn_sched_barrier(0)
; template <int EPI>
; __device__ __forceinline__ void gemm_tile(const Params& p, const bf16* __restrict__ A, const bf16* __restrict__ Bt, const int K,
;                                           const int nt, const int brow, const int bcol, int pm, int pn) {
;     ...
;   for (int t = 0; t < nt - 2; t += 2) {
;     LDB(B0, 0, 0); SCHED; LDA(At, 0, 0); STAGE(SA(1, 1), A, brow + HALF, t + 1);
;     WAIT_L(8); BAR; WAIT_L(0); MMA(0, 0, At, B0); BAR; SCHED;
;     LDB(B1, 0, 1); STAGE(SB(0, 0), Bt, bcol, t + 2);
;     BAR; WAIT_L(0); MMA(0, 1, At, B1); BAR;
;     LDA(At, 0, 1); STAGE(SA(0, 0), A, brow, t + 2);
;     BAR; WAIT_L(0); MMA(1, 0, At, B0); BAR; SCHED;
;     STAGE(SB(0, 1), Bt, bcol + HALF, t + 2);
;     WAIT_V(6); BAR; MMA(1, 1, At, B1); BAR;
;     LDB(B0, 1, 0); SCHED; LDA(At, 1, 0); STAGE(SA(0, 1), A, brow + HALF, t + 2);
;     WAIT_L(8); BAR; WAIT_L(0); MMA(0, 0, At, B0); BAR; SCHED;
;     LDB(B1, 1, 1); STAGE(SB(1, 0), Bt, bcol, t + 3);
;     BAR; WAIT_L(0); MMA(0, 1, At, B1); BAR;
;     LDA(At, 1, 1); STAGE(SA(1, 0), A, brow, t + 3);
;     BAR; WAIT_L(0); MMA(1, 0, At, B0); BAR; SCHED;
;     STAGE(SB(1, 1), Bt, bcol + HALF, t + 3);
;     WAIT_V(6); BAR; MMA(1, 1, At, B1); BAR;
;   }
	v_mfma_f32_16x16x32_bf16 v[28:31], v[172:175], v[208:211], v[28:31]
	v_mfma_f32_16x16x32_bf16 v[24:27], v[172:175], v[216:219], v[24:27]
	v_mfma_f32_16x16x32_bf16 v[20:23], v[180:183], v[208:211], v[20:23]
	v_mfma_f32_16x16x32_bf16 v[16:19], v[180:183], v[216:219], v[16:19]
	v_mfma_f32_16x16x32_bf16 v[12:15], v[188:191], v[208:211], v[12:15]
	v_mfma_f32_16x16x32_bf16 v[8:11], v[188:191], v[216:219], v[8:11]
	v_mfma_f32_16x16x32_bf16 v[4:7], v[196:199], v[208:211], v[4:7]
	v_mfma_f32_16x16x32_bf16 v[0:3], v[196:199], v[216:219], v[0:3]
	v_mfma_f32_16x16x32_bf16 v[28:31], v[176:179], v[212:215], v[28:31]
	v_mfma_f32_16x16x32_bf16 v[24:27], v[176:179], v[220:223], v[24:27]
	v_mfma_f32_16x16x32_bf16 v[20:23], v[184:187], v[212:215], v[20:23]
	v_mfma_f32_16x16x32_bf16 v[16:19], v[184:187], v[220:223], v[16:19]
	v_mfma_f32_16x16x32_bf16 v[12:15], v[192:195], v[212:215], v[12:15]
	v_mfma_f32_16x16x32_bf16 v[8:11], v[192:195], v[220:223], v[8:11]
	v_mfma_f32_16x16x32_bf16 v[4:7], v[200:203], v[212:215], v[4:7]
	v_mfma_f32_16x16x32_bf16 v[0:3], v[200:203], v[220:223], v[0:3]
	s_barrier
	s_setprio 0
	ds_read_b128 v[156:159], v144
	ds_read_b128 v[160:163], v144 offset:1024
	ds_read_b128 v[164:167], v144 offset:2048
	ds_read_b128 v[168:171], v144 offset:3072
	v_readfirstlane_b32 s11, v143
	v_lshl_add_u64 v[208:209], v[130:131], 0, s[24:25]
	s_mov_b32 m0, s11
	v_readfirstlane_b32 s11, v145
	ds_read_b128 v[172:175], v135 offset:32768
	ds_read_b128 v[176:179], v135 offset:33792
	ds_read_b128 v[180:183], v134 offset:32768
	ds_read_b128 v[184:187], v134 offset:33792
	ds_read_b128 v[188:191], v133 offset:32768
	ds_read_b128 v[192:195], v133 offset:33792
	ds_read_b128 v[196:199], v132 offset:32768
	ds_read_b128 v[200:203], v132 offset:33792
	global_load_lds_dwordx4 v[208:209], off
	v_lshl_add_u64 v[208:209], v[130:131], 0, s[26:27]
	s_mov_b32 m0, s11
	s_nop 0
	global_load_lds_dwordx4 v[208:209], off
	s_waitcnt lgkmcnt(8)
	s_setprio 1
	s_barrier
	s_waitcnt lgkmcnt(0)
	v_mfma_f32_16x16x32_bf16 v[124:127], v[172:175], v[156:159], v[124:127]
	v_mfma_f32_16x16x32_bf16 v[120:123], v[172:175], v[164:167], v[120:123]
	v_mfma_f32_16x16x32_bf16 v[116:119], v[180:183], v[156:159], v[116:119]
	v_mfma_f32_16x16x32_bf16 v[112:115], v[180:183], v[164:167], v[112:115]
	v_mfma_f32_16x16x32_bf16 v[108:111], v[188:191], v[156:159], v[108:111]
	v_mfma_f32_16x16x32_bf16 v[104:107], v[188:191], v[164:167], v[104:107]
	v_mfma_f32_16x16x32_bf16 v[100:103], v[196:199], v[156:159], v[100:103]
	v_mfma_f32_16x16x32_bf16 v[96:99], v[196:199], v[164:167], v[96:99]
	v_mfma_f32_16x16x32_bf16 v[124:127], v[176:179], v[160:163], v[124:127]
	v_mfma_f32_16x16x32_bf16 v[120:123], v[176:179], v[168:171], v[120:123]
	v_mfma_f32_16x16x32_bf16 v[116:119], v[184:187], v[160:163], v[116:119]
	v_mfma_f32_16x16x32_bf16 v[112:115], v[184:187], v[168:171], v[112:115]
	v_mfma_f32_16x16x32_bf16 v[108:111], v[192:195], v[160:163], v[108:111]
	v_mfma_f32_16x16x32_bf16 v[104:107], v[192:195], v[168:171], v[104:107]
	v_mfma_f32_16x16x32_bf16 v[100:103], v[200:203], v[160:163], v[100:103]
	v_mfma_f32_16x16x32_bf16 v[96:99], v[200:203], v[168:171], v[96:99]
	s_barrier
	s_setprio 0
	v_readfirstlane_b32 s11, v146
	v_lshl_add_u64 v[224:225], v[204:205], 0, s[28:29]
	s_mov_b32 m0, s11
	v_readfirstlane_b32 s11, v147
	ds_read_b128 v[208:211], v139
	ds_read_b128 v[212:215], v139 offset:1024
	ds_read_b128 v[216:219], v139 offset:2048
	ds_read_b128 v[220:223], v139 offset:3072
	global_load_lds_dwordx4 v[224:225], off
	v_lshl_add_u64 v[224:225], v[204:205], 0, s[30:31]
	s_mov_b32 m0, s11
	s_nop 0
	global_load_lds_dwordx4 v[224:225], off
	s_setprio 1
	s_barrier
	s_waitcnt lgkmcnt(0)
	v_mfma_f32_16x16x32_bf16 v[92:95], v[172:175], v[208:211], v[92:95]
	v_mfma_f32_16x16x32_bf16 v[88:91], v[172:175], v[216:219], v[88:91]
	v_mfma_f32_16x16x32_bf16 v[84:87], v[180:183], v[208:211], v[84:87]
	v_mfma_f32_16x16x32_bf16 v[80:83], v[180:183], v[216:219], v[80:83]
	v_mfma_f32_16x16x32_bf16 v[76:79], v[188:191], v[208:211], v[76:79]
	v_mfma_f32_16x16x32_bf16 v[72:75], v[188:191], v[216:219], v[72:75]
	v_mfma_f32_16x16x32_bf16 v[68:71], v[196:199], v[208:211], v[68:71]
	v_mfma_f32_16x16x32_bf16 v[64:67], v[196:199], v[216:219], v[64:67]
	v_mfma_f32_16x16x32_bf16 v[92:95], v[176:179], v[212:215], v[92:95]
	v_mfma_f32_16x16x32_bf16 v[88:91], v[176:179], v[220:223], v[88:91]
	v_mfma_f32_16x16x32_bf16 v[84:87], v[184:187], v[212:215], v[84:87]
	v_mfma_f32_16x16x32_bf16 v[80:83], v[184:187], v[220:223], v[80:83]
	v_mfma_f32_16x16x32_bf16 v[76:79], v[192:195], v[212:215], v[76:79]
	v_mfma_f32_16x16x32_bf16 v[72:75], v[192:195], v[220:223], v[72:75]
	v_mfma_f32_16x16x32_bf16 v[68:71], v[200:203], v[212:215], v[68:71]
	v_mfma_f32_16x16x32_bf16 v[64:67], v[200:203], v[220:223], v[64:67]
	s_barrier
	s_setprio 0
	v_readfirstlane_b32 s11, v148
	v_lshl_add_u64 v[224:225], v[130:131], 0, s[6:7]
	s_mov_b32 m0, s11
	v_readfirstlane_b32 s11, v149
	ds_read_b128 v[172:175], v135 offset:49152
	ds_read_b128 v[176:179], v135 offset:50176
	ds_read_b128 v[180:183], v134 offset:49152
	ds_read_b128 v[184:187], v134 offset:50176
	ds_read_b128 v[188:191], v133 offset:49152
	ds_read_b128 v[192:195], v133 offset:50176
	ds_read_b128 v[196:199], v132 offset:49152
	ds_read_b128 v[200:203], v132 offset:50176
	global_load_lds_dwordx4 v[224:225], off
	v_lshl_add_u64 v[224:225], v[130:131], 0, s[34:35]
	s_mov_b32 m0, s11
	s_nop 0
	global_load_lds_dwordx4 v[224:225], off
	s_setprio 1
	s_barrier
; #define WAIT_V(n) asm volatile("s_waitcnt vmcnt(" #n ")" ::: "memory")
; #define WAIT_L(n) asm volatile("s_waitcnt lgkmcnt(" #n ")" ::: "memory")
; #define BAR __builtin_amdgcn_s_barrier()
; #define SCHED __builtin_amdgcn_sched_barrier(0)
; template <int EPI>
; __device__ __forceinline__ void gemm_tile(const Params& p, const bf16* __restrict__ A, const bf16* __restrict__ Bt, const int K,
;                                           const int nt, const int brow, const int bcol, int pm, int pn) {
;     ...
;     WAIT_V(6); BAR; MMA(1, 1, At, B1); BAR;
;     LDB(B0, 1, 0); SCHED; LDA(At, 1, 0); STAGE(SA(0, 1), A, brow + HALF, t + 2);
;     WAIT_L(8); BAR; WAIT_L(0); MMA(0, 0, At, B0); BAR; SCHED;
;     LDB(B1, 1, 1); STAGE(SB(1, 0), Bt, bcol, t + 3);
;     BAR; WAIT_L(0); MMA(0, 1, At, B1); BAR;
;     LDA(At, 1, 1); STAGE(SA(1, 0), A, brow, t + 3);
;     BAR; WAIT_L(0); MMA(1, 0, At, B0); BAR; SCHED;
;     STAGE(SB(1, 1), Bt, bcol + HALF, t + 3);
;     WAIT_V(6); BAR; MMA(1, 1, At, B1); BAR;
;   }
;   { LDB(B0, 0, 0); LDA(At, 0, 0); STAGE(SA(1, 1), A, brow + HALF, nt - 1);
;     BAR; WAIT_L(0); MMA(0, 0, At, B0); BAR;
;     LDB(B1, 0, 1); BAR; WAIT_L(0); MMA(0, 1, At, B1); BAR;
	s_waitcnt lgkmcnt(0)
	v_mfma_f32_16x16x32_bf16 v[60:63], v[172:175], v[156:159], v[60:63]
	v_mfma_f32_16x16x32_bf16 v[56:59], v[172:175], v[164:167], v[56:59]
	v_mfma_f32_16x16x32_bf16 v[52:55], v[180:183], v[156:159], v[52:55]
	v_mfma_f32_16x16x32_bf16 v[48:51], v[180:183], v[164:167], v[48:51]
	v_mfma_f32_16x16x32_bf16 v[44:47], v[188:191], v[156:159], v[44:47]
	v_mfma_f32_16x16x32_bf16 v[40:43], v[188:191], v[164:167], v[40:43]
	v_mfma_f32_16x16x32_bf16 v[36:39], v[196:199], v[156:159], v[36:39]
	v_mfma_f32_16x16x32_bf16 v[32:35], v[196:199], v[164:167], v[32:35]
	v_mfma_f32_16x16x32_bf16 v[60:63], v[176:179], v[160:163], v[60:63]
	v_mfma_f32_16x16x32_bf16 v[56:59], v[176:179], v[168:171], v[56:59]
	v_mfma_f32_16x16x32_bf16 v[52:55], v[184:187], v[160:163], v[52:55]
	v_mfma_f32_16x16x32_bf16 v[48:51], v[184:187], v[168:171], v[48:51]
	v_mfma_f32_16x16x32_bf16 v[44:47], v[192:195], v[160:163], v[44:47]
	v_mfma_f32_16x16x32_bf16 v[40:43], v[192:195], v[168:171], v[40:43]
	v_mfma_f32_16x16x32_bf16 v[36:39], v[200:203], v[160:163], v[36:39]
	v_mfma_f32_16x16x32_bf16 v[32:35], v[200:203], v[168:171], v[32:35]
	s_barrier
	s_setprio 0
	v_readfirstlane_b32 s11, v150
	v_lshl_add_u64 v[156:157], v[204:205], 0, s[36:37]
	s_mov_b32 m0, s11
	v_readfirstlane_b32 s11, v152
	global_load_lds_dwordx4 v[156:157], off
	v_lshl_add_u64 v[156:157], v[204:205], 0, s[38:39]
	s_mov_b32 m0, s11
	s_nop 0
	global_load_lds_dwordx4 v[156:157], off
	s_waitcnt vmcnt(6)
	s_setprio 1
	s_barrier
	v_mfma_f32_16x16x32_bf16 v[28:31], v[172:175], v[208:211], v[28:31]
	v_mfma_f32_16x16x32_bf16 v[24:27], v[172:175], v[216:219], v[24:27]
	v_mfma_f32_16x16x32_bf16 v[20:23], v[180:183], v[208:211], v[20:23]
	v_mfma_f32_16x16x32_bf16 v[16:19], v[180:183], v[216:219], v[16:19]
	v_mfma_f32_16x16x32_bf16 v[12:15], v[188:191], v[208:211], v[12:15]
	v_mfma_f32_16x16x32_bf16 v[8:11], v[188:191], v[216:219], v[8:11]
	v_mfma_f32_16x16x32_bf16 v[4:7], v[196:199], v[208:211], v[4:7]
	v_mfma_f32_16x16x32_bf16 v[0:3], v[196:199], v[216:219], v[0:3]
	v_mfma_f32_16x16x32_bf16 v[28:31], v[176:179], v[212:215], v[28:31]
	v_mfma_f32_16x16x32_bf16 v[24:27], v[176:179], v[220:223], v[24:27]
	v_mfma_f32_16x16x32_bf16 v[20:23], v[184:187], v[212:215], v[20:23]
	v_mfma_f32_16x16x32_bf16 v[16:19], v[184:187], v[220:223], v[16:19]
	v_mfma_f32_16x16x32_bf16 v[12:15], v[192:195], v[212:215], v[12:15]
	v_mfma_f32_16x16x32_bf16 v[8:11], v[192:195], v[220:223], v[8:11]
	v_mfma_f32_16x16x32_bf16 v[4:7], v[200:203], v[212:215], v[4:7]
	v_mfma_f32_16x16x32_bf16 v[0:3], v[200:203], v[220:223], v[0:3]
	s_barrier
	s_setprio 0
	s_add_i32 s10, s10, 2
	s_cmp_lt_u32 s10, 28
	v_lshl_add_u64 v[130:131], v[130:131], 0, s[40:41]
	s_cbranch_scc1 .LBB0_116
	s_mov_b64 s[4:5], 0xa282f80
	v_add_u32_e32 v137, 0xc000, v136
	v_lshl_add_u64 v[130:131], v[128:129], 0, s[4:5]
	v_readfirstlane_b32 s4, v137
	s_mov_b32 m0, s4
	ds_read_b128 v[140:143], v153
	ds_read_b128 v[146:149], v153 offset:1024
	ds_read_b128 v[154:157], v153 offset:2048
	ds_read_b128 v[158:161], v153 offset:3072
	ds_read_b128 v[162:165], v135
	ds_read_b128 v[166:169], v135 offset:1024
	ds_read_b128 v[170:173], v134
	ds_read_b128 v[174:177], v134 offset:1024
	ds_read_b128 v[178:181], v133
	ds_read_b128 v[182:185], v133 offset:1024
	ds_read_b128 v[186:189], v132
	ds_read_b128 v[190:193], v132 offset:1024
	global_load_lds_dwordx4 v[130:131], off
	s_mov_b64 s[4:5], 0xa2c2f80
	v_add_u32_e32 v130, 0xe000, v136
	v_lshl_add_u64 v[128:129], v[128:129], 0, s[4:5]
	v_readfirstlane_b32 s4, v130
	s_mov_b32 m0, s4
	s_nop 0
	global_load_lds_dwordx4 v[128:129], off
	s_setprio 1
	s_barrier
	s_waitcnt lgkmcnt(0)
	v_mfma_f32_16x16x32_bf16 v[124:127], v[162:165], v[140:143], v[124:127]
	v_mfma_f32_16x16x32_bf16 v[120:123], v[162:165], v[154:157], v[120:123]
	v_mfma_f32_16x16x32_bf16 v[108:111], v[178:181], v[140:143], v[108:111]
	v_mfma_f32_16x16x32_bf16 v[100:103], v[186:189], v[140:143], v[100:103]
	v_mfma_f32_16x16x32_bf16 v[124:127], v[166:169], v[146:149], v[124:127]
	v_mfma_f32_16x16x32_bf16 v[120:123], v[166:169], v[158:161], v[120:123]
	v_mfma_f32_16x16x32_bf16 v[116:119], v[170:173], v[140:143], v[116:119]
	v_mfma_f32_16x16x32_bf16 v[112:115], v[170:173], v[154:157], v[112:115]
	v_mfma_f32_16x16x32_bf16 v[108:111], v[182:185], v[146:149], v[108:111]
	v_mfma_f32_16x16x32_bf16 v[104:107], v[178:181], v[154:157], v[104:107]
	v_mfma_f32_16x16x32_bf16 v[100:103], v[190:193], v[146:149], v[100:103]
	v_mfma_f32_16x16x32_bf16 v[96:99], v[186:189], v[154:157], v[96:99]
	v_mfma_f32_16x16x32_bf16 v[128:131], v[174:177], v[146:149], v[116:119]
	v_mfma_f32_16x16x32_bf16 v[194:197], v[174:177], v[158:161], v[112:115]
	v_mfma_f32_16x16x32_bf16 v[198:201], v[182:185], v[158:161], v[104:107]
	v_mfma_f32_16x16x32_bf16 v[202:205], v[190:193], v[158:161], v[96:99]
	s_barrier
	s_setprio 0
	s_nop 1
	ds_read_b128 v[96:99], v151
	ds_read_b128 v[104:107], v151 offset:1024
	ds_read_b128 v[112:115], v151 offset:2048
	ds_read_b128 v[116:119], v151 offset:3072
	s_setprio 1
	s_barrier
	s_waitcnt lgkmcnt(0)
	v_mfma_f32_16x16x32_bf16 v[92:95], v[162:165], v[96:99], v[92:95]
	v_mfma_f32_16x16x32_bf16 v[88:91], v[162:165], v[112:115], v[88:91]
	v_mfma_f32_16x16x32_bf16 v[76:79], v[178:181], v[96:99], v[76:79]
	v_mfma_f32_16x16x32_bf16 v[68:71], v[186:189], v[96:99], v[68:71]
	v_mfma_f32_16x16x32_bf16 v[92:95], v[166:169], v[104:107], v[92:95]
	v_mfma_f32_16x16x32_bf16 v[88:91], v[166:169], v[116:119], v[88:91]
	v_mfma_f32_16x16x32_bf16 v[84:87], v[170:173], v[96:99], v[84:87]
	v_mfma_f32_16x16x32_bf16 v[80:83], v[170:173], v[112:115], v[80:83]
	v_mfma_f32_16x16x32_bf16 v[76:79], v[182:185], v[104:107], v[76:79]
	v_mfma_f32_16x16x32_bf16 v[72:75], v[178:181], v[112:115], v[72:75]
	v_mfma_f32_16x16x32_bf16 v[68:71], v[190:193], v[104:107], v[68:71]
	v_mfma_f32_16x16x32_bf16 v[64:67], v[186:189], v[112:115], v[64:67]
	v_mfma_f32_16x16x32_bf16 v[150:153], v[174:177], v[104:107], v[84:87]
	v_mfma_f32_16x16x32_bf16 v[162:165], v[174:177], v[116:119], v[80:83]
	v_mfma_f32_16x16x32_bf16 v[166:169], v[182:185], v[116:119], v[72:75]
	v_mfma_f32_16x16x32_bf16 v[170:173], v[190:193], v[116:119], v[64:67]
	s_barrier
; #define WAIT_V(n) asm volatile("s_waitcnt vmcnt(" #n ")" ::: "memory")
; #define WAIT_L(n) asm volatile("s_waitcnt lgkmcnt(" #n ")" ::: "memory")
; #define BAR __builtin_amdgcn_s_barrier()
; template <int EPI>
; __device__ __forceinline__ void gemm_tile(const Params& p, const bf16* __restrict__ A, const bf16* __restrict__ Bt, const int K,
;                                           const int nt, const int brow, const int bcol, int pm, int pn) {
;     ...
;     LDB(B1, 0, 1); BAR; WAIT_L(0); MMA(0, 1, At, B1); BAR;
;     LDA(At, 0, 1); WAIT_V(4); BAR; WAIT_L(0); MMA(1, 0, At, B0); MMA(1, 1, At, B1); BAR; }
;   { LDB(B0, 1, 0); LDA(At, 1, 0); WAIT_V(2); BAR; WAIT_L(0); MMA(0, 0, At, B0); BAR;
;     LDB(B1, 1, 1); WAIT_V(0); BAR; WAIT_L(0); MMA(0, 1, At, B1); BAR;
	s_setprio 0
	s_nop 1
	ds_read_b128 v[64:67], v135 offset:16384
	ds_read_b128 v[72:75], v135 offset:17408
	ds_read_b128 v[80:83], v134 offset:16384
	ds_read_b128 v[84:87], v134 offset:17408
	ds_read_b128 v[174:177], v133 offset:16384
	ds_read_b128 v[178:181], v133 offset:17408
	ds_read_b128 v[182:185], v132 offset:16384
	ds_read_b128 v[186:189], v132 offset:17408
	s_waitcnt vmcnt(4)
	s_setprio 1
	s_barrier
	s_waitcnt lgkmcnt(0)
	v_mfma_f32_16x16x32_bf16 v[60:63], v[64:67], v[140:143], v[60:63]
	v_mfma_f32_16x16x32_bf16 v[56:59], v[64:67], v[154:157], v[56:59]
	v_mfma_f32_16x16x32_bf16 v[44:47], v[174:177], v[140:143], v[44:47]
	v_mfma_f32_16x16x32_bf16 v[36:39], v[182:185], v[140:143], v[36:39]
	v_mfma_f32_16x16x32_bf16 v[60:63], v[72:75], v[146:149], v[60:63]
	v_mfma_f32_16x16x32_bf16 v[56:59], v[72:75], v[158:161], v[56:59]
	v_mfma_f32_16x16x32_bf16 v[52:55], v[80:83], v[140:143], v[52:55]
	v_mfma_f32_16x16x32_bf16 v[48:51], v[80:83], v[154:157], v[48:51]
	v_mfma_f32_16x16x32_bf16 v[44:47], v[178:181], v[146:149], v[44:47]
	v_mfma_f32_16x16x32_bf16 v[40:43], v[174:177], v[154:157], v[40:43]
	v_mfma_f32_16x16x32_bf16 v[36:39], v[186:189], v[146:149], v[36:39]
	v_mfma_f32_16x16x32_bf16 v[32:35], v[182:185], v[154:157], v[32:35]
	v_mfma_f32_16x16x32_bf16 v[190:193], v[84:87], v[146:149], v[52:55]
	v_mfma_f32_16x16x32_bf16 v[208:211], v[84:87], v[158:161], v[48:51]
	v_mfma_f32_16x16x32_bf16 v[212:215], v[178:181], v[158:161], v[40:43]
	v_mfma_f32_16x16x32_bf16 v[140:143], v[186:189], v[158:161], v[32:35]
	s_setprio 0
	s_setprio 1
	v_mfma_f32_16x16x32_bf16 v[28:31], v[64:67], v[96:99], v[28:31]
	v_mfma_f32_16x16x32_bf16 v[24:27], v[64:67], v[112:115], v[24:27]
	v_mfma_f32_16x16x32_bf16 v[12:15], v[174:177], v[96:99], v[12:15]
	v_mfma_f32_16x16x32_bf16 v[4:7], v[182:185], v[96:99], v[4:7]
	v_mfma_f32_16x16x32_bf16 v[28:31], v[72:75], v[104:107], v[28:31]
	v_mfma_f32_16x16x32_bf16 v[24:27], v[72:75], v[116:119], v[24:27]
	v_mfma_f32_16x16x32_bf16 v[20:23], v[80:83], v[96:99], v[20:23]
	v_mfma_f32_16x16x32_bf16 v[16:19], v[80:83], v[112:115], v[16:19]
	v_mfma_f32_16x16x32_bf16 v[12:15], v[178:181], v[104:107], v[12:15]
	v_mfma_f32_16x16x32_bf16 v[8:11], v[174:177], v[112:115], v[8:11]
	v_mfma_f32_16x16x32_bf16 v[4:7], v[186:189], v[104:107], v[4:7]
	v_mfma_f32_16x16x32_bf16 v[0:3], v[182:185], v[112:115], v[0:3]
	v_mfma_f32_16x16x32_bf16 v[146:149], v[84:87], v[104:107], v[20:23]
	v_mfma_f32_16x16x32_bf16 v[154:157], v[84:87], v[116:119], v[16:19]
	v_mfma_f32_16x16x32_bf16 v[158:161], v[178:181], v[116:119], v[8:11]
	v_mfma_f32_16x16x32_bf16 v[174:177], v[186:189], v[116:119], v[0:3]
	s_barrier
	s_setprio 0
	s_nop 1
	ds_read_b128 v[0:3], v144
	ds_read_b128 v[8:11], v144 offset:1024
	ds_read_b128 v[16:19], v144 offset:2048
	ds_read_b128 v[20:23], v144 offset:3072
	ds_read_b128 v[32:35], v135 offset:32768
	ds_read_b128 v[40:43], v135 offset:33792
	ds_read_b128 v[48:51], v134 offset:32768
	ds_read_b128 v[52:55], v134 offset:33792
	ds_read_b128 v[64:67], v133 offset:32768
	ds_read_b128 v[178:181], v133 offset:33792
	ds_read_b128 v[182:185], v132 offset:32768
	ds_read_b128 v[186:189], v132 offset:33792
	s_waitcnt vmcnt(2)
	s_setprio 1
	s_barrier
	s_waitcnt lgkmcnt(0)
	v_mfma_f32_16x16x32_bf16 v[72:75], v[32:35], v[0:3], v[124:127]
	v_mfma_f32_16x16x32_bf16 v[116:119], v[40:43], v[8:11], v[72:75]
	v_mfma_f32_16x16x32_bf16 v[72:75], v[32:35], v[16:19], v[120:123]
	v_mfma_f32_16x16x32_bf16 v[124:127], v[40:43], v[20:23], v[72:75]
	v_mfma_f32_16x16x32_bf16 v[72:75], v[48:51], v[0:3], v[128:131]
	v_mfma_f32_16x16x32_bf16 v[112:115], v[52:55], v[8:11], v[72:75]
	v_mfma_f32_16x16x32_bf16 v[72:75], v[48:51], v[16:19], v[194:197]
	v_mfma_f32_16x16x32_bf16 v[120:123], v[52:55], v[20:23], v[72:75]
	v_mfma_f32_16x16x32_bf16 v[72:75], v[64:67], v[0:3], v[108:111]
	v_mfma_f32_16x16x32_bf16 v[104:107], v[178:181], v[8:11], v[72:75]
	v_mfma_f32_16x16x32_bf16 v[72:75], v[64:67], v[16:19], v[198:201]
	v_mfma_f32_16x16x32_bf16 v[108:111], v[178:181], v[20:23], v[72:75]
	v_mfma_f32_16x16x32_bf16 v[72:75], v[182:185], v[0:3], v[100:103]
	v_mfma_f32_16x16x32_bf16 v[96:99], v[186:189], v[8:11], v[72:75]
	v_mfma_f32_16x16x32_bf16 v[72:75], v[182:185], v[16:19], v[202:205]
	v_mfma_f32_16x16x32_bf16 v[100:103], v[186:189], v[20:23], v[72:75]
	s_barrier
; #define WAIT_V(n) asm volatile("s_waitcnt vmcnt(" #n ")" ::: "memory")
; #define WAIT_L(n) asm volatile("s_waitcnt lgkmcnt(" #n ")" ::: "memory")
; #define BAR __builtin_amdgcn_s_barrier()
; template <int EPI>
; __device__ __forceinline__ void gemm_tile(const Params& p, const bf16* __restrict__ A, const bf16* __restrict__ Bt, const int K,
;                                           const int nt, const int brow, const int bcol, int pm, int pn) {
;     ...
;     LDA(At, 0, 1); WAIT_V(4); BAR; WAIT_L(0); MMA(1, 0, At, B0); MMA(1, 1, At, B1); BAR; }
;   { LDB(B0, 1, 0); LDA(At, 1, 0); WAIT_V(2); BAR; WAIT_L(0); MMA(0, 0, At, B0); BAR;
;     LDB(B1, 1, 1); WAIT_V(0); BAR; WAIT_L(0); MMA(0, 1, At, B1); BAR;
;     LDA(At, 1, 1); BAR; WAIT_L(0); MMA(1, 0, At, B0); MMA(1, 1, At, B1); BAR; }
;   if (wr == 0) BAR;
	s_setprio 0
	ds_read_b128 v[128:131], v139
	ds_read_b128 v[194:197], v139 offset:1024
	ds_read_b128 v[198:201], v139 offset:2048
	ds_read_b128 v[136:139], v139 offset:3072
	s_waitcnt vmcnt(0)
	s_setprio 1
	s_barrier
	s_waitcnt lgkmcnt(0)
	v_mfma_f32_16x16x32_bf16 v[72:75], v[32:35], v[128:131], v[92:95]
	v_mfma_f32_16x16x32_bf16 v[32:35], v[32:35], v[198:201], v[88:91]
	v_mfma_f32_16x16x32_bf16 v[92:95], v[40:43], v[136:139], v[32:35]
	v_mfma_f32_16x16x32_bf16 v[32:35], v[48:51], v[128:131], v[150:153]
	v_mfma_f32_16x16x32_bf16 v[80:83], v[52:55], v[194:197], v[32:35]
	v_mfma_f32_16x16x32_bf16 v[32:35], v[48:51], v[198:201], v[162:165]
	v_mfma_f32_16x16x32_bf16 v[88:91], v[52:55], v[136:139], v[32:35]
	v_mfma_f32_16x16x32_bf16 v[32:35], v[64:67], v[128:131], v[76:79]
	v_mfma_f32_16x16x32_bf16 v[84:87], v[40:43], v[194:197], v[72:75]
	v_mfma_f32_16x16x32_bf16 v[72:75], v[178:181], v[194:197], v[32:35]
	v_mfma_f32_16x16x32_bf16 v[32:35], v[64:67], v[198:201], v[166:169]
	v_mfma_f32_16x16x32_bf16 v[76:79], v[178:181], v[136:139], v[32:35]
	v_mfma_f32_16x16x32_bf16 v[32:35], v[182:185], v[128:131], v[68:71]
	v_mfma_f32_16x16x32_bf16 v[64:67], v[186:189], v[194:197], v[32:35]
	v_mfma_f32_16x16x32_bf16 v[32:35], v[182:185], v[198:201], v[170:173]
	v_mfma_f32_16x16x32_bf16 v[68:71], v[186:189], v[136:139], v[32:35]
	s_barrier
	s_setprio 0
	ds_read_b128 v[150:153], v135 offset:49152
	ds_read_b128 v[162:165], v135 offset:50176
	ds_read_b128 v[166:169], v134 offset:49152
	ds_read_b128 v[170:173], v134 offset:50176
	ds_read_b128 v[178:181], v133 offset:49152
	ds_read_b128 v[182:185], v133 offset:50176
	ds_read_b128 v[186:189], v132 offset:49152
	ds_read_b128 v[132:135], v132 offset:50176
	s_setprio 1
	s_barrier
	s_waitcnt lgkmcnt(0)
	v_mfma_f32_16x16x32_bf16 v[32:35], v[150:153], v[0:3], v[60:63]
	v_mfma_f32_16x16x32_bf16 v[52:55], v[162:165], v[8:11], v[32:35]
	v_mfma_f32_16x16x32_bf16 v[32:35], v[150:153], v[16:19], v[56:59]
	v_mfma_f32_16x16x32_bf16 v[60:63], v[162:165], v[20:23], v[32:35]
	v_mfma_f32_16x16x32_bf16 v[32:35], v[166:169], v[0:3], v[190:193]
	v_mfma_f32_16x16x32_bf16 v[48:51], v[170:173], v[8:11], v[32:35]
	v_mfma_f32_16x16x32_bf16 v[32:35], v[166:169], v[16:19], v[208:211]
	v_mfma_f32_16x16x32_bf16 v[56:59], v[170:173], v[20:23], v[32:35]
	v_mfma_f32_16x16x32_bf16 v[32:35], v[178:181], v[0:3], v[44:47]
	v_mfma_f32_16x16x32_bf16 v[40:43], v[182:185], v[8:11], v[32:35]
	v_mfma_f32_16x16x32_bf16 v[32:35], v[178:181], v[16:19], v[212:215]
	v_mfma_f32_16x16x32_bf16 v[0:3], v[186:189], v[0:3], v[36:39]
	v_mfma_f32_16x16x32_bf16 v[44:47], v[182:185], v[20:23], v[32:35]
	v_mfma_f32_16x16x32_bf16 v[32:35], v[132:135], v[8:11], v[0:3]
	v_mfma_f32_16x16x32_bf16 v[0:3], v[186:189], v[16:19], v[140:143]
	v_mfma_f32_16x16x32_bf16 v[36:39], v[132:135], v[20:23], v[0:3]
	s_setprio 0
	s_setprio 1
	v_mfma_f32_16x16x32_bf16 v[0:3], v[150:153], v[128:131], v[28:31]
	v_mfma_f32_16x16x32_bf16 v[20:23], v[162:165], v[194:197], v[0:3]
	v_mfma_f32_16x16x32_bf16 v[0:3], v[150:153], v[198:201], v[24:27]
	v_mfma_f32_16x16x32_bf16 v[28:31], v[162:165], v[136:139], v[0:3]
	v_mfma_f32_16x16x32_bf16 v[0:3], v[166:169], v[128:131], v[146:149]
	v_mfma_f32_16x16x32_bf16 v[16:19], v[170:173], v[194:197], v[0:3]
	v_mfma_f32_16x16x32_bf16 v[0:3], v[166:169], v[198:201], v[154:157]
	v_mfma_f32_16x16x32_bf16 v[24:27], v[170:173], v[136:139], v[0:3]
	v_mfma_f32_16x16x32_bf16 v[0:3], v[178:181], v[128:131], v[12:15]
	v_mfma_f32_16x16x32_bf16 v[8:11], v[182:185], v[194:197], v[0:3]
	v_mfma_f32_16x16x32_bf16 v[0:3], v[178:181], v[198:201], v[158:161]
	v_mfma_f32_16x16x32_bf16 v[12:15], v[182:185], v[136:139], v[0:3]
	v_mfma_f32_16x16x32_bf16 v[0:3], v[186:189], v[128:131], v[4:7]
	v_mfma_f32_16x16x32_bf16 v[4:7], v[186:189], v[198:201], v[174:177]
	v_mfma_f32_16x16x32_bf16 v[0:3], v[132:135], v[194:197], v[0:3]
	v_mfma_f32_16x16x32_bf16 v[4:7], v[132:135], v[136:139], v[4:7]
	s_barrier
	s_setprio 0
	s_cmpk_gt_u32 s2, 0xff
	s_cbranch_scc1 .LBB0_119
	s_barrier

; #define WAIT_V(n) asm volatile("s_waitcnt vmcnt(" #n ")" ::: "memory")
; #define WAIT_L(n) asm volatile("s_waitcnt lgkmcnt(" #n ")" ::: "memory")
; #define BAR __builtin_amdgcn_s_barrier()
; #define SCHED __builtin_amdgcn_sched_barrier(0)
; template <int EPI>
; __device__ __forceinline__ void gemm_tile(const Params& p, const bf16* __restrict__ A, const bf16* __restrict__ Bt, const int K,
;                                           const int nt, const int brow, const int bcol, int pm, int pn) {
;     ...
;   for (int t = 0; t < nt - 2; t += 2) {
;     LDB(B0, 0, 0); SCHED; LDA(At, 0, 0); STAGE(SA(1, 1), A, brow + HALF, t + 1);
;     WAIT_L(8); BAR; WAIT_L(0); MMA(0, 0, At, B0); BAR; SCHED;
;     LDB(B1, 0, 1); STAGE(SB(0, 0), Bt, bcol, t + 2);
;     BAR; WAIT_L(0); MMA(0, 1, At, B1); BAR;
;     LDA(At, 0, 1); STAGE(SA(0, 0), A, brow, t + 2);
;     BAR; WAIT_L(0); MMA(1, 0, At, B0); BAR; SCHED;
;     STAGE(SB(0, 1), Bt, bcol + HALF, t + 2);
;     WAIT_V(6); BAR; MMA(1, 1, At, B1); BAR;
;     LDB(B0, 1, 0); SCHED; LDA(At, 1, 0); STAGE(SA(0, 1), A, brow + HALF, t + 2);
;     WAIT_L(8); BAR; WAIT_L(0); MMA(0, 0, At, B0); BAR; SCHED;
;     LDB(B1, 1, 1); STAGE(SB(1, 0), Bt, bcol, t + 3);
;     BAR; WAIT_L(0); MMA(0, 1, At, B1); BAR;
;     LDA(At, 1, 1); STAGE(SA(1, 0), A, brow, t + 3);
;     BAR; WAIT_L(0); MMA(1, 0, At, B0); BAR; SCHED;
;     STAGE(SB(1, 1), Bt, bcol + HALF, t + 3);
;     WAIT_V(6); BAR; MMA(1, 1, At, B1); BAR;
;   }
.LBB0_415:
	ds_read_b128 v[162:165], v160
	ds_read_b128 v[166:169], v160 offset:1024
	ds_read_b128 v[170:173], v160 offset:2048
	ds_read_b128 v[174:177], v160 offset:3072
	v_lshl_add_u64 v[228:229], s[38:39], 0, v[128:129]
	s_mov_b64 s[40:41], 0x6282080
	v_readfirstlane_b32 s31, v159
	v_lshl_add_u64 v[212:213], v[228:229], 0, s[40:41]
	s_mov_b32 m0, s31
	s_mov_b64 s[40:41], 0x62c2080
	v_readfirstlane_b32 s31, v158
	ds_read_b128 v[178:181], v136
	ds_read_b128 v[182:185], v136 offset:1024
	ds_read_b128 v[186:189], v135
	ds_read_b128 v[190:193], v135 offset:1024
	ds_read_b128 v[194:197], v131
	ds_read_b128 v[198:201], v131 offset:1024
	ds_read_b128 v[202:205], v130
	ds_read_b128 v[208:211], v130 offset:1024
	global_load_lds_dwordx4 v[212:213], off
	v_lshl_add_u64 v[212:213], v[228:229], 0, s[40:41]
	s_mov_b32 m0, s31
	s_nop 0
	global_load_lds_dwordx4 v[212:213], off
	s_waitcnt lgkmcnt(8)
	s_setprio 1
	s_barrier
	s_waitcnt lgkmcnt(0)
	v_mfma_f32_16x16x32_bf16 v[124:127], v[178:181], v[162:165], v[124:127]
	v_mfma_f32_16x16x32_bf16 v[120:123], v[178:181], v[170:173], v[120:123]
	v_mfma_f32_16x16x32_bf16 v[116:119], v[186:189], v[162:165], v[116:119]
	v_mfma_f32_16x16x32_bf16 v[112:115], v[186:189], v[170:173], v[112:115]
	v_mfma_f32_16x16x32_bf16 v[108:111], v[194:197], v[162:165], v[108:111]
	v_mfma_f32_16x16x32_bf16 v[104:107], v[194:197], v[170:173], v[104:107]
	v_mfma_f32_16x16x32_bf16 v[100:103], v[202:205], v[162:165], v[100:103]
	v_mfma_f32_16x16x32_bf16 v[96:99], v[202:205], v[170:173], v[96:99]
	v_mfma_f32_16x16x32_bf16 v[124:127], v[182:185], v[166:169], v[124:127]
	v_mfma_f32_16x16x32_bf16 v[120:123], v[182:185], v[174:177], v[120:123]
	v_mfma_f32_16x16x32_bf16 v[116:119], v[190:193], v[166:169], v[116:119]
	v_mfma_f32_16x16x32_bf16 v[112:115], v[190:193], v[174:177], v[112:115]
	v_mfma_f32_16x16x32_bf16 v[108:111], v[198:201], v[166:169], v[108:111]
	v_mfma_f32_16x16x32_bf16 v[104:107], v[198:201], v[174:177], v[104:107]
	v_mfma_f32_16x16x32_bf16 v[100:103], v[208:211], v[166:169], v[100:103]
	v_mfma_f32_16x16x32_bf16 v[96:99], v[208:211], v[174:177], v[96:99]
	s_barrier
	s_setprio 0
	v_lshl_add_u64 v[230:231], s[36:37], 0, v[128:129]
	s_mov_b64 s[40:41], 0x100
	v_readfirstlane_b32 s31, v134
	v_lshl_add_u64 v[232:233], v[230:231], 0, s[40:41]
	s_mov_b32 m0, s31
	s_mov_b64 s[40:41], 0x40100
	v_readfirstlane_b32 s31, v137
	ds_read_b128 v[212:215], v156
	ds_read_b128 v[216:219], v156 offset:1024
	ds_read_b128 v[220:223], v156 offset:2048
	ds_read_b128 v[224:227], v156 offset:3072
	global_load_lds_dwordx4 v[232:233], off
	v_lshl_add_u64 v[232:233], v[230:231], 0, s[40:41]
	s_mov_b32 m0, s31
	s_nop 0
	global_load_lds_dwordx4 v[232:233], off
	s_setprio 1
	s_barrier
	s_waitcnt lgkmcnt(0)
	v_mfma_f32_16x16x32_bf16 v[92:95], v[178:181], v[212:215], v[92:95]
	v_mfma_f32_16x16x32_bf16 v[88:91], v[178:181], v[220:223], v[88:91]
	v_mfma_f32_16x16x32_bf16 v[84:87], v[186:189], v[212:215], v[84:87]
	v_mfma_f32_16x16x32_bf16 v[80:83], v[186:189], v[220:223], v[80:83]
	v_mfma_f32_16x16x32_bf16 v[76:79], v[194:197], v[212:215], v[76:79]
	v_mfma_f32_16x16x32_bf16 v[72:75], v[194:197], v[220:223], v[72:75]
	v_mfma_f32_16x16x32_bf16 v[68:71], v[202:205], v[212:215], v[68:71]
	v_mfma_f32_16x16x32_bf16 v[64:67], v[202:205], v[220:223], v[64:67]
	v_mfma_f32_16x16x32_bf16 v[92:95], v[182:185], v[216:219], v[92:95]
	v_mfma_f32_16x16x32_bf16 v[88:91], v[182:185], v[224:227], v[88:91]
	v_mfma_f32_16x16x32_bf16 v[84:87], v[190:193], v[216:219], v[84:87]
	v_mfma_f32_16x16x32_bf16 v[80:83], v[190:193], v[224:227], v[80:83]
	v_mfma_f32_16x16x32_bf16 v[76:79], v[198:201], v[216:219], v[76:79]
	v_mfma_f32_16x16x32_bf16 v[72:75], v[198:201], v[224:227], v[72:75]
	v_mfma_f32_16x16x32_bf16 v[68:71], v[208:211], v[216:219], v[68:71]
	v_mfma_f32_16x16x32_bf16 v[64:67], v[208:211], v[224:227], v[64:67]
	s_barrier
	s_setprio 0
	s_mov_b64 s[40:41], 0x6202100
	v_readfirstlane_b32 s31, v138
	v_lshl_add_u64 v[232:233], v[228:229], 0, s[40:41]
	s_mov_b32 m0, s31
	s_mov_b64 s[40:41], 0x6242100
	v_readfirstlane_b32 s31, v140
	ds_read_b128 v[178:181], v136 offset:16384
	ds_read_b128 v[182:185], v136 offset:17408
	ds_read_b128 v[186:189], v135 offset:16384
	ds_read_b128 v[190:193], v135 offset:17408
	ds_read_b128 v[194:197], v131 offset:16384
	ds_read_b128 v[198:201], v131 offset:17408
	ds_read_b128 v[202:205], v130 offset:16384
	ds_read_b128 v[208:211], v130 offset:17408
	global_load_lds_dwordx4 v[232:233], off
	v_lshl_add_u64 v[232:233], v[228:229], 0, s[40:41]
	s_mov_b32 m0, s31
	s_nop 0
	global_load_lds_dwordx4 v[232:233], off
	s_setprio 1
	s_barrier
	s_waitcnt lgkmcnt(0)
	v_mfma_f32_16x16x32_bf16 v[60:63], v[178:181], v[162:165], v[60:63]
	v_mfma_f32_16x16x32_bf16 v[56:59], v[178:181], v[170:173], v[56:59]
	v_mfma_f32_16x16x32_bf16 v[52:55], v[186:189], v[162:165], v[52:55]
	v_mfma_f32_16x16x32_bf16 v[48:51], v[186:189], v[170:173], v[48:51]
	v_mfma_f32_16x16x32_bf16 v[44:47], v[194:197], v[162:165], v[44:47]
	v_mfma_f32_16x16x32_bf16 v[40:43], v[194:197], v[170:173], v[40:43]
	v_mfma_f32_16x16x32_bf16 v[36:39], v[202:205], v[162:165], v[36:39]
	v_mfma_f32_16x16x32_bf16 v[32:35], v[202:205], v[170:173], v[32:35]
	v_mfma_f32_16x16x32_bf16 v[60:63], v[182:185], v[166:169], v[60:63]
	v_mfma_f32_16x16x32_bf16 v[56:59], v[182:185], v[174:177], v[56:59]
	v_mfma_f32_16x16x32_bf16 v[52:55], v[190:193], v[166:169], v[52:55]
	v_mfma_f32_16x16x32_bf16 v[48:51], v[190:193], v[174:177], v[48:51]
	v_mfma_f32_16x16x32_bf16 v[44:47], v[198:201], v[166:169], v[44:47]
	v_mfma_f32_16x16x32_bf16 v[40:43], v[198:201], v[174:177], v[40:43]
	v_mfma_f32_16x16x32_bf16 v[36:39], v[208:211], v[166:169], v[36:39]
	v_mfma_f32_16x16x32_bf16 v[32:35], v[208:211], v[174:177], v[32:35]
	s_barrier
; #define WAIT_V(n) asm volatile("s_waitcnt vmcnt(" #n ")" ::: "memory")
; #define WAIT_L(n) asm volatile("s_waitcnt lgkmcnt(" #n ")" ::: "memory")
; #define BAR __builtin_amdgcn_s_barrier()
; #define SCHED __builtin_amdgcn_sched_barrier(0)
; template <int EPI>
; __device__ __forceinline__ void gemm_tile(const Params& p, const bf16* __restrict__ A, const bf16* __restrict__ Bt, const int K,
;                                           const int nt, const int brow, const int bcol, int pm, int pn) {
;     ...
;   for (int t = 0; t < nt - 2; t += 2) {
;     LDB(B0, 0, 0); SCHED; LDA(At, 0, 0); STAGE(SA(1, 1), A, brow + HALF, t + 1);
;     WAIT_L(8); BAR; WAIT_L(0); MMA(0, 0, At, B0); BAR; SCHED;
;     LDB(B1, 0, 1); STAGE(SB(0, 0), Bt, bcol, t + 2);
;     BAR; WAIT_L(0); MMA(0, 1, At, B1); BAR;
;     LDA(At, 0, 1); STAGE(SA(0, 0), A, brow, t + 2);
;     BAR; WAIT_L(0); MMA(1, 0, At, B0); BAR; SCHED;
;     STAGE(SB(0, 1), Bt, bcol + HALF, t + 2);
;     WAIT_V(6); BAR; MMA(1, 1, At, B1); BAR;
;     LDB(B0, 1, 0); SCHED; LDA(At, 1, 0); STAGE(SA(0, 1), A, brow + HALF, t + 2);
;     WAIT_L(8); BAR; WAIT_L(0); MMA(0, 0, At, B0); BAR; SCHED;
;     LDB(B1, 1, 1); STAGE(SB(1, 0), Bt, bcol, t + 3);
;     BAR; WAIT_L(0); MMA(0, 1, At, B1); BAR;
;     LDA(At, 1, 1); STAGE(SA(1, 0), A, brow, t + 3);
;     BAR; WAIT_L(0); MMA(1, 0, At, B0); BAR; SCHED;
;     STAGE(SB(1, 1), Bt, bcol + HALF, t + 3);
;     WAIT_V(6); BAR; MMA(1, 1, At, B1); BAR;
;   }
	s_setprio 0
	s_add_i32 s9, s9, 2
	s_add_u32 s38, s38, 0x100
	s_addc_u32 s39, s39, 0
	s_add_u32 s36, s36, 0x100
	s_addc_u32 s37, s37, 0
	s_mov_b64 s[40:41], 0x80100
	v_readfirstlane_b32 s31, v141
	v_lshl_add_u64 v[162:163], v[230:231], 0, s[40:41]
	s_mov_b32 m0, s31
	s_mov_b64 s[40:41], 0xc0100
	v_readfirstlane_b32 s31, v147
	global_load_lds_dwordx4 v[162:163], off
	v_lshl_add_u64 v[162:163], v[230:231], 0, s[40:41]
	s_mov_b32 m0, s31
	s_nop 0
	global_load_lds_dwordx4 v[162:163], off
	s_waitcnt vmcnt(6)
	s_setprio 1
	s_barrier
	v_mfma_f32_16x16x32_bf16 v[28:31], v[178:181], v[212:215], v[28:31]
	v_mfma_f32_16x16x32_bf16 v[24:27], v[178:181], v[220:223], v[24:27]
	v_mfma_f32_16x16x32_bf16 v[20:23], v[186:189], v[212:215], v[20:23]
	v_mfma_f32_16x16x32_bf16 v[16:19], v[186:189], v[220:223], v[16:19]
	v_mfma_f32_16x16x32_bf16 v[12:15], v[194:197], v[212:215], v[12:15]
	v_mfma_f32_16x16x32_bf16 v[8:11], v[194:197], v[220:223], v[8:11]
	v_mfma_f32_16x16x32_bf16 v[4:7], v[202:205], v[212:215], v[4:7]
	v_mfma_f32_16x16x32_bf16 v[0:3], v[202:205], v[220:223], v[0:3]
	v_mfma_f32_16x16x32_bf16 v[28:31], v[182:185], v[216:219], v[28:31]
	v_mfma_f32_16x16x32_bf16 v[24:27], v[182:185], v[224:227], v[24:27]
	v_mfma_f32_16x16x32_bf16 v[20:23], v[190:193], v[216:219], v[20:23]
	v_mfma_f32_16x16x32_bf16 v[16:19], v[190:193], v[224:227], v[16:19]
	v_mfma_f32_16x16x32_bf16 v[12:15], v[198:201], v[216:219], v[12:15]
	v_mfma_f32_16x16x32_bf16 v[8:11], v[198:201], v[224:227], v[8:11]
	v_mfma_f32_16x16x32_bf16 v[4:7], v[208:211], v[216:219], v[4:7]
	v_mfma_f32_16x16x32_bf16 v[0:3], v[208:211], v[224:227], v[0:3]
	s_barrier
	s_setprio 0
	ds_read_b128 v[162:165], v149
	ds_read_b128 v[166:169], v149 offset:1024
	ds_read_b128 v[170:173], v149 offset:2048
	ds_read_b128 v[174:177], v149 offset:3072
	s_mov_b64 s[40:41], 0x6282100
	v_readfirstlane_b32 s31, v148
	v_lshl_add_u64 v[212:213], v[228:229], 0, s[40:41]
	s_mov_b32 m0, s31
	s_mov_b64 s[40:41], 0x62c2100
	v_readfirstlane_b32 s31, v150
	ds_read_b128 v[178:181], v136 offset:32768
	ds_read_b128 v[182:185], v136 offset:33792
	ds_read_b128 v[186:189], v135 offset:32768
	ds_read_b128 v[190:193], v135 offset:33792
	ds_read_b128 v[194:197], v131 offset:32768
	ds_read_b128 v[198:201], v131 offset:33792
	ds_read_b128 v[202:205], v130 offset:32768
	ds_read_b128 v[208:211], v130 offset:33792
	global_load_lds_dwordx4 v[212:213], off
	v_lshl_add_u64 v[212:213], v[228:229], 0, s[40:41]
	s_mov_b32 m0, s31
	s_nop 0
	global_load_lds_dwordx4 v[212:213], off
	s_waitcnt lgkmcnt(8)
	s_setprio 1
	s_barrier
	s_waitcnt lgkmcnt(0)
	v_mfma_f32_16x16x32_bf16 v[124:127], v[178:181], v[162:165], v[124:127]
	v_mfma_f32_16x16x32_bf16 v[120:123], v[178:181], v[170:173], v[120:123]
	v_mfma_f32_16x16x32_bf16 v[116:119], v[186:189], v[162:165], v[116:119]
	v_mfma_f32_16x16x32_bf16 v[112:115], v[186:189], v[170:173], v[112:115]
	v_mfma_f32_16x16x32_bf16 v[108:111], v[194:197], v[162:165], v[108:111]
	v_mfma_f32_16x16x32_bf16 v[104:107], v[194:197], v[170:173], v[104:107]
	v_mfma_f32_16x16x32_bf16 v[100:103], v[202:205], v[162:165], v[100:103]
	v_mfma_f32_16x16x32_bf16 v[96:99], v[202:205], v[170:173], v[96:99]
	v_mfma_f32_16x16x32_bf16 v[124:127], v[182:185], v[166:169], v[124:127]
	v_mfma_f32_16x16x32_bf16 v[120:123], v[182:185], v[174:177], v[120:123]
	v_mfma_f32_16x16x32_bf16 v[116:119], v[190:193], v[166:169], v[116:119]
	v_mfma_f32_16x16x32_bf16 v[112:115], v[190:193], v[174:177], v[112:115]
	v_mfma_f32_16x16x32_bf16 v[108:111], v[198:201], v[166:169], v[108:111]
	v_mfma_f32_16x16x32_bf16 v[104:107], v[198:201], v[174:177], v[104:107]
	v_mfma_f32_16x16x32_bf16 v[100:103], v[208:211], v[166:169], v[100:103]
	v_mfma_f32_16x16x32_bf16 v[96:99], v[208:211], v[174:177], v[96:99]
	s_barrier
	s_setprio 0
	s_mov_b64 s[40:41], 0x180
	v_readfirstlane_b32 s31, v151
	v_lshl_add_u64 v[232:233], v[230:231], 0, s[40:41]
	s_mov_b32 m0, s31
	s_mov_b64 s[40:41], 0x40180
	v_readfirstlane_b32 s31, v152
	ds_read_b128 v[212:215], v139
	ds_read_b128 v[216:219], v139 offset:1024
	ds_read_b128 v[220:223], v139 offset:2048
	ds_read_b128 v[224:227], v139 offset:3072
	global_load_lds_dwordx4 v[232:233], off
	v_lshl_add_u64 v[232:233], v[230:231], 0, s[40:41]
	s_mov_b32 m0, s31
	s_nop 0
	global_load_lds_dwordx4 v[232:233], off
	s_setprio 1
	s_barrier
	s_waitcnt lgkmcnt(0)
	v_mfma_f32_16x16x32_bf16 v[92:95], v[178:181], v[212:215], v[92:95]
	v_mfma_f32_16x16x32_bf16 v[88:91], v[178:181], v[220:223], v[88:91]
	v_mfma_f32_16x16x32_bf16 v[84:87], v[186:189], v[212:215], v[84:87]
	v_mfma_f32_16x16x32_bf16 v[80:83], v[186:189], v[220:223], v[80:83]
	v_mfma_f32_16x16x32_bf16 v[76:79], v[194:197], v[212:215], v[76:79]
	v_mfma_f32_16x16x32_bf16 v[72:75], v[194:197], v[220:223], v[72:75]
	v_mfma_f32_16x16x32_bf16 v[68:71], v[202:205], v[212:215], v[68:71]
	v_mfma_f32_16x16x32_bf16 v[64:67], v[202:205], v[220:223], v[64:67]
	v_mfma_f32_16x16x32_bf16 v[92:95], v[182:185], v[216:219], v[92:95]
	v_mfma_f32_16x16x32_bf16 v[88:91], v[182:185], v[224:227], v[88:91]
	v_mfma_f32_16x16x32_bf16 v[84:87], v[190:193], v[216:219], v[84:87]
	v_mfma_f32_16x16x32_bf16 v[80:83], v[190:193], v[224:227], v[80:83]
	v_mfma_f32_16x16x32_bf16 v[76:79], v[198:201], v[216:219], v[76:79]
	v_mfma_f32_16x16x32_bf16 v[72:75], v[198:201], v[224:227], v[72:75]
	v_mfma_f32_16x16x32_bf16 v[68:71], v[208:211], v[216:219], v[68:71]
	v_mfma_f32_16x16x32_bf16 v[64:67], v[208:211], v[224:227], v[64:67]
	s_barrier
; #define WAIT_V(n) asm volatile("s_waitcnt vmcnt(" #n ")" ::: "memory")
; #define WAIT_L(n) asm volatile("s_waitcnt lgkmcnt(" #n ")" ::: "memory")
; #define BAR __builtin_amdgcn_s_barrier()
; #define SCHED __builtin_amdgcn_sched_barrier(0)
; template <int EPI>
; __device__ __forceinline__ void gemm_tile(const Params& p, const bf16* __restrict__ A, const bf16* __restrict__ Bt, const int K,
;                                           const int nt, const int brow, const int bcol, int pm, int pn) {
;     ...
;     WAIT_V(6); BAR; MMA(1, 1, At, B1); BAR;
;     LDB(B0, 1, 0); SCHED; LDA(At, 1, 0); STAGE(SA(0, 1), A, brow + HALF, t + 2);
;     WAIT_L(8); BAR; WAIT_L(0); MMA(0, 0, At, B0); BAR; SCHED;
;     LDB(B1, 1, 1); STAGE(SB(1, 0), Bt, bcol, t + 3);
;     BAR; WAIT_L(0); MMA(0, 1, At, B1); BAR;
;     LDA(At, 1, 1); STAGE(SA(1, 0), A, brow, t + 3);
;     BAR; WAIT_L(0); MMA(1, 0, At, B0); BAR; SCHED;
;     STAGE(SB(1, 1), Bt, bcol + HALF, t + 3);
;     WAIT_V(6); BAR; MMA(1, 1, At, B1); BAR;
;   }
;   { LDB(B0, 0, 0); LDA(At, 0, 0); STAGE(SA(1, 1), A, brow + HALF, nt - 1);
;     BAR; WAIT_L(0); MMA(0, 0, At, B0); BAR;
	s_setprio 0
	s_mov_b64 s[40:41], 0x6202180
	v_readfirstlane_b32 s31, v153
	v_lshl_add_u64 v[232:233], v[228:229], 0, s[40:41]
	s_mov_b32 m0, s31
	s_mov_b64 s[40:41], 0x6242180
	v_readfirstlane_b32 s31, v154
	ds_read_b128 v[178:181], v136 offset:49152
	ds_read_b128 v[182:185], v136 offset:50176
	ds_read_b128 v[186:189], v135 offset:49152
	ds_read_b128 v[190:193], v135 offset:50176
	ds_read_b128 v[194:197], v131 offset:49152
	ds_read_b128 v[198:201], v131 offset:50176
	ds_read_b128 v[202:205], v130 offset:49152
	ds_read_b128 v[208:211], v130 offset:50176
	global_load_lds_dwordx4 v[232:233], off
	v_lshl_add_u64 v[228:229], v[228:229], 0, s[40:41]
	s_mov_b32 m0, s31
	s_nop 0
	global_load_lds_dwordx4 v[228:229], off
	s_setprio 1
	s_barrier
	s_waitcnt lgkmcnt(0)
	v_mfma_f32_16x16x32_bf16 v[60:63], v[178:181], v[162:165], v[60:63]
	v_mfma_f32_16x16x32_bf16 v[56:59], v[178:181], v[170:173], v[56:59]
	v_mfma_f32_16x16x32_bf16 v[52:55], v[186:189], v[162:165], v[52:55]
	v_mfma_f32_16x16x32_bf16 v[48:51], v[186:189], v[170:173], v[48:51]
	v_mfma_f32_16x16x32_bf16 v[44:47], v[194:197], v[162:165], v[44:47]
	v_mfma_f32_16x16x32_bf16 v[40:43], v[194:197], v[170:173], v[40:43]
	v_mfma_f32_16x16x32_bf16 v[36:39], v[202:205], v[162:165], v[36:39]
	v_mfma_f32_16x16x32_bf16 v[32:35], v[202:205], v[170:173], v[32:35]
	v_mfma_f32_16x16x32_bf16 v[60:63], v[182:185], v[166:169], v[60:63]
	v_mfma_f32_16x16x32_bf16 v[56:59], v[182:185], v[174:177], v[56:59]
	v_mfma_f32_16x16x32_bf16 v[52:55], v[190:193], v[166:169], v[52:55]
	v_mfma_f32_16x16x32_bf16 v[48:51], v[190:193], v[174:177], v[48:51]
	v_mfma_f32_16x16x32_bf16 v[44:47], v[198:201], v[166:169], v[44:47]
	v_mfma_f32_16x16x32_bf16 v[40:43], v[198:201], v[174:177], v[40:43]
	v_mfma_f32_16x16x32_bf16 v[36:39], v[208:211], v[166:169], v[36:39]
	v_mfma_f32_16x16x32_bf16 v[32:35], v[208:211], v[174:177], v[32:35]
	s_barrier
	s_setprio 0
	s_mov_b64 s[40:41], 0x80180
	v_readfirstlane_b32 s31, v155
	v_lshl_add_u64 v[162:163], v[230:231], 0, s[40:41]
	s_mov_b32 m0, s31
	s_mov_b64 s[40:41], 0xc0180
	v_readfirstlane_b32 s31, v157
	global_load_lds_dwordx4 v[162:163], off
	v_lshl_add_u64 v[162:163], v[230:231], 0, s[40:41]
	s_mov_b32 m0, s31
	s_nop 0
	global_load_lds_dwordx4 v[162:163], off
	s_waitcnt vmcnt(6)
	s_setprio 1
	s_barrier
	v_mfma_f32_16x16x32_bf16 v[28:31], v[178:181], v[212:215], v[28:31]
	v_mfma_f32_16x16x32_bf16 v[24:27], v[178:181], v[220:223], v[24:27]
	v_mfma_f32_16x16x32_bf16 v[20:23], v[186:189], v[212:215], v[20:23]
	v_mfma_f32_16x16x32_bf16 v[16:19], v[186:189], v[220:223], v[16:19]
	v_mfma_f32_16x16x32_bf16 v[12:15], v[194:197], v[212:215], v[12:15]
	v_mfma_f32_16x16x32_bf16 v[8:11], v[194:197], v[220:223], v[8:11]
	v_mfma_f32_16x16x32_bf16 v[4:7], v[202:205], v[212:215], v[4:7]
	v_mfma_f32_16x16x32_bf16 v[0:3], v[202:205], v[220:223], v[0:3]
	v_mfma_f32_16x16x32_bf16 v[28:31], v[182:185], v[216:219], v[28:31]
	v_mfma_f32_16x16x32_bf16 v[24:27], v[182:185], v[224:227], v[24:27]
	v_mfma_f32_16x16x32_bf16 v[20:23], v[190:193], v[216:219], v[20:23]
	v_mfma_f32_16x16x32_bf16 v[16:19], v[190:193], v[224:227], v[16:19]
	v_mfma_f32_16x16x32_bf16 v[12:15], v[198:201], v[216:219], v[12:15]
	v_mfma_f32_16x16x32_bf16 v[8:11], v[198:201], v[224:227], v[8:11]
	v_mfma_f32_16x16x32_bf16 v[4:7], v[208:211], v[216:219], v[4:7]
	v_mfma_f32_16x16x32_bf16 v[0:3], v[208:211], v[224:227], v[0:3]
	s_barrier
	s_setprio 0
	s_cmp_lt_u32 s9, 28
	s_cbranch_scc1 .LBB0_415
	s_add_u32 s6, s60, s6
	s_addc_u32 s7, s61, s7
	v_lshl_add_u64 v[128:129], s[6:7], 0, v[132:133]
	v_readfirstlane_b32 s6, v159
	s_mov_b32 m0, s6
	s_add_u32 s6, s60, s34
	v_lshl_add_u64 v[128:129], v[128:129], 0, s[28:29]
	s_addc_u32 s7, s61, s35
	ds_read_b128 v[150:153], v160
	ds_read_b128 v[162:165], v160 offset:1024
	ds_read_b128 v[166:169], v160 offset:2048
	ds_read_b128 v[170:173], v160 offset:3072
	ds_read_b128 v[174:177], v136
	ds_read_b128 v[178:181], v136 offset:1024
	ds_read_b128 v[182:185], v135
	ds_read_b128 v[186:189], v135 offset:1024
	ds_read_b128 v[190:193], v131
	ds_read_b128 v[194:197], v131 offset:1024
	ds_read_b128 v[198:201], v130
	ds_read_b128 v[202:205], v130 offset:1024
	global_load_lds_dwordx4 v[128:129], off
	v_lshl_add_u64 v[128:129], s[6:7], 0, v[132:133]
	v_readfirstlane_b32 s6, v158
	v_lshl_add_u64 v[128:129], v[128:129], 0, s[28:29]
	s_mov_b32 m0, s6
	s_nop 0
	global_load_lds_dwordx4 v[128:129], off
	s_setprio 1
	s_barrier
	s_waitcnt lgkmcnt(0)
	v_mfma_f32_16x16x32_bf16 v[124:127], v[174:177], v[150:153], v[124:127]
	v_mfma_f32_16x16x32_bf16 v[120:123], v[174:177], v[166:169], v[120:123]
	v_mfma_f32_16x16x32_bf16 v[116:119], v[182:185], v[150:153], v[116:119]
	v_mfma_f32_16x16x32_bf16 v[108:111], v[190:193], v[150:153], v[108:111]
	v_mfma_f32_16x16x32_bf16 v[124:127], v[178:181], v[162:165], v[124:127]
	v_mfma_f32_16x16x32_bf16 v[120:123], v[178:181], v[170:173], v[120:123]
	v_mfma_f32_16x16x32_bf16 v[116:119], v[186:189], v[162:165], v[116:119]
	v_mfma_f32_16x16x32_bf16 v[112:115], v[182:185], v[166:169], v[112:115]
	v_mfma_f32_16x16x32_bf16 v[108:111], v[194:197], v[162:165], v[108:111]
	v_mfma_f32_16x16x32_bf16 v[104:107], v[190:193], v[166:169], v[104:107]
	v_mfma_f32_16x16x32_bf16 v[100:103], v[198:201], v[150:153], v[100:103]
	v_mfma_f32_16x16x32_bf16 v[96:99], v[198:201], v[166:169], v[96:99]
	v_mfma_f32_16x16x32_bf16 v[158:161], v[186:189], v[170:173], v[112:115]
	v_mfma_f32_16x16x32_bf16 v[208:211], v[194:197], v[170:173], v[104:107]
	v_mfma_f32_16x16x32_bf16 v[212:215], v[202:205], v[162:165], v[100:103]
	v_mfma_f32_16x16x32_bf16 v[216:219], v[202:205], v[170:173], v[96:99]
	s_barrier
; #define WAIT_V(n) asm volatile("s_waitcnt vmcnt(" #n ")" ::: "memory")
; #define WAIT_L(n) asm volatile("s_waitcnt lgkmcnt(" #n ")" ::: "memory")
; #define BAR __builtin_amdgcn_s_barrier()
; template <int EPI>
; __device__ __forceinline__ void gemm_tile(const Params& p, const bf16* __restrict__ A, const bf16* __restrict__ Bt, const int K,
;                                           const int nt, const int brow, const int bcol, int pm, int pn) {
;     ...
;     BAR; WAIT_L(0); MMA(0, 0, At, B0); BAR;
;     LDB(B1, 0, 1); BAR; WAIT_L(0); MMA(0, 1, At, B1); BAR;
;     LDA(At, 0, 1); WAIT_V(4); BAR; WAIT_L(0); MMA(1, 0, At, B0); MMA(1, 1, At, B1); BAR; }
;   { LDB(B0, 1, 0); LDA(At, 1, 0); WAIT_V(2); BAR; WAIT_L(0); MMA(0, 0, At, B0); BAR;
;     LDB(B1, 1, 1); WAIT_V(0); BAR; WAIT_L(0); MMA(0, 1, At, B1); BAR;
	s_setprio 0
	s_nop 1
	ds_read_b128 v[96:99], v156
	ds_read_b128 v[100:103], v156 offset:1024
	ds_read_b128 v[104:107], v156 offset:2048
	ds_read_b128 v[112:115], v156 offset:3072
	s_setprio 1
	s_barrier
	s_waitcnt lgkmcnt(0)
	v_mfma_f32_16x16x32_bf16 v[92:95], v[174:177], v[96:99], v[92:95]
	v_mfma_f32_16x16x32_bf16 v[88:91], v[174:177], v[104:107], v[88:91]
	v_mfma_f32_16x16x32_bf16 v[84:87], v[182:185], v[96:99], v[84:87]
	v_mfma_f32_16x16x32_bf16 v[76:79], v[190:193], v[96:99], v[76:79]
	v_mfma_f32_16x16x32_bf16 v[92:95], v[178:181], v[100:103], v[92:95]
	v_mfma_f32_16x16x32_bf16 v[88:91], v[178:181], v[112:115], v[88:91]
	v_mfma_f32_16x16x32_bf16 v[84:87], v[186:189], v[100:103], v[84:87]
	v_mfma_f32_16x16x32_bf16 v[80:83], v[182:185], v[104:107], v[80:83]
	v_mfma_f32_16x16x32_bf16 v[76:79], v[194:197], v[100:103], v[76:79]
	v_mfma_f32_16x16x32_bf16 v[72:75], v[190:193], v[104:107], v[72:75]
	v_mfma_f32_16x16x32_bf16 v[68:71], v[198:201], v[96:99], v[68:71]
	v_mfma_f32_16x16x32_bf16 v[64:67], v[198:201], v[104:107], v[64:67]
	v_mfma_f32_16x16x32_bf16 v[154:157], v[186:189], v[112:115], v[80:83]
	v_mfma_f32_16x16x32_bf16 v[174:177], v[194:197], v[112:115], v[72:75]
	v_mfma_f32_16x16x32_bf16 v[178:181], v[202:205], v[100:103], v[68:71]
	v_mfma_f32_16x16x32_bf16 v[182:185], v[202:205], v[112:115], v[64:67]
	s_barrier
	s_setprio 0
	s_nop 1
	ds_read_b128 v[64:67], v136 offset:16384
	ds_read_b128 v[68:71], v136 offset:17408
	ds_read_b128 v[72:75], v135 offset:16384
	ds_read_b128 v[80:83], v135 offset:17408
	ds_read_b128 v[186:189], v131 offset:16384
	ds_read_b128 v[190:193], v131 offset:17408
	ds_read_b128 v[194:197], v130 offset:16384
	ds_read_b128 v[198:201], v130 offset:17408
	s_waitcnt vmcnt(4)
	s_setprio 1
	s_barrier
	s_waitcnt lgkmcnt(0)
	v_mfma_f32_16x16x32_bf16 v[60:63], v[64:67], v[150:153], v[60:63]
	v_mfma_f32_16x16x32_bf16 v[56:59], v[64:67], v[166:169], v[56:59]
	v_mfma_f32_16x16x32_bf16 v[52:55], v[72:75], v[150:153], v[52:55]
	v_mfma_f32_16x16x32_bf16 v[44:47], v[186:189], v[150:153], v[44:47]
	v_mfma_f32_16x16x32_bf16 v[60:63], v[68:71], v[162:165], v[60:63]
	v_mfma_f32_16x16x32_bf16 v[56:59], v[68:71], v[170:173], v[56:59]
	v_mfma_f32_16x16x32_bf16 v[52:55], v[80:83], v[162:165], v[52:55]
	v_mfma_f32_16x16x32_bf16 v[48:51], v[72:75], v[166:169], v[48:51]
	v_mfma_f32_16x16x32_bf16 v[44:47], v[190:193], v[162:165], v[44:47]
	v_mfma_f32_16x16x32_bf16 v[40:43], v[186:189], v[166:169], v[40:43]
	v_mfma_f32_16x16x32_bf16 v[36:39], v[194:197], v[150:153], v[36:39]
	v_mfma_f32_16x16x32_bf16 v[32:35], v[194:197], v[166:169], v[32:35]
	v_mfma_f32_16x16x32_bf16 v[202:205], v[80:83], v[170:173], v[48:51]
	v_mfma_f32_16x16x32_bf16 v[220:223], v[190:193], v[170:173], v[40:43]
	v_mfma_f32_16x16x32_bf16 v[150:153], v[198:201], v[162:165], v[36:39]
	v_mfma_f32_16x16x32_bf16 v[162:165], v[198:201], v[170:173], v[32:35]
	s_setprio 0
	s_setprio 1
	v_mfma_f32_16x16x32_bf16 v[28:31], v[64:67], v[96:99], v[28:31]
	v_mfma_f32_16x16x32_bf16 v[24:27], v[64:67], v[104:107], v[24:27]
	v_mfma_f32_16x16x32_bf16 v[20:23], v[72:75], v[96:99], v[20:23]
	v_mfma_f32_16x16x32_bf16 v[12:15], v[186:189], v[96:99], v[12:15]
	v_mfma_f32_16x16x32_bf16 v[28:31], v[68:71], v[100:103], v[28:31]
	v_mfma_f32_16x16x32_bf16 v[24:27], v[68:71], v[112:115], v[24:27]
	v_mfma_f32_16x16x32_bf16 v[20:23], v[80:83], v[100:103], v[20:23]
	v_mfma_f32_16x16x32_bf16 v[16:19], v[72:75], v[104:107], v[16:19]
	v_mfma_f32_16x16x32_bf16 v[12:15], v[190:193], v[100:103], v[12:15]
	v_mfma_f32_16x16x32_bf16 v[8:11], v[186:189], v[104:107], v[8:11]
	v_mfma_f32_16x16x32_bf16 v[4:7], v[194:197], v[96:99], v[4:7]
	v_mfma_f32_16x16x32_bf16 v[0:3], v[194:197], v[104:107], v[0:3]
	v_mfma_f32_16x16x32_bf16 v[166:169], v[80:83], v[112:115], v[16:19]
	v_mfma_f32_16x16x32_bf16 v[170:173], v[190:193], v[112:115], v[8:11]
	v_mfma_f32_16x16x32_bf16 v[186:189], v[198:201], v[100:103], v[4:7]
	v_mfma_f32_16x16x32_bf16 v[190:193], v[198:201], v[112:115], v[0:3]
	s_barrier
	s_setprio 0
	s_nop 1
	ds_read_b128 v[0:3], v149
	ds_read_b128 v[4:7], v149 offset:1024
	ds_read_b128 v[8:11], v149 offset:2048
	ds_read_b128 v[16:19], v149 offset:3072
	ds_read_b128 v[32:35], v136 offset:32768
	ds_read_b128 v[36:39], v136 offset:33792
	ds_read_b128 v[40:43], v135 offset:32768
	ds_read_b128 v[48:51], v135 offset:33792
	ds_read_b128 v[194:197], v131 offset:32768
	ds_read_b128 v[198:201], v131 offset:33792
	ds_read_b128 v[224:227], v130 offset:32768
	ds_read_b128 v[228:231], v130 offset:33792
	s_waitcnt vmcnt(2)
	s_setprio 1
	s_barrier
; #define WAIT_V(n) asm volatile("s_waitcnt vmcnt(" #n ")" ::: "memory")
; #define WAIT_L(n) asm volatile("s_waitcnt lgkmcnt(" #n ")" ::: "memory")
; #define BAR __builtin_amdgcn_s_barrier()
; template <int EPI>
; __device__ __forceinline__ void gemm_tile(const Params& p, const bf16* __restrict__ A, const bf16* __restrict__ Bt, const int K,
;                                           const int nt, const int brow, const int bcol, int pm, int pn) {
;     ...
;   { LDB(B0, 1, 0); LDA(At, 1, 0); WAIT_V(2); BAR; WAIT_L(0); MMA(0, 0, At, B0); BAR;
;     LDB(B1, 1, 1); WAIT_V(0); BAR; WAIT_L(0); MMA(0, 1, At, B1); BAR;
;     LDA(At, 1, 1); BAR; WAIT_L(0); MMA(1, 0, At, B0); MMA(1, 1, At, B1); BAR; }
;   if (wr == 0) BAR;
	s_waitcnt lgkmcnt(0)
	v_mfma_f32_16x16x32_bf16 v[64:67], v[32:35], v[0:3], v[124:127]
	v_mfma_f32_16x16x32_bf16 v[96:99], v[36:39], v[4:7], v[64:67]
	v_mfma_f32_16x16x32_bf16 v[64:67], v[32:35], v[8:11], v[120:123]
	v_mfma_f32_16x16x32_bf16 v[112:115], v[36:39], v[16:19], v[64:67]
	v_mfma_f32_16x16x32_bf16 v[64:67], v[40:43], v[0:3], v[116:119]
	v_mfma_f32_16x16x32_bf16 v[100:103], v[48:51], v[4:7], v[64:67]
	v_mfma_f32_16x16x32_bf16 v[64:67], v[40:43], v[8:11], v[158:161]
	v_mfma_f32_16x16x32_bf16 v[116:119], v[48:51], v[16:19], v[64:67]
	v_mfma_f32_16x16x32_bf16 v[64:67], v[194:197], v[0:3], v[108:111]
	v_mfma_f32_16x16x32_bf16 v[104:107], v[198:201], v[4:7], v[64:67]
	v_mfma_f32_16x16x32_bf16 v[64:67], v[194:197], v[8:11], v[208:211]
	v_mfma_f32_16x16x32_bf16 v[120:123], v[198:201], v[16:19], v[64:67]
	v_mfma_f32_16x16x32_bf16 v[64:67], v[224:227], v[0:3], v[212:215]
	v_mfma_f32_16x16x32_bf16 v[108:111], v[228:231], v[4:7], v[64:67]
	v_mfma_f32_16x16x32_bf16 v[64:67], v[224:227], v[8:11], v[216:219]
	v_mfma_f32_16x16x32_bf16 v[124:127], v[228:231], v[16:19], v[64:67]
	s_barrier
	s_setprio 0
	ds_read_b128 v[158:161], v139
	ds_read_b128 v[208:211], v139 offset:1024
	ds_read_b128 v[212:215], v139 offset:2048
	ds_read_b128 v[138:141], v139 offset:3072
	s_waitcnt vmcnt(0)
	s_setprio 1
	s_barrier
	s_waitcnt lgkmcnt(0)
	v_mfma_f32_16x16x32_bf16 v[64:67], v[32:35], v[158:161], v[92:95]
	v_mfma_f32_16x16x32_bf16 v[32:35], v[32:35], v[212:215], v[88:91]
	v_mfma_f32_16x16x32_bf16 v[80:83], v[36:39], v[138:141], v[32:35]
	v_mfma_f32_16x16x32_bf16 v[32:35], v[40:43], v[158:161], v[84:87]
	v_mfma_f32_16x16x32_bf16 v[68:71], v[48:51], v[208:211], v[32:35]
	v_mfma_f32_16x16x32_bf16 v[32:35], v[40:43], v[212:215], v[154:157]
	v_mfma_f32_16x16x32_bf16 v[84:87], v[48:51], v[138:141], v[32:35]
	v_mfma_f32_16x16x32_bf16 v[32:35], v[194:197], v[158:161], v[76:79]
	v_mfma_f32_16x16x32_bf16 v[72:75], v[198:201], v[208:211], v[32:35]
	v_mfma_f32_16x16x32_bf16 v[32:35], v[194:197], v[212:215], v[174:177]
	v_mfma_f32_16x16x32_bf16 v[88:91], v[198:201], v[138:141], v[32:35]
	v_mfma_f32_16x16x32_bf16 v[32:35], v[224:227], v[158:161], v[178:181]
	v_mfma_f32_16x16x32_bf16 v[76:79], v[228:231], v[208:211], v[32:35]
	v_mfma_f32_16x16x32_bf16 v[32:35], v[224:227], v[212:215], v[182:185]
	v_mfma_f32_16x16x32_bf16 v[64:67], v[36:39], v[208:211], v[64:67]
	v_mfma_f32_16x16x32_bf16 v[92:95], v[228:231], v[138:141], v[32:35]
	s_barrier
	s_setprio 0
	ds_read_b128 v[154:157], v136 offset:49152
	ds_read_b128 v[174:177], v136 offset:50176
	ds_read_b128 v[178:181], v135 offset:49152
	ds_read_b128 v[134:137], v135 offset:50176
	ds_read_b128 v[182:185], v131 offset:49152
	ds_read_b128 v[194:197], v131 offset:50176
	ds_read_b128 v[198:201], v130 offset:49152
	ds_read_b128 v[128:131], v130 offset:50176
	s_setprio 1
	s_barrier
	s_waitcnt lgkmcnt(0)
	v_mfma_f32_16x16x32_bf16 v[36:39], v[154:157], v[8:11], v[56:59]
	v_mfma_f32_16x16x32_bf16 v[40:43], v[178:181], v[8:11], v[202:205]
	v_mfma_f32_16x16x32_bf16 v[32:35], v[154:157], v[0:3], v[60:63]
	v_mfma_f32_16x16x32_bf16 v[48:51], v[174:177], v[16:19], v[36:39]
	v_mfma_f32_16x16x32_bf16 v[36:39], v[178:181], v[0:3], v[52:55]
	v_mfma_f32_16x16x32_bf16 v[52:55], v[134:137], v[16:19], v[40:43]
	v_mfma_f32_16x16x32_bf16 v[40:43], v[182:185], v[0:3], v[44:47]
	v_mfma_f32_16x16x32_bf16 v[44:47], v[182:185], v[8:11], v[220:223]
	v_mfma_f32_16x16x32_bf16 v[0:3], v[198:201], v[0:3], v[150:153]
	v_mfma_f32_16x16x32_bf16 v[56:59], v[194:197], v[16:19], v[44:47]
	v_mfma_f32_16x16x32_bf16 v[44:47], v[128:131], v[4:7], v[0:3]
	v_mfma_f32_16x16x32_bf16 v[0:3], v[198:201], v[8:11], v[162:165]
	v_mfma_f32_16x16x32_bf16 v[32:35], v[174:177], v[4:7], v[32:35]
	v_mfma_f32_16x16x32_bf16 v[36:39], v[134:137], v[4:7], v[36:39]
	v_mfma_f32_16x16x32_bf16 v[40:43], v[194:197], v[4:7], v[40:43]
	v_mfma_f32_16x16x32_bf16 v[60:63], v[128:131], v[16:19], v[0:3]
	s_setprio 0
	s_setprio 1
	v_mfma_f32_16x16x32_bf16 v[4:7], v[154:157], v[212:215], v[24:27]
	v_mfma_f32_16x16x32_bf16 v[8:11], v[178:181], v[212:215], v[166:169]
	v_mfma_f32_16x16x32_bf16 v[16:19], v[174:177], v[138:141], v[4:7]
	v_mfma_f32_16x16x32_bf16 v[4:7], v[178:181], v[158:161], v[20:23]
	v_mfma_f32_16x16x32_bf16 v[20:23], v[134:137], v[138:141], v[8:11]
	v_mfma_f32_16x16x32_bf16 v[8:11], v[182:185], v[158:161], v[12:15]
	v_mfma_f32_16x16x32_bf16 v[12:15], v[182:185], v[212:215], v[170:173]
	v_mfma_f32_16x16x32_bf16 v[0:3], v[154:157], v[158:161], v[28:31]
	v_mfma_f32_16x16x32_bf16 v[24:27], v[194:197], v[138:141], v[12:15]
	v_mfma_f32_16x16x32_bf16 v[12:15], v[198:201], v[158:161], v[186:189]
	v_mfma_f32_16x16x32_bf16 v[28:31], v[198:201], v[212:215], v[190:193]
	v_mfma_f32_16x16x32_bf16 v[0:3], v[174:177], v[208:211], v[0:3]
	v_mfma_f32_16x16x32_bf16 v[4:7], v[134:137], v[208:211], v[4:7]
	v_mfma_f32_16x16x32_bf16 v[8:11], v[194:197], v[208:211], v[8:11]
	v_mfma_f32_16x16x32_bf16 v[12:15], v[128:131], v[208:211], v[12:15]
	v_mfma_f32_16x16x32_bf16 v[28:31], v[128:131], v[138:141], v[28:31]
	s_barrier
	s_setprio 0
	s_cmpk_gt_u32 s5, 0xff
	s_cbranch_scc1 .LBB0_418
	s_barrier

; #define WAIT_L(n) asm volatile("s_waitcnt lgkmcnt(" #n ")" ::: "memory")
; #define BAR __builtin_amdgcn_s_barrier()
; #define SCHED __builtin_amdgcn_sched_barrier(0)
; template <int EPI>
; __device__ __forceinline__ void gemm_tile(const Params& p, const bf16* __restrict__ A, const bf16* __restrict__ Bt, const int K,
;                                           const int nt, const int brow, const int bcol, int pm, int pn) {
;     ...
;     LDB(B0, 0, 0); SCHED; LDA(At, 0, 0); STAGE(SA(1, 1), A, brow + HALF, t + 1);
;     WAIT_L(8); BAR; WAIT_L(0); MMA(0, 0, At, B0); BAR; SCHED;
;     LDB(B1, 0, 1); STAGE(SB(0, 0), Bt, bcol, t + 2);
;     BAR; WAIT_L(0); MMA(0, 1, At, B1); BAR;
;     LDA(At, 0, 1); STAGE(SA(0, 0), A, brow, t + 2);
;     BAR; WAIT_L(0); MMA(1, 0, At, B0); BAR; SCHED;
.LBB0_1378:
	ds_read_b128 v[158:161], v153
	ds_read_b128 v[162:165], v153 offset:1024
	ds_read_b128 v[166:169], v153 offset:2048
	ds_read_b128 v[170:173], v153 offset:3072
	v_lshl_add_u64 v[154:155], s[52:53], 0, v[128:129]
	s_mov_b64 s[66:67], 0x14602080
	v_readfirstlane_b32 s57, v151
	v_lshl_add_u64 v[204:205], v[154:155], 0, s[66:67]
	s_mov_b32 m0, s57
	s_mov_b64 s[66:67], 0x14642080
	v_readfirstlane_b32 s57, v150
	ds_read_b128 v[174:177], v147
	ds_read_b128 v[178:181], v147 offset:1024
	ds_read_b128 v[182:185], v146
	ds_read_b128 v[186:189], v146 offset:1024
	ds_read_b128 v[190:193], v145
	ds_read_b128 v[196:199], v145 offset:1024
	ds_read_b128 v[200:203], v144
	ds_read_b128 v[208:211], v144 offset:1024
	global_load_lds_dwordx4 v[204:205], off
	v_lshl_add_u64 v[204:205], v[154:155], 0, s[66:67]
	s_mov_b32 m0, s57
	s_nop 0
	global_load_lds_dwordx4 v[204:205], off
	s_waitcnt lgkmcnt(8)
	s_setprio 1
	s_barrier
	s_waitcnt lgkmcnt(0)
	v_mfma_f32_16x16x32_bf16 v[124:127], v[174:177], v[158:161], v[124:127]
	v_mfma_f32_16x16x32_bf16 v[120:123], v[174:177], v[166:169], v[120:123]
	v_mfma_f32_16x16x32_bf16 v[116:119], v[182:185], v[158:161], v[116:119]
	v_mfma_f32_16x16x32_bf16 v[112:115], v[182:185], v[166:169], v[112:115]
	v_mfma_f32_16x16x32_bf16 v[108:111], v[190:193], v[158:161], v[108:111]
	v_mfma_f32_16x16x32_bf16 v[104:107], v[190:193], v[166:169], v[104:107]
	v_mfma_f32_16x16x32_bf16 v[100:103], v[200:203], v[158:161], v[100:103]
	v_mfma_f32_16x16x32_bf16 v[96:99], v[200:203], v[166:169], v[96:99]
	v_mfma_f32_16x16x32_bf16 v[124:127], v[178:181], v[162:165], v[124:127]
	v_mfma_f32_16x16x32_bf16 v[120:123], v[178:181], v[170:173], v[120:123]
	v_mfma_f32_16x16x32_bf16 v[116:119], v[186:189], v[162:165], v[116:119]
	v_mfma_f32_16x16x32_bf16 v[112:115], v[186:189], v[170:173], v[112:115]
	v_mfma_f32_16x16x32_bf16 v[108:111], v[196:199], v[162:165], v[108:111]
	v_mfma_f32_16x16x32_bf16 v[104:107], v[196:199], v[170:173], v[104:107]
	v_mfma_f32_16x16x32_bf16 v[100:103], v[208:211], v[162:165], v[100:103]
	v_mfma_f32_16x16x32_bf16 v[96:99], v[208:211], v[170:173], v[96:99]
	s_barrier
	s_setprio 0
	v_lshl_add_u64 v[204:205], s[54:55], 0, v[128:129]
	s_mov_b64 s[66:67], 0x1800100
	v_readfirstlane_b32 s57, v130
	v_lshl_add_u64 v[228:229], v[204:205], 0, s[66:67]
	s_mov_b32 m0, s57
	s_mov_b64 s[66:67], 0x1840100
	v_readfirstlane_b32 s57, v131
	ds_read_b128 v[212:215], v149
	ds_read_b128 v[216:219], v149 offset:1024
	ds_read_b128 v[220:223], v149 offset:2048
	ds_read_b128 v[224:227], v149 offset:3072
	global_load_lds_dwordx4 v[228:229], off
	v_lshl_add_u64 v[228:229], v[204:205], 0, s[66:67]
	s_mov_b32 m0, s57
	s_nop 0
	global_load_lds_dwordx4 v[228:229], off
	s_setprio 1
	s_barrier
	s_waitcnt lgkmcnt(0)
	v_mfma_f32_16x16x32_bf16 v[92:95], v[174:177], v[212:215], v[92:95]
	v_mfma_f32_16x16x32_bf16 v[88:91], v[174:177], v[220:223], v[88:91]
	v_mfma_f32_16x16x32_bf16 v[84:87], v[182:185], v[212:215], v[84:87]
	v_mfma_f32_16x16x32_bf16 v[80:83], v[182:185], v[220:223], v[80:83]
	v_mfma_f32_16x16x32_bf16 v[76:79], v[190:193], v[212:215], v[76:79]
	v_mfma_f32_16x16x32_bf16 v[72:75], v[190:193], v[220:223], v[72:75]
	v_mfma_f32_16x16x32_bf16 v[68:71], v[200:203], v[212:215], v[68:71]
	v_mfma_f32_16x16x32_bf16 v[64:67], v[200:203], v[220:223], v[64:67]
	v_mfma_f32_16x16x32_bf16 v[92:95], v[178:181], v[216:219], v[92:95]
	v_mfma_f32_16x16x32_bf16 v[88:91], v[178:181], v[224:227], v[88:91]
	v_mfma_f32_16x16x32_bf16 v[84:87], v[186:189], v[216:219], v[84:87]
	v_mfma_f32_16x16x32_bf16 v[80:83], v[186:189], v[224:227], v[80:83]
	v_mfma_f32_16x16x32_bf16 v[76:79], v[196:199], v[216:219], v[76:79]
	v_mfma_f32_16x16x32_bf16 v[72:75], v[196:199], v[224:227], v[72:75]
	v_mfma_f32_16x16x32_bf16 v[68:71], v[208:211], v[216:219], v[68:71]
	v_mfma_f32_16x16x32_bf16 v[64:67], v[208:211], v[224:227], v[64:67]
	s_barrier
	s_setprio 0
	s_mov_b64 s[66:67], 0x14582100
	v_readfirstlane_b32 s57, v132
	v_lshl_add_u64 v[228:229], v[154:155], 0, s[66:67]
	s_mov_b32 m0, s57
	v_readfirstlane_b32 s57, v133
	ds_read_b128 v[174:177], v147 offset:16384
	ds_read_b128 v[178:181], v147 offset:17408
	ds_read_b128 v[182:185], v146 offset:16384
	ds_read_b128 v[186:189], v146 offset:17408
	ds_read_b128 v[190:193], v145 offset:16384
	ds_read_b128 v[196:199], v145 offset:17408
	ds_read_b128 v[200:203], v144 offset:16384
	ds_read_b128 v[208:211], v144 offset:17408
	global_load_lds_dwordx4 v[228:229], off
	v_lshl_add_u64 v[228:229], v[154:155], 0, s[14:15]
	s_mov_b32 m0, s57
	s_nop 0
	global_load_lds_dwordx4 v[228:229], off
	s_setprio 1
	s_barrier
	s_waitcnt lgkmcnt(0)
	v_mfma_f32_16x16x32_bf16 v[60:63], v[174:177], v[158:161], v[60:63]
	v_mfma_f32_16x16x32_bf16 v[56:59], v[174:177], v[166:169], v[56:59]
	v_mfma_f32_16x16x32_bf16 v[52:55], v[182:185], v[158:161], v[52:55]
	v_mfma_f32_16x16x32_bf16 v[48:51], v[182:185], v[166:169], v[48:51]
	v_mfma_f32_16x16x32_bf16 v[44:47], v[190:193], v[158:161], v[44:47]
	v_mfma_f32_16x16x32_bf16 v[40:43], v[190:193], v[166:169], v[40:43]
	v_mfma_f32_16x16x32_bf16 v[36:39], v[200:203], v[158:161], v[36:39]
	v_mfma_f32_16x16x32_bf16 v[32:35], v[200:203], v[166:169], v[32:35]
	v_mfma_f32_16x16x32_bf16 v[60:63], v[178:181], v[162:165], v[60:63]
	v_mfma_f32_16x16x32_bf16 v[56:59], v[178:181], v[170:173], v[56:59]
	v_mfma_f32_16x16x32_bf16 v[52:55], v[186:189], v[162:165], v[52:55]
	v_mfma_f32_16x16x32_bf16 v[48:51], v[186:189], v[170:173], v[48:51]
	v_mfma_f32_16x16x32_bf16 v[44:47], v[196:199], v[162:165], v[44:47]
	v_mfma_f32_16x16x32_bf16 v[40:43], v[196:199], v[170:173], v[40:43]
	v_mfma_f32_16x16x32_bf16 v[36:39], v[208:211], v[162:165], v[36:39]
	v_mfma_f32_16x16x32_bf16 v[32:35], v[208:211], v[170:173], v[32:35]
	s_barrier
; #define WAIT_V(n) asm volatile("s_waitcnt vmcnt(" #n ")" ::: "memory")
; #define WAIT_L(n) asm volatile("s_waitcnt lgkmcnt(" #n ")" ::: "memory")
; #define BAR __builtin_amdgcn_s_barrier()
; #define SCHED __builtin_amdgcn_sched_barrier(0)
; template <int EPI>
; __device__ __forceinline__ void gemm_tile(const Params& p, const bf16* __restrict__ A, const bf16* __restrict__ Bt, const int K,
;                                           const int nt, const int brow, const int bcol, int pm, int pn) {
;     ...
;     STAGE(SB(0, 1), Bt, bcol + HALF, t + 2);
;     WAIT_V(6); BAR; MMA(1, 1, At, B1); BAR;
;     LDB(B0, 1, 0); SCHED; LDA(At, 1, 0); STAGE(SA(0, 1), A, brow + HALF, t + 2);
;     WAIT_L(8); BAR; WAIT_L(0); MMA(0, 0, At, B0); BAR; SCHED;
;     LDB(B1, 1, 1); STAGE(SB(1, 0), Bt, bcol, t + 3);
;     BAR; WAIT_L(0); MMA(0, 1, At, B1); BAR;
;     LDA(At, 1, 1); STAGE(SA(1, 0), A, brow, t + 3);
	s_setprio 0
	s_add_i32 s56, s56, 2
	s_add_u32 s52, s52, 0x100
	s_addc_u32 s53, s53, 0
	s_add_u32 s54, s54, 0x100
	s_addc_u32 s55, s55, 0
	v_readfirstlane_b32 s57, v134
	v_lshl_add_u64 v[158:159], v[204:205], 0, s[16:17]
	s_mov_b32 m0, s57
	v_readfirstlane_b32 s57, v135
	global_load_lds_dwordx4 v[158:159], off
	v_lshl_add_u64 v[158:159], v[204:205], 0, s[18:19]
	s_mov_b32 m0, s57
	s_nop 0
	global_load_lds_dwordx4 v[158:159], off
	s_waitcnt vmcnt(6)
	s_setprio 1
	s_barrier
	v_mfma_f32_16x16x32_bf16 v[28:31], v[174:177], v[212:215], v[28:31]
	v_mfma_f32_16x16x32_bf16 v[24:27], v[174:177], v[220:223], v[24:27]
	v_mfma_f32_16x16x32_bf16 v[20:23], v[182:185], v[212:215], v[20:23]
	v_mfma_f32_16x16x32_bf16 v[16:19], v[182:185], v[220:223], v[16:19]
	v_mfma_f32_16x16x32_bf16 v[12:15], v[190:193], v[212:215], v[12:15]
	v_mfma_f32_16x16x32_bf16 v[8:11], v[190:193], v[220:223], v[8:11]
	v_mfma_f32_16x16x32_bf16 v[4:7], v[200:203], v[212:215], v[4:7]
	v_mfma_f32_16x16x32_bf16 v[0:3], v[200:203], v[220:223], v[0:3]
	v_mfma_f32_16x16x32_bf16 v[28:31], v[178:181], v[216:219], v[28:31]
	v_mfma_f32_16x16x32_bf16 v[24:27], v[178:181], v[224:227], v[24:27]
	v_mfma_f32_16x16x32_bf16 v[20:23], v[186:189], v[216:219], v[20:23]
	v_mfma_f32_16x16x32_bf16 v[16:19], v[186:189], v[224:227], v[16:19]
	v_mfma_f32_16x16x32_bf16 v[12:15], v[196:199], v[216:219], v[12:15]
	v_mfma_f32_16x16x32_bf16 v[8:11], v[196:199], v[224:227], v[8:11]
	v_mfma_f32_16x16x32_bf16 v[4:7], v[208:211], v[216:219], v[4:7]
	v_mfma_f32_16x16x32_bf16 v[0:3], v[208:211], v[224:227], v[0:3]
	s_barrier
	s_setprio 0
	ds_read_b128 v[158:161], v138
	ds_read_b128 v[162:165], v138 offset:1024
	ds_read_b128 v[166:169], v138 offset:2048
	ds_read_b128 v[170:173], v138 offset:3072
	v_readfirstlane_b32 s57, v136
	v_lshl_add_u64 v[212:213], v[154:155], 0, s[20:21]
	s_mov_b32 m0, s57
	v_readfirstlane_b32 s57, v137
	ds_read_b128 v[174:177], v147 offset:32768
	ds_read_b128 v[178:181], v147 offset:33792
	ds_read_b128 v[182:185], v146 offset:32768
	ds_read_b128 v[186:189], v146 offset:33792
	ds_read_b128 v[190:193], v145 offset:32768
	ds_read_b128 v[196:199], v145 offset:33792
	ds_read_b128 v[200:203], v144 offset:32768
	ds_read_b128 v[208:211], v144 offset:33792
	global_load_lds_dwordx4 v[212:213], off
	v_lshl_add_u64 v[212:213], v[154:155], 0, s[22:23]
	s_mov_b32 m0, s57
	s_nop 0
	global_load_lds_dwordx4 v[212:213], off
	s_waitcnt lgkmcnt(8)
	s_setprio 1
	s_barrier
	s_waitcnt lgkmcnt(0)
	v_mfma_f32_16x16x32_bf16 v[124:127], v[174:177], v[158:161], v[124:127]
	v_mfma_f32_16x16x32_bf16 v[120:123], v[174:177], v[166:169], v[120:123]
	v_mfma_f32_16x16x32_bf16 v[116:119], v[182:185], v[158:161], v[116:119]
	v_mfma_f32_16x16x32_bf16 v[112:115], v[182:185], v[166:169], v[112:115]
	v_mfma_f32_16x16x32_bf16 v[108:111], v[190:193], v[158:161], v[108:111]
	v_mfma_f32_16x16x32_bf16 v[104:107], v[190:193], v[166:169], v[104:107]
	v_mfma_f32_16x16x32_bf16 v[100:103], v[200:203], v[158:161], v[100:103]
	v_mfma_f32_16x16x32_bf16 v[96:99], v[200:203], v[166:169], v[96:99]
	v_mfma_f32_16x16x32_bf16 v[124:127], v[178:181], v[162:165], v[124:127]
	v_mfma_f32_16x16x32_bf16 v[120:123], v[178:181], v[170:173], v[120:123]
	v_mfma_f32_16x16x32_bf16 v[116:119], v[186:189], v[162:165], v[116:119]
	v_mfma_f32_16x16x32_bf16 v[112:115], v[186:189], v[170:173], v[112:115]
	v_mfma_f32_16x16x32_bf16 v[108:111], v[196:199], v[162:165], v[108:111]
	v_mfma_f32_16x16x32_bf16 v[104:107], v[196:199], v[170:173], v[104:107]
	v_mfma_f32_16x16x32_bf16 v[100:103], v[208:211], v[162:165], v[100:103]
	v_mfma_f32_16x16x32_bf16 v[96:99], v[208:211], v[170:173], v[96:99]
	s_barrier
	s_setprio 0
	v_readfirstlane_b32 s57, v139
	v_lshl_add_u64 v[228:229], v[204:205], 0, s[24:25]
	s_mov_b32 m0, s57
	v_readfirstlane_b32 s57, v140
	ds_read_b128 v[212:215], v152
	ds_read_b128 v[216:219], v152 offset:1024
	ds_read_b128 v[220:223], v152 offset:2048
	ds_read_b128 v[224:227], v152 offset:3072
	global_load_lds_dwordx4 v[228:229], off
	v_lshl_add_u64 v[228:229], v[204:205], 0, s[26:27]
	s_mov_b32 m0, s57
	s_nop 0
	global_load_lds_dwordx4 v[228:229], off
	s_setprio 1
	s_barrier
	s_waitcnt lgkmcnt(0)
	v_mfma_f32_16x16x32_bf16 v[92:95], v[174:177], v[212:215], v[92:95]
	v_mfma_f32_16x16x32_bf16 v[88:91], v[174:177], v[220:223], v[88:91]
	v_mfma_f32_16x16x32_bf16 v[84:87], v[182:185], v[212:215], v[84:87]
	v_mfma_f32_16x16x32_bf16 v[80:83], v[182:185], v[220:223], v[80:83]
	v_mfma_f32_16x16x32_bf16 v[76:79], v[190:193], v[212:215], v[76:79]
	v_mfma_f32_16x16x32_bf16 v[72:75], v[190:193], v[220:223], v[72:75]
	v_mfma_f32_16x16x32_bf16 v[68:71], v[200:203], v[212:215], v[68:71]
	v_mfma_f32_16x16x32_bf16 v[64:67], v[200:203], v[220:223], v[64:67]
	v_mfma_f32_16x16x32_bf16 v[92:95], v[178:181], v[216:219], v[92:95]
	v_mfma_f32_16x16x32_bf16 v[88:91], v[178:181], v[224:227], v[88:91]
	v_mfma_f32_16x16x32_bf16 v[84:87], v[186:189], v[216:219], v[84:87]
	v_mfma_f32_16x16x32_bf16 v[80:83], v[186:189], v[224:227], v[80:83]
	v_mfma_f32_16x16x32_bf16 v[76:79], v[196:199], v[216:219], v[76:79]
	v_mfma_f32_16x16x32_bf16 v[72:75], v[196:199], v[224:227], v[72:75]
	v_mfma_f32_16x16x32_bf16 v[68:71], v[208:211], v[216:219], v[68:71]
	v_mfma_f32_16x16x32_bf16 v[64:67], v[208:211], v[224:227], v[64:67]
	s_barrier
	s_setprio 0
	v_readfirstlane_b32 s57, v141
	v_lshl_add_u64 v[228:229], v[154:155], 0, s[28:29]
	s_mov_b32 m0, s57
	v_readfirstlane_b32 s57, v142
	ds_read_b128 v[174:177], v147 offset:49152
	ds_read_b128 v[178:181], v147 offset:50176
	ds_read_b128 v[182:185], v146 offset:49152
	ds_read_b128 v[186:189], v146 offset:50176
	ds_read_b128 v[190:193], v145 offset:49152
	ds_read_b128 v[196:199], v145 offset:50176
	ds_read_b128 v[200:203], v144 offset:49152
	ds_read_b128 v[208:211], v144 offset:50176
	global_load_lds_dwordx4 v[228:229], off
	v_lshl_add_u64 v[154:155], v[154:155], 0, s[30:31]
	s_mov_b32 m0, s57
	s_nop 0
	global_load_lds_dwordx4 v[154:155], off
	s_setprio 1
	s_barrier
; #define WAIT_V(n) asm volatile("s_waitcnt vmcnt(" #n ")" ::: "memory")
; #define WAIT_L(n) asm volatile("s_waitcnt lgkmcnt(" #n ")" ::: "memory")
; #define BAR __builtin_amdgcn_s_barrier()
; #define SCHED __builtin_amdgcn_sched_barrier(0)
; template <int EPI>
; __device__ __forceinline__ void gemm_tile(const Params& p, const bf16* __restrict__ A, const bf16* __restrict__ Bt, const int K,
;                                           const int nt, const int brow, const int bcol, int pm, int pn) {
;     ...
;     BAR; WAIT_L(0); MMA(1, 0, At, B0); BAR; SCHED;
;     STAGE(SB(1, 1), Bt, bcol + HALF, t + 3);
;     WAIT_V(6); BAR; MMA(1, 1, At, B1); BAR;
;   }
;   { LDB(B0, 0, 0); LDA(At, 0, 0); STAGE(SA(1, 1), A, brow + HALF, nt - 1);
;     BAR; WAIT_L(0); MMA(0, 0, At, B0); BAR;
;     LDB(B1, 0, 1); BAR; WAIT_L(0); MMA(0, 1, At, B1); BAR;
	s_waitcnt lgkmcnt(0)
	v_mfma_f32_16x16x32_bf16 v[60:63], v[174:177], v[158:161], v[60:63]
	v_mfma_f32_16x16x32_bf16 v[56:59], v[174:177], v[166:169], v[56:59]
	v_mfma_f32_16x16x32_bf16 v[52:55], v[182:185], v[158:161], v[52:55]
	v_mfma_f32_16x16x32_bf16 v[48:51], v[182:185], v[166:169], v[48:51]
	v_mfma_f32_16x16x32_bf16 v[44:47], v[190:193], v[158:161], v[44:47]
	v_mfma_f32_16x16x32_bf16 v[40:43], v[190:193], v[166:169], v[40:43]
	v_mfma_f32_16x16x32_bf16 v[36:39], v[200:203], v[158:161], v[36:39]
	v_mfma_f32_16x16x32_bf16 v[32:35], v[200:203], v[166:169], v[32:35]
	v_mfma_f32_16x16x32_bf16 v[60:63], v[178:181], v[162:165], v[60:63]
	v_mfma_f32_16x16x32_bf16 v[56:59], v[178:181], v[170:173], v[56:59]
	v_mfma_f32_16x16x32_bf16 v[52:55], v[186:189], v[162:165], v[52:55]
	v_mfma_f32_16x16x32_bf16 v[48:51], v[186:189], v[170:173], v[48:51]
	v_mfma_f32_16x16x32_bf16 v[44:47], v[196:199], v[162:165], v[44:47]
	v_mfma_f32_16x16x32_bf16 v[40:43], v[196:199], v[170:173], v[40:43]
	v_mfma_f32_16x16x32_bf16 v[36:39], v[208:211], v[162:165], v[36:39]
	v_mfma_f32_16x16x32_bf16 v[32:35], v[208:211], v[170:173], v[32:35]
	s_barrier
	s_setprio 0
	v_readfirstlane_b32 s57, v143
	v_lshl_add_u64 v[154:155], v[204:205], 0, s[34:35]
	s_mov_b32 m0, s57
	v_readfirstlane_b32 s57, v148
	global_load_lds_dwordx4 v[154:155], off
	v_lshl_add_u64 v[154:155], v[204:205], 0, s[36:37]
	s_mov_b32 m0, s57
	s_nop 0
	global_load_lds_dwordx4 v[154:155], off
	s_waitcnt vmcnt(6)
	s_setprio 1
	s_barrier
	v_mfma_f32_16x16x32_bf16 v[28:31], v[174:177], v[212:215], v[28:31]
	v_mfma_f32_16x16x32_bf16 v[24:27], v[174:177], v[220:223], v[24:27]
	v_mfma_f32_16x16x32_bf16 v[20:23], v[182:185], v[212:215], v[20:23]
	v_mfma_f32_16x16x32_bf16 v[16:19], v[182:185], v[220:223], v[16:19]
	v_mfma_f32_16x16x32_bf16 v[12:15], v[190:193], v[212:215], v[12:15]
	v_mfma_f32_16x16x32_bf16 v[8:11], v[190:193], v[220:223], v[8:11]
	v_mfma_f32_16x16x32_bf16 v[4:7], v[200:203], v[212:215], v[4:7]
	v_mfma_f32_16x16x32_bf16 v[0:3], v[200:203], v[220:223], v[0:3]
	v_mfma_f32_16x16x32_bf16 v[28:31], v[178:181], v[216:219], v[28:31]
	v_mfma_f32_16x16x32_bf16 v[24:27], v[178:181], v[224:227], v[24:27]
	v_mfma_f32_16x16x32_bf16 v[20:23], v[186:189], v[216:219], v[20:23]
	v_mfma_f32_16x16x32_bf16 v[16:19], v[186:189], v[224:227], v[16:19]
	v_mfma_f32_16x16x32_bf16 v[12:15], v[196:199], v[216:219], v[12:15]
	v_mfma_f32_16x16x32_bf16 v[8:11], v[196:199], v[224:227], v[8:11]
	v_mfma_f32_16x16x32_bf16 v[4:7], v[208:211], v[216:219], v[4:7]
	v_mfma_f32_16x16x32_bf16 v[0:3], v[208:211], v[224:227], v[0:3]
	s_barrier
	s_setprio 0
	s_cmp_lt_u32 s56, 28
	s_cbranch_scc1 .LBB0_1378
	s_add_u32 s6, s64, s6
	s_addc_u32 s7, s65, s7
	v_lshl_add_u64 v[136:137], s[6:7], 0, v[156:157]
	v_readfirstlane_b32 s6, v151
	s_mov_b32 m0, s6
	s_add_u32 s6, s64, s42
	v_lshl_add_u64 v[136:137], v[136:137], 0, s[38:39]
	s_addc_u32 s7, s65, s43
	ds_read_b128 v[128:131], v153
	ds_read_b128 v[132:135], v153 offset:1024
	ds_read_b128 v[140:143], v153 offset:2048
	ds_read_b128 v[158:161], v153 offset:3072
	ds_read_b128 v[162:165], v147
	ds_read_b128 v[166:169], v147 offset:1024
	ds_read_b128 v[170:173], v146
	ds_read_b128 v[174:177], v146 offset:1024
	ds_read_b128 v[178:181], v145
	ds_read_b128 v[182:185], v145 offset:1024
	ds_read_b128 v[186:189], v144
	ds_read_b128 v[190:193], v144 offset:1024
	global_load_lds_dwordx4 v[136:137], off
	v_lshl_add_u64 v[136:137], s[6:7], 0, v[156:157]
	v_readfirstlane_b32 s6, v150
	v_lshl_add_u64 v[136:137], v[136:137], 0, s[38:39]
	s_mov_b32 m0, s6
	s_nop 0
	global_load_lds_dwordx4 v[136:137], off
	s_setprio 1
	s_barrier
	s_waitcnt lgkmcnt(0)
	v_mfma_f32_16x16x32_bf16 v[124:127], v[162:165], v[128:131], v[124:127]
	v_mfma_f32_16x16x32_bf16 v[120:123], v[162:165], v[140:143], v[120:123]
	v_mfma_f32_16x16x32_bf16 v[116:119], v[170:173], v[128:131], v[116:119]
	v_mfma_f32_16x16x32_bf16 v[124:127], v[166:169], v[132:135], v[124:127]
	v_mfma_f32_16x16x32_bf16 v[120:123], v[166:169], v[158:161], v[120:123]
	v_mfma_f32_16x16x32_bf16 v[116:119], v[174:177], v[132:135], v[116:119]
	v_mfma_f32_16x16x32_bf16 v[112:115], v[170:173], v[140:143], v[112:115]
	v_mfma_f32_16x16x32_bf16 v[108:111], v[178:181], v[128:131], v[108:111]
	v_mfma_f32_16x16x32_bf16 v[104:107], v[178:181], v[140:143], v[104:107]
	v_mfma_f32_16x16x32_bf16 v[100:103], v[186:189], v[128:131], v[100:103]
	v_mfma_f32_16x16x32_bf16 v[96:99], v[186:189], v[140:143], v[96:99]
	v_mfma_f32_16x16x32_bf16 v[112:115], v[174:177], v[158:161], v[112:115]
	v_mfma_f32_16x16x32_bf16 v[108:111], v[182:185], v[132:135], v[108:111]
	v_mfma_f32_16x16x32_bf16 v[104:107], v[182:185], v[158:161], v[104:107]
	v_mfma_f32_16x16x32_bf16 v[100:103], v[190:193], v[132:135], v[100:103]
	v_mfma_f32_16x16x32_bf16 v[96:99], v[190:193], v[158:161], v[96:99]
	s_barrier
	s_setprio 0
	ds_read_b128 v[196:199], v149
	ds_read_b128 v[200:203], v149 offset:1024
	ds_read_b128 v[208:211], v149 offset:2048
	ds_read_b128 v[148:151], v149 offset:3072
	s_setprio 1
	s_barrier
	s_waitcnt lgkmcnt(0)
	v_mfma_f32_16x16x32_bf16 v[92:95], v[162:165], v[196:199], v[92:95]
	v_mfma_f32_16x16x32_bf16 v[88:91], v[162:165], v[208:211], v[88:91]
	v_mfma_f32_16x16x32_bf16 v[84:87], v[170:173], v[196:199], v[84:87]
	v_mfma_f32_16x16x32_bf16 v[76:79], v[178:181], v[196:199], v[76:79]
	v_mfma_f32_16x16x32_bf16 v[92:95], v[166:169], v[200:203], v[92:95]
	v_mfma_f32_16x16x32_bf16 v[88:91], v[166:169], v[148:151], v[88:91]
	v_mfma_f32_16x16x32_bf16 v[84:87], v[174:177], v[200:203], v[84:87]
	v_mfma_f32_16x16x32_bf16 v[80:83], v[170:173], v[208:211], v[80:83]
	v_mfma_f32_16x16x32_bf16 v[76:79], v[182:185], v[200:203], v[76:79]
	v_mfma_f32_16x16x32_bf16 v[72:75], v[178:181], v[208:211], v[72:75]
	v_mfma_f32_16x16x32_bf16 v[68:71], v[186:189], v[196:199], v[68:71]
	v_mfma_f32_16x16x32_bf16 v[64:67], v[186:189], v[208:211], v[64:67]
	v_mfma_f32_16x16x32_bf16 v[162:165], v[174:177], v[148:151], v[80:83]
	v_mfma_f32_16x16x32_bf16 v[166:169], v[182:185], v[148:151], v[72:75]
	v_mfma_f32_16x16x32_bf16 v[170:173], v[190:193], v[200:203], v[68:71]
	v_mfma_f32_16x16x32_bf16 v[174:177], v[190:193], v[148:151], v[64:67]
	s_barrier
; #define WAIT_V(n) asm volatile("s_waitcnt vmcnt(" #n ")" ::: "memory")
; #define WAIT_L(n) asm volatile("s_waitcnt lgkmcnt(" #n ")" ::: "memory")
; #define BAR __builtin_amdgcn_s_barrier()
; template <int EPI>
; __device__ __forceinline__ void gemm_tile(const Params& p, const bf16* __restrict__ A, const bf16* __restrict__ Bt, const int K,
;                                           const int nt, const int brow, const int bcol, int pm, int pn) {
;     ...
;     LDA(At, 0, 1); WAIT_V(4); BAR; WAIT_L(0); MMA(1, 0, At, B0); MMA(1, 1, At, B1); BAR; }
;   { LDB(B0, 1, 0); LDA(At, 1, 0); WAIT_V(2); BAR; WAIT_L(0); MMA(0, 0, At, B0); BAR;
	s_setprio 0
	s_nop 1
	ds_read_b128 v[64:67], v147 offset:16384
	ds_read_b128 v[68:71], v147 offset:17408
	ds_read_b128 v[72:75], v146 offset:16384
	ds_read_b128 v[80:83], v146 offset:17408
	ds_read_b128 v[178:181], v145 offset:16384
	ds_read_b128 v[182:185], v145 offset:17408
	ds_read_b128 v[186:189], v144 offset:16384
	ds_read_b128 v[190:193], v144 offset:17408
	s_waitcnt vmcnt(4)
	s_setprio 1
	s_barrier
	s_waitcnt lgkmcnt(0)
	v_mfma_f32_16x16x32_bf16 v[60:63], v[64:67], v[128:131], v[60:63]
	v_mfma_f32_16x16x32_bf16 v[56:59], v[64:67], v[140:143], v[56:59]
	v_mfma_f32_16x16x32_bf16 v[52:55], v[72:75], v[128:131], v[52:55]
	v_mfma_f32_16x16x32_bf16 v[44:47], v[178:181], v[128:131], v[44:47]
	v_mfma_f32_16x16x32_bf16 v[60:63], v[68:71], v[132:135], v[60:63]
	v_mfma_f32_16x16x32_bf16 v[56:59], v[68:71], v[158:161], v[56:59]
	v_mfma_f32_16x16x32_bf16 v[52:55], v[80:83], v[132:135], v[52:55]
	v_mfma_f32_16x16x32_bf16 v[48:51], v[72:75], v[140:143], v[48:51]
	v_mfma_f32_16x16x32_bf16 v[44:47], v[182:185], v[132:135], v[44:47]
	v_mfma_f32_16x16x32_bf16 v[40:43], v[178:181], v[140:143], v[40:43]
	v_mfma_f32_16x16x32_bf16 v[36:39], v[186:189], v[128:131], v[36:39]
	v_mfma_f32_16x16x32_bf16 v[32:35], v[186:189], v[140:143], v[32:35]
	v_mfma_f32_16x16x32_bf16 v[212:215], v[80:83], v[158:161], v[48:51]
	v_mfma_f32_16x16x32_bf16 v[216:219], v[182:185], v[158:161], v[40:43]
	v_mfma_f32_16x16x32_bf16 v[220:223], v[190:193], v[132:135], v[36:39]
	v_mfma_f32_16x16x32_bf16 v[158:161], v[190:193], v[158:161], v[32:35]
	s_setprio 0
	s_setprio 1
	v_mfma_f32_16x16x32_bf16 v[28:31], v[64:67], v[196:199], v[28:31]
	v_mfma_f32_16x16x32_bf16 v[24:27], v[64:67], v[208:211], v[24:27]
	v_mfma_f32_16x16x32_bf16 v[20:23], v[72:75], v[196:199], v[20:23]
	v_mfma_f32_16x16x32_bf16 v[12:15], v[178:181], v[196:199], v[12:15]
	v_mfma_f32_16x16x32_bf16 v[28:31], v[68:71], v[200:203], v[28:31]
	v_mfma_f32_16x16x32_bf16 v[24:27], v[68:71], v[148:151], v[24:27]
	v_mfma_f32_16x16x32_bf16 v[20:23], v[80:83], v[200:203], v[20:23]
	v_mfma_f32_16x16x32_bf16 v[16:19], v[72:75], v[208:211], v[16:19]
	v_mfma_f32_16x16x32_bf16 v[12:15], v[182:185], v[200:203], v[12:15]
	v_mfma_f32_16x16x32_bf16 v[8:11], v[178:181], v[208:211], v[8:11]
	v_mfma_f32_16x16x32_bf16 v[4:7], v[186:189], v[196:199], v[4:7]
	v_mfma_f32_16x16x32_bf16 v[0:3], v[186:189], v[208:211], v[0:3]
	v_mfma_f32_16x16x32_bf16 v[224:227], v[80:83], v[148:151], v[16:19]
	v_mfma_f32_16x16x32_bf16 v[178:181], v[182:185], v[148:151], v[8:11]
	v_mfma_f32_16x16x32_bf16 v[182:185], v[190:193], v[200:203], v[4:7]
	v_mfma_f32_16x16x32_bf16 v[186:189], v[190:193], v[148:151], v[0:3]
	s_barrier
	s_setprio 0
	s_nop 1
	ds_read_b128 v[0:3], v138
	ds_read_b128 v[4:7], v138 offset:1024
	ds_read_b128 v[8:11], v138 offset:2048
	ds_read_b128 v[16:19], v138 offset:3072
	ds_read_b128 v[32:35], v147 offset:32768
	ds_read_b128 v[36:39], v147 offset:33792
	ds_read_b128 v[40:43], v146 offset:32768
	ds_read_b128 v[48:51], v146 offset:33792
	ds_read_b128 v[190:193], v145 offset:32768
	ds_read_b128 v[196:199], v145 offset:33792
	ds_read_b128 v[200:203], v144 offset:32768
	ds_read_b128 v[208:211], v144 offset:33792
	s_waitcnt vmcnt(2)
	s_setprio 1
	s_barrier
	s_waitcnt lgkmcnt(0)
	v_mfma_f32_16x16x32_bf16 v[64:67], v[32:35], v[0:3], v[124:127]
	v_mfma_f32_16x16x32_bf16 v[136:139], v[36:39], v[4:7], v[64:67]
	v_mfma_f32_16x16x32_bf16 v[64:67], v[32:35], v[8:11], v[120:123]
	v_mfma_f32_16x16x32_bf16 v[148:151], v[36:39], v[16:19], v[64:67]
	v_mfma_f32_16x16x32_bf16 v[64:67], v[40:43], v[0:3], v[116:119]
	v_mfma_f32_16x16x32_bf16 v[132:135], v[48:51], v[4:7], v[64:67]
	v_mfma_f32_16x16x32_bf16 v[64:67], v[40:43], v[8:11], v[112:115]
	v_mfma_f32_16x16x32_bf16 v[140:143], v[48:51], v[16:19], v[64:67]
	v_mfma_f32_16x16x32_bf16 v[64:67], v[190:193], v[0:3], v[108:111]
	v_mfma_f32_16x16x32_bf16 v[124:127], v[196:199], v[4:7], v[64:67]
	v_mfma_f32_16x16x32_bf16 v[64:67], v[190:193], v[8:11], v[104:107]
	v_mfma_f32_16x16x32_bf16 v[128:131], v[196:199], v[16:19], v[64:67]
	v_mfma_f32_16x16x32_bf16 v[64:67], v[200:203], v[0:3], v[100:103]
	v_mfma_f32_16x16x32_bf16 v[116:119], v[208:211], v[4:7], v[64:67]
	v_mfma_f32_16x16x32_bf16 v[64:67], v[200:203], v[8:11], v[96:99]
	v_mfma_f32_16x16x32_bf16 v[120:123], v[208:211], v[16:19], v[64:67]
	s_barrier
; #define WAIT_V(n) asm volatile("s_waitcnt vmcnt(" #n ")" ::: "memory")
; #define WAIT_L(n) asm volatile("s_waitcnt lgkmcnt(" #n ")" ::: "memory")
; #define BAR __builtin_amdgcn_s_barrier()
; template <int EPI>
; __device__ __forceinline__ void gemm_tile(const Params& p, const bf16* __restrict__ A, const bf16* __restrict__ Bt, const int K,
;                                           const int nt, const int brow, const int bcol, int pm, int pn) {
;     ...
;     LDB(B1, 1, 1); WAIT_V(0); BAR; WAIT_L(0); MMA(0, 1, At, B1); BAR;
;     LDA(At, 1, 1); BAR; WAIT_L(0); MMA(1, 0, At, B0); MMA(1, 1, At, B1); BAR; }
;   if (wr == 0) BAR;
	s_setprio 0
	ds_read_b128 v[96:99], v152
	ds_read_b128 v[100:103], v152 offset:1024
	ds_read_b128 v[104:107], v152 offset:2048
	ds_read_b128 v[108:111], v152 offset:3072
	s_waitcnt vmcnt(0)
	s_setprio 1
	s_barrier
	s_waitcnt lgkmcnt(0)
	v_mfma_f32_16x16x32_bf16 v[64:67], v[32:35], v[96:99], v[92:95]
	v_mfma_f32_16x16x32_bf16 v[32:35], v[32:35], v[104:107], v[88:91]
	v_mfma_f32_16x16x32_bf16 v[80:83], v[36:39], v[108:111], v[32:35]
	v_mfma_f32_16x16x32_bf16 v[32:35], v[40:43], v[96:99], v[84:87]
	v_mfma_f32_16x16x32_bf16 v[68:71], v[48:51], v[100:103], v[32:35]
	v_mfma_f32_16x16x32_bf16 v[32:35], v[40:43], v[104:107], v[162:165]
	v_mfma_f32_16x16x32_bf16 v[84:87], v[48:51], v[108:111], v[32:35]
	v_mfma_f32_16x16x32_bf16 v[32:35], v[190:193], v[96:99], v[76:79]
	v_mfma_f32_16x16x32_bf16 v[72:75], v[196:199], v[100:103], v[32:35]
	v_mfma_f32_16x16x32_bf16 v[32:35], v[190:193], v[104:107], v[166:169]
	v_mfma_f32_16x16x32_bf16 v[88:91], v[196:199], v[108:111], v[32:35]
	v_mfma_f32_16x16x32_bf16 v[32:35], v[200:203], v[96:99], v[170:173]
	v_mfma_f32_16x16x32_bf16 v[76:79], v[208:211], v[100:103], v[32:35]
	v_mfma_f32_16x16x32_bf16 v[32:35], v[200:203], v[104:107], v[174:177]
	v_mfma_f32_16x16x32_bf16 v[64:67], v[36:39], v[100:103], v[64:67]
	v_mfma_f32_16x16x32_bf16 v[92:95], v[208:211], v[108:111], v[32:35]
	s_barrier
	s_setprio 0
	ds_read_b128 v[112:115], v147 offset:49152
	ds_read_b128 v[152:155], v147 offset:50176
	ds_read_b128 v[162:165], v146 offset:49152
	ds_read_b128 v[166:169], v146 offset:50176
	ds_read_b128 v[170:173], v145 offset:49152
	ds_read_b128 v[174:177], v145 offset:50176
	ds_read_b128 v[190:193], v144 offset:49152
	ds_read_b128 v[144:147], v144 offset:50176
	s_setprio 1
	s_barrier
	s_waitcnt lgkmcnt(0)
	v_mfma_f32_16x16x32_bf16 v[36:39], v[112:115], v[8:11], v[56:59]
	v_mfma_f32_16x16x32_bf16 v[40:43], v[162:165], v[8:11], v[212:215]
	v_mfma_f32_16x16x32_bf16 v[32:35], v[112:115], v[0:3], v[60:63]
	v_mfma_f32_16x16x32_bf16 v[48:51], v[152:155], v[16:19], v[36:39]
	v_mfma_f32_16x16x32_bf16 v[36:39], v[162:165], v[0:3], v[52:55]
	v_mfma_f32_16x16x32_bf16 v[52:55], v[166:169], v[16:19], v[40:43]
	v_mfma_f32_16x16x32_bf16 v[40:43], v[170:173], v[0:3], v[44:47]
	v_mfma_f32_16x16x32_bf16 v[44:47], v[170:173], v[8:11], v[216:219]
	v_mfma_f32_16x16x32_bf16 v[0:3], v[190:193], v[0:3], v[220:223]
	v_mfma_f32_16x16x32_bf16 v[56:59], v[174:177], v[16:19], v[44:47]
	v_mfma_f32_16x16x32_bf16 v[44:47], v[144:147], v[4:7], v[0:3]
	v_mfma_f32_16x16x32_bf16 v[0:3], v[190:193], v[8:11], v[158:161]
	v_mfma_f32_16x16x32_bf16 v[32:35], v[152:155], v[4:7], v[32:35]
	v_mfma_f32_16x16x32_bf16 v[36:39], v[166:169], v[4:7], v[36:39]
	v_mfma_f32_16x16x32_bf16 v[40:43], v[174:177], v[4:7], v[40:43]
	v_mfma_f32_16x16x32_bf16 v[60:63], v[144:147], v[16:19], v[0:3]
	s_setprio 0
	s_setprio 1
	v_mfma_f32_16x16x32_bf16 v[4:7], v[112:115], v[104:107], v[24:27]
	v_mfma_f32_16x16x32_bf16 v[8:11], v[162:165], v[104:107], v[224:227]
	v_mfma_f32_16x16x32_bf16 v[16:19], v[152:155], v[108:111], v[4:7]
	v_mfma_f32_16x16x32_bf16 v[4:7], v[162:165], v[96:99], v[20:23]
	v_mfma_f32_16x16x32_bf16 v[20:23], v[166:169], v[108:111], v[8:11]
	v_mfma_f32_16x16x32_bf16 v[8:11], v[170:173], v[96:99], v[12:15]
	v_mfma_f32_16x16x32_bf16 v[12:15], v[170:173], v[104:107], v[178:181]
	v_mfma_f32_16x16x32_bf16 v[0:3], v[112:115], v[96:99], v[28:31]
	v_mfma_f32_16x16x32_bf16 v[24:27], v[174:177], v[108:111], v[12:15]
	v_mfma_f32_16x16x32_bf16 v[12:15], v[190:193], v[96:99], v[182:185]
	v_mfma_f32_16x16x32_bf16 v[28:31], v[190:193], v[104:107], v[186:189]
	v_mfma_f32_16x16x32_bf16 v[0:3], v[152:155], v[100:103], v[0:3]
	v_mfma_f32_16x16x32_bf16 v[4:7], v[166:169], v[100:103], v[4:7]
	v_mfma_f32_16x16x32_bf16 v[8:11], v[174:177], v[100:103], v[8:11]
	v_mfma_f32_16x16x32_bf16 v[12:15], v[144:147], v[100:103], v[12:15]
	v_mfma_f32_16x16x32_bf16 v[28:31], v[144:147], v[108:111], v[28:31]
	s_barrier
	s_setprio 0
	s_cmpk_gt_u32 s89, 0xff
	s_cbranch_scc1 .LBB0_1381
	s_barrier

; #define WAIT_L(n) asm volatile("s_waitcnt lgkmcnt(" #n ")" ::: "memory")
; #define BAR __builtin_amdgcn_s_barrier()
; #define SCHED __builtin_amdgcn_sched_barrier(0)
; template <int EPI>
; __device__ __forceinline__ void gemm_tile(const Params& p, const bf16* __restrict__ A, const bf16* __restrict__ Bt, const int K,
;                                           const int nt, const int brow, const int bcol, int pm, int pn) {
;     ...
;     LDB(B0, 0, 0); SCHED; LDA(At, 0, 0); STAGE(SA(1, 1), A, brow + HALF, t + 1);
;     WAIT_L(8); BAR; WAIT_L(0); MMA(0, 0, At, B0); BAR; SCHED;
;     LDB(B1, 0, 1); STAGE(SB(0, 0), Bt, bcol, t + 2);
;     BAR; WAIT_L(0); MMA(0, 1, At, B1); BAR;
;     LDA(At, 0, 1); STAGE(SA(0, 0), A, brow, t + 2);
;     BAR; WAIT_L(0); MMA(1, 0, At, B0); BAR; SCHED;
.LBB0_1562:
	ds_read_b128 v[162:165], v154
	ds_read_b128 v[166:169], v154 offset:1024
	ds_read_b128 v[170:173], v154 offset:2048
	ds_read_b128 v[174:177], v154 offset:3072
	v_lshl_add_u64 v[204:205], s[42:43], 0, v[128:129]
	v_readfirstlane_b32 s57, v159
	v_lshl_add_u64 v[216:217], v[204:205], 0, s[20:21]
	s_mov_b32 m0, s57
	v_lshl_add_u64 v[232:233], s[48:49], 0, v[128:129]
	v_readfirstlane_b32 s57, v158
	ds_read_b128 v[178:181], v141
	ds_read_b128 v[182:185], v141 offset:1024
	ds_read_b128 v[186:189], v155
	ds_read_b128 v[190:193], v155 offset:1024
	ds_read_b128 v[196:199], v156
	ds_read_b128 v[200:203], v156 offset:1024
	ds_read_b128 v[208:211], v157
	ds_read_b128 v[212:215], v157 offset:1024
	global_load_lds_dwordx4 v[216:217], off
	v_lshl_add_u64 v[216:217], v[232:233], 0, s[20:21]
	s_mov_b32 m0, s57
	s_nop 0
	global_load_lds_dwordx4 v[216:217], off
	s_waitcnt lgkmcnt(8)
	s_setprio 1
	s_barrier
	s_waitcnt lgkmcnt(0)
	v_mfma_f32_16x16x32_bf16 v[124:127], v[178:181], v[162:165], v[124:127]
	v_mfma_f32_16x16x32_bf16 v[120:123], v[178:181], v[170:173], v[120:123]
	v_mfma_f32_16x16x32_bf16 v[116:119], v[186:189], v[162:165], v[116:119]
	v_mfma_f32_16x16x32_bf16 v[112:115], v[186:189], v[170:173], v[112:115]
	v_mfma_f32_16x16x32_bf16 v[108:111], v[196:199], v[162:165], v[108:111]
	v_mfma_f32_16x16x32_bf16 v[104:107], v[196:199], v[170:173], v[104:107]
	v_mfma_f32_16x16x32_bf16 v[100:103], v[208:211], v[162:165], v[100:103]
	v_mfma_f32_16x16x32_bf16 v[96:99], v[208:211], v[170:173], v[96:99]
	v_mfma_f32_16x16x32_bf16 v[124:127], v[182:185], v[166:169], v[124:127]
	v_mfma_f32_16x16x32_bf16 v[120:123], v[182:185], v[174:177], v[120:123]
	v_mfma_f32_16x16x32_bf16 v[116:119], v[190:193], v[166:169], v[116:119]
	v_mfma_f32_16x16x32_bf16 v[112:115], v[190:193], v[174:177], v[112:115]
	v_mfma_f32_16x16x32_bf16 v[108:111], v[200:203], v[166:169], v[108:111]
	v_mfma_f32_16x16x32_bf16 v[104:107], v[200:203], v[174:177], v[104:107]
	v_mfma_f32_16x16x32_bf16 v[100:103], v[212:215], v[166:169], v[100:103]
	v_mfma_f32_16x16x32_bf16 v[96:99], v[212:215], v[174:177], v[96:99]
	s_barrier
	s_setprio 0
	v_lshl_add_u64 v[234:235], s[54:55], 0, v[128:129]
	s_mov_b64 s[84:85], 0x2000100
	v_readfirstlane_b32 s57, v130
	v_lshl_add_u64 v[236:237], v[234:235], 0, s[84:85]
	s_mov_b32 m0, s57
	s_mov_b64 s[84:85], 0x2040100
	v_readfirstlane_b32 s57, v131
	ds_read_b128 v[216:219], v152
	ds_read_b128 v[220:223], v152 offset:1024
	ds_read_b128 v[224:227], v152 offset:2048
	ds_read_b128 v[228:231], v152 offset:3072
	global_load_lds_dwordx4 v[236:237], off
	v_lshl_add_u64 v[236:237], v[234:235], 0, s[84:85]
	s_mov_b32 m0, s57
	s_nop 0
	global_load_lds_dwordx4 v[236:237], off
	s_setprio 1
	s_barrier
	s_waitcnt lgkmcnt(0)
	v_mfma_f32_16x16x32_bf16 v[92:95], v[178:181], v[216:219], v[92:95]
	v_mfma_f32_16x16x32_bf16 v[88:91], v[178:181], v[224:227], v[88:91]
	v_mfma_f32_16x16x32_bf16 v[84:87], v[186:189], v[216:219], v[84:87]
	v_mfma_f32_16x16x32_bf16 v[80:83], v[186:189], v[224:227], v[80:83]
	v_mfma_f32_16x16x32_bf16 v[76:79], v[196:199], v[216:219], v[76:79]
	v_mfma_f32_16x16x32_bf16 v[72:75], v[196:199], v[224:227], v[72:75]
	v_mfma_f32_16x16x32_bf16 v[68:71], v[208:211], v[216:219], v[68:71]
	v_mfma_f32_16x16x32_bf16 v[64:67], v[208:211], v[224:227], v[64:67]
	v_mfma_f32_16x16x32_bf16 v[92:95], v[182:185], v[220:223], v[92:95]
	v_mfma_f32_16x16x32_bf16 v[88:91], v[182:185], v[228:231], v[88:91]
	v_mfma_f32_16x16x32_bf16 v[84:87], v[190:193], v[220:223], v[84:87]
	v_mfma_f32_16x16x32_bf16 v[80:83], v[190:193], v[228:231], v[80:83]
	v_mfma_f32_16x16x32_bf16 v[76:79], v[200:203], v[220:223], v[76:79]
	v_mfma_f32_16x16x32_bf16 v[72:75], v[200:203], v[228:231], v[72:75]
	v_mfma_f32_16x16x32_bf16 v[68:71], v[212:215], v[220:223], v[68:71]
	v_mfma_f32_16x16x32_bf16 v[64:67], v[212:215], v[228:231], v[64:67]
	s_barrier
	s_setprio 0
	v_lshl_add_u64 v[236:237], s[50:51], 0, v[128:129]
	v_readfirstlane_b32 s57, v132
	v_lshl_add_u64 v[238:239], v[236:237], 0, s[22:23]
	s_mov_b32 m0, s57
	ds_read_b128 v[178:181], v141 offset:16384
	ds_read_b128 v[182:185], v141 offset:17408
	ds_read_b128 v[186:189], v155 offset:16384
	ds_read_b128 v[190:193], v155 offset:17408
	ds_read_b128 v[196:199], v156 offset:16384
	ds_read_b128 v[200:203], v156 offset:17408
	ds_read_b128 v[208:211], v157 offset:16384
	ds_read_b128 v[212:215], v157 offset:17408
	global_load_lds_dwordx4 v[238:239], off
	v_lshl_add_u64 v[238:239], s[52:53], 0, v[128:129]
	v_readfirstlane_b32 s57, v133
	v_lshl_add_u64 v[240:241], v[238:239], 0, s[22:23]
	s_mov_b32 m0, s57
	s_nop 0
	global_load_lds_dwordx4 v[240:241], off
	s_setprio 1
	s_barrier
	s_waitcnt lgkmcnt(0)
	v_mfma_f32_16x16x32_bf16 v[60:63], v[178:181], v[162:165], v[60:63]
	v_mfma_f32_16x16x32_bf16 v[56:59], v[178:181], v[170:173], v[56:59]
	v_mfma_f32_16x16x32_bf16 v[52:55], v[186:189], v[162:165], v[52:55]
	v_mfma_f32_16x16x32_bf16 v[48:51], v[186:189], v[170:173], v[48:51]
	v_mfma_f32_16x16x32_bf16 v[44:47], v[196:199], v[162:165], v[44:47]
	v_mfma_f32_16x16x32_bf16 v[40:43], v[196:199], v[170:173], v[40:43]
	v_mfma_f32_16x16x32_bf16 v[36:39], v[208:211], v[162:165], v[36:39]
	v_mfma_f32_16x16x32_bf16 v[32:35], v[208:211], v[170:173], v[32:35]
	v_mfma_f32_16x16x32_bf16 v[60:63], v[182:185], v[166:169], v[60:63]
	v_mfma_f32_16x16x32_bf16 v[56:59], v[182:185], v[174:177], v[56:59]
	v_mfma_f32_16x16x32_bf16 v[52:55], v[190:193], v[166:169], v[52:55]
	v_mfma_f32_16x16x32_bf16 v[48:51], v[190:193], v[174:177], v[48:51]
	v_mfma_f32_16x16x32_bf16 v[44:47], v[200:203], v[166:169], v[44:47]
	v_mfma_f32_16x16x32_bf16 v[40:43], v[200:203], v[174:177], v[40:43]
	v_mfma_f32_16x16x32_bf16 v[36:39], v[212:215], v[166:169], v[36:39]
	v_mfma_f32_16x16x32_bf16 v[32:35], v[212:215], v[174:177], v[32:35]
	s_barrier
; #define WAIT_V(n) asm volatile("s_waitcnt vmcnt(" #n ")" ::: "memory")
; #define WAIT_L(n) asm volatile("s_waitcnt lgkmcnt(" #n ")" ::: "memory")
; #define BAR __builtin_amdgcn_s_barrier()
; #define SCHED __builtin_amdgcn_sched_barrier(0)
; template <int EPI>
; __device__ __forceinline__ void gemm_tile(const Params& p, const bf16* __restrict__ A, const bf16* __restrict__ Bt, const int K,
;                                           const int nt, const int brow, const int bcol, int pm, int pn) {
;     ...
;     STAGE(SB(0, 1), Bt, bcol + HALF, t + 2);
;     WAIT_V(6); BAR; MMA(1, 1, At, B1); BAR;
;     LDB(B0, 1, 0); SCHED; LDA(At, 1, 0); STAGE(SA(0, 1), A, brow + HALF, t + 2);
;     WAIT_L(8); BAR; WAIT_L(0); MMA(0, 0, At, B0); BAR; SCHED;
;     LDB(B1, 1, 1); STAGE(SB(1, 0), Bt, bcol, t + 3);
;     BAR; WAIT_L(0); MMA(0, 1, At, B1); BAR;
;     LDA(At, 1, 1); STAGE(SA(1, 0), A, brow, t + 3);
	s_setprio 0
	s_add_i32 s56, s56, 2
	s_add_u32 s42, s42, 0x100
	s_addc_u32 s43, s43, 0
	s_add_u32 s48, s48, 0x100
	s_addc_u32 s49, s49, 0
	s_add_u32 s50, s50, 0x100
	s_addc_u32 s51, s51, 0
	s_add_u32 s52, s52, 0x100
	s_addc_u32 s53, s53, 0
	s_add_u32 s54, s54, 0x100
	s_addc_u32 s55, s55, 0
	s_mov_b64 s[84:85], 0x2080100
	v_readfirstlane_b32 s57, v134
	v_lshl_add_u64 v[162:163], v[234:235], 0, s[84:85]
	s_mov_b32 m0, s57
	s_mov_b64 s[84:85], 0x20c0100
	v_readfirstlane_b32 s57, v135
	global_load_lds_dwordx4 v[162:163], off
	v_lshl_add_u64 v[162:163], v[234:235], 0, s[84:85]
	s_mov_b32 m0, s57
	s_nop 0
	global_load_lds_dwordx4 v[162:163], off
	s_waitcnt vmcnt(6)
	s_setprio 1
	s_barrier
	v_mfma_f32_16x16x32_bf16 v[28:31], v[178:181], v[216:219], v[28:31]
	v_mfma_f32_16x16x32_bf16 v[24:27], v[178:181], v[224:227], v[24:27]
	v_mfma_f32_16x16x32_bf16 v[20:23], v[186:189], v[216:219], v[20:23]
	v_mfma_f32_16x16x32_bf16 v[16:19], v[186:189], v[224:227], v[16:19]
	v_mfma_f32_16x16x32_bf16 v[12:15], v[196:199], v[216:219], v[12:15]
	v_mfma_f32_16x16x32_bf16 v[8:11], v[196:199], v[224:227], v[8:11]
	v_mfma_f32_16x16x32_bf16 v[4:7], v[208:211], v[216:219], v[4:7]
	v_mfma_f32_16x16x32_bf16 v[0:3], v[208:211], v[224:227], v[0:3]
	v_mfma_f32_16x16x32_bf16 v[28:31], v[182:185], v[220:223], v[28:31]
	v_mfma_f32_16x16x32_bf16 v[24:27], v[182:185], v[228:231], v[24:27]
	v_mfma_f32_16x16x32_bf16 v[20:23], v[190:193], v[220:223], v[20:23]
	v_mfma_f32_16x16x32_bf16 v[16:19], v[190:193], v[228:231], v[16:19]
	v_mfma_f32_16x16x32_bf16 v[12:15], v[200:203], v[220:223], v[12:15]
	v_mfma_f32_16x16x32_bf16 v[8:11], v[200:203], v[228:231], v[8:11]
	v_mfma_f32_16x16x32_bf16 v[4:7], v[212:215], v[220:223], v[4:7]
	v_mfma_f32_16x16x32_bf16 v[0:3], v[212:215], v[228:231], v[0:3]
	s_barrier
	s_setprio 0
	ds_read_b128 v[162:165], v145
	ds_read_b128 v[166:169], v145 offset:1024
	ds_read_b128 v[170:173], v145 offset:2048
	ds_read_b128 v[174:177], v145 offset:3072
	v_readfirstlane_b32 s57, v143
	v_lshl_add_u64 v[204:205], v[204:205], 0, s[22:23]
	s_mov_b32 m0, s57
	v_readfirstlane_b32 s57, v144
	ds_read_b128 v[178:181], v141 offset:32768
	ds_read_b128 v[182:185], v141 offset:33792
	ds_read_b128 v[186:189], v155 offset:32768
	ds_read_b128 v[190:193], v155 offset:33792
	ds_read_b128 v[196:199], v156 offset:32768
	ds_read_b128 v[200:203], v156 offset:33792
	ds_read_b128 v[208:211], v157 offset:32768
	ds_read_b128 v[212:215], v157 offset:33792
	global_load_lds_dwordx4 v[204:205], off
	v_lshl_add_u64 v[204:205], v[232:233], 0, s[22:23]
	s_mov_b32 m0, s57
	s_nop 0
	global_load_lds_dwordx4 v[204:205], off
	s_waitcnt lgkmcnt(8)
	s_setprio 1
	s_barrier
	s_waitcnt lgkmcnt(0)
	v_mfma_f32_16x16x32_bf16 v[124:127], v[178:181], v[162:165], v[124:127]
	v_mfma_f32_16x16x32_bf16 v[120:123], v[178:181], v[170:173], v[120:123]
	v_mfma_f32_16x16x32_bf16 v[116:119], v[186:189], v[162:165], v[116:119]
	v_mfma_f32_16x16x32_bf16 v[112:115], v[186:189], v[170:173], v[112:115]
	v_mfma_f32_16x16x32_bf16 v[108:111], v[196:199], v[162:165], v[108:111]
	v_mfma_f32_16x16x32_bf16 v[104:107], v[196:199], v[170:173], v[104:107]
	v_mfma_f32_16x16x32_bf16 v[100:103], v[208:211], v[162:165], v[100:103]
	v_mfma_f32_16x16x32_bf16 v[96:99], v[208:211], v[170:173], v[96:99]
	v_mfma_f32_16x16x32_bf16 v[124:127], v[182:185], v[166:169], v[124:127]
	v_mfma_f32_16x16x32_bf16 v[120:123], v[182:185], v[174:177], v[120:123]
	v_mfma_f32_16x16x32_bf16 v[116:119], v[190:193], v[166:169], v[116:119]
	v_mfma_f32_16x16x32_bf16 v[112:115], v[190:193], v[174:177], v[112:115]
	v_mfma_f32_16x16x32_bf16 v[108:111], v[200:203], v[166:169], v[108:111]
	v_mfma_f32_16x16x32_bf16 v[104:107], v[200:203], v[174:177], v[104:107]
	v_mfma_f32_16x16x32_bf16 v[100:103], v[212:215], v[166:169], v[100:103]
	v_mfma_f32_16x16x32_bf16 v[96:99], v[212:215], v[174:177], v[96:99]
	s_barrier
	s_setprio 0
	s_mov_b64 s[84:85], 0x2000180
	v_readfirstlane_b32 s57, v146
	v_lshl_add_u64 v[204:205], v[234:235], 0, s[84:85]
	s_mov_b32 m0, s57
	s_mov_b64 s[84:85], 0x2040180
	v_readfirstlane_b32 s57, v147
	ds_read_b128 v[216:219], v142
	ds_read_b128 v[220:223], v142 offset:1024
	ds_read_b128 v[224:227], v142 offset:2048
	ds_read_b128 v[228:231], v142 offset:3072
	global_load_lds_dwordx4 v[204:205], off
	v_lshl_add_u64 v[204:205], v[234:235], 0, s[84:85]
	s_mov_b32 m0, s57
	s_nop 0
	global_load_lds_dwordx4 v[204:205], off
	s_setprio 1
	s_barrier
	s_waitcnt lgkmcnt(0)
	v_mfma_f32_16x16x32_bf16 v[92:95], v[178:181], v[216:219], v[92:95]
	v_mfma_f32_16x16x32_bf16 v[88:91], v[178:181], v[224:227], v[88:91]
	v_mfma_f32_16x16x32_bf16 v[84:87], v[186:189], v[216:219], v[84:87]
	v_mfma_f32_16x16x32_bf16 v[80:83], v[186:189], v[224:227], v[80:83]
	v_mfma_f32_16x16x32_bf16 v[76:79], v[196:199], v[216:219], v[76:79]
	v_mfma_f32_16x16x32_bf16 v[72:75], v[196:199], v[224:227], v[72:75]
	v_mfma_f32_16x16x32_bf16 v[68:71], v[208:211], v[216:219], v[68:71]
	v_mfma_f32_16x16x32_bf16 v[64:67], v[208:211], v[224:227], v[64:67]
	v_mfma_f32_16x16x32_bf16 v[92:95], v[182:185], v[220:223], v[92:95]
	v_mfma_f32_16x16x32_bf16 v[88:91], v[182:185], v[228:231], v[88:91]
	v_mfma_f32_16x16x32_bf16 v[84:87], v[190:193], v[220:223], v[84:87]
	v_mfma_f32_16x16x32_bf16 v[80:83], v[190:193], v[228:231], v[80:83]
	v_mfma_f32_16x16x32_bf16 v[76:79], v[200:203], v[220:223], v[76:79]
	v_mfma_f32_16x16x32_bf16 v[72:75], v[200:203], v[228:231], v[72:75]
	v_mfma_f32_16x16x32_bf16 v[68:71], v[212:215], v[220:223], v[68:71]
	v_mfma_f32_16x16x32_bf16 v[64:67], v[212:215], v[228:231], v[64:67]
	s_barrier
; #define WAIT_V(n) asm volatile("s_waitcnt vmcnt(" #n ")" ::: "memory")
; #define WAIT_L(n) asm volatile("s_waitcnt lgkmcnt(" #n ")" ::: "memory")
; #define BAR __builtin_amdgcn_s_barrier()
; #define SCHED __builtin_amdgcn_sched_barrier(0)
; template <int EPI>
; __device__ __forceinline__ void gemm_tile(const Params& p, const bf16* __restrict__ A, const bf16* __restrict__ Bt, const int K,
;                                           const int nt, const int brow, const int bcol, int pm, int pn) {
;     ...
;     LDA(At, 1, 1); STAGE(SA(1, 0), A, brow, t + 3);
;     BAR; WAIT_L(0); MMA(1, 0, At, B0); BAR; SCHED;
;     STAGE(SB(1, 1), Bt, bcol + HALF, t + 3);
;     WAIT_V(6); BAR; MMA(1, 1, At, B1); BAR;
;   }
;   { LDB(B0, 0, 0); LDA(At, 0, 0); STAGE(SA(1, 1), A, brow + HALF, nt - 1);
;     BAR; WAIT_L(0); MMA(0, 0, At, B0); BAR;
;     LDB(B1, 0, 1); BAR; WAIT_L(0); MMA(0, 1, At, B1); BAR;
	s_setprio 0
	v_readfirstlane_b32 s57, v148
	v_lshl_add_u64 v[204:205], v[236:237], 0, s[24:25]
	s_mov_b32 m0, s57
	v_readfirstlane_b32 s57, v149
	ds_read_b128 v[178:181], v141 offset:49152
	ds_read_b128 v[182:185], v141 offset:50176
	ds_read_b128 v[186:189], v155 offset:49152
	ds_read_b128 v[190:193], v155 offset:50176
	ds_read_b128 v[196:199], v156 offset:49152
	ds_read_b128 v[200:203], v156 offset:50176
	ds_read_b128 v[208:211], v157 offset:49152
	ds_read_b128 v[212:215], v157 offset:50176
	global_load_lds_dwordx4 v[204:205], off
	v_lshl_add_u64 v[204:205], v[238:239], 0, s[24:25]
	s_mov_b32 m0, s57
	s_nop 0
	global_load_lds_dwordx4 v[204:205], off
	s_setprio 1
	s_barrier
	s_waitcnt lgkmcnt(0)
	v_mfma_f32_16x16x32_bf16 v[60:63], v[178:181], v[162:165], v[60:63]
	v_mfma_f32_16x16x32_bf16 v[56:59], v[178:181], v[170:173], v[56:59]
	v_mfma_f32_16x16x32_bf16 v[52:55], v[186:189], v[162:165], v[52:55]
	v_mfma_f32_16x16x32_bf16 v[48:51], v[186:189], v[170:173], v[48:51]
	v_mfma_f32_16x16x32_bf16 v[44:47], v[196:199], v[162:165], v[44:47]
	v_mfma_f32_16x16x32_bf16 v[40:43], v[196:199], v[170:173], v[40:43]
	v_mfma_f32_16x16x32_bf16 v[36:39], v[208:211], v[162:165], v[36:39]
	v_mfma_f32_16x16x32_bf16 v[32:35], v[208:211], v[170:173], v[32:35]
	v_mfma_f32_16x16x32_bf16 v[60:63], v[182:185], v[166:169], v[60:63]
	v_mfma_f32_16x16x32_bf16 v[56:59], v[182:185], v[174:177], v[56:59]
	v_mfma_f32_16x16x32_bf16 v[52:55], v[190:193], v[166:169], v[52:55]
	v_mfma_f32_16x16x32_bf16 v[48:51], v[190:193], v[174:177], v[48:51]
	v_mfma_f32_16x16x32_bf16 v[44:47], v[200:203], v[166:169], v[44:47]
	v_mfma_f32_16x16x32_bf16 v[40:43], v[200:203], v[174:177], v[40:43]
	v_mfma_f32_16x16x32_bf16 v[36:39], v[212:215], v[166:169], v[36:39]
	v_mfma_f32_16x16x32_bf16 v[32:35], v[212:215], v[174:177], v[32:35]
	s_barrier
	s_setprio 0
	s_mov_b64 s[84:85], 0x2080180
	v_readfirstlane_b32 s57, v150
	v_lshl_add_u64 v[162:163], v[234:235], 0, s[84:85]
	s_mov_b32 m0, s57
	v_readfirstlane_b32 s57, v151
	global_load_lds_dwordx4 v[162:163], off
	v_lshl_add_u64 v[162:163], v[234:235], 0, s[26:27]
	s_mov_b32 m0, s57
	s_nop 0
	global_load_lds_dwordx4 v[162:163], off
	s_waitcnt vmcnt(6)
	s_setprio 1
	s_barrier
	v_mfma_f32_16x16x32_bf16 v[28:31], v[178:181], v[216:219], v[28:31]
	v_mfma_f32_16x16x32_bf16 v[24:27], v[178:181], v[224:227], v[24:27]
	v_mfma_f32_16x16x32_bf16 v[20:23], v[186:189], v[216:219], v[20:23]
	v_mfma_f32_16x16x32_bf16 v[16:19], v[186:189], v[224:227], v[16:19]
	v_mfma_f32_16x16x32_bf16 v[12:15], v[196:199], v[216:219], v[12:15]
	v_mfma_f32_16x16x32_bf16 v[8:11], v[196:199], v[224:227], v[8:11]
	v_mfma_f32_16x16x32_bf16 v[4:7], v[208:211], v[216:219], v[4:7]
	v_mfma_f32_16x16x32_bf16 v[0:3], v[208:211], v[224:227], v[0:3]
	v_mfma_f32_16x16x32_bf16 v[28:31], v[182:185], v[220:223], v[28:31]
	v_mfma_f32_16x16x32_bf16 v[24:27], v[182:185], v[228:231], v[24:27]
	v_mfma_f32_16x16x32_bf16 v[20:23], v[190:193], v[220:223], v[20:23]
	v_mfma_f32_16x16x32_bf16 v[16:19], v[190:193], v[228:231], v[16:19]
	v_mfma_f32_16x16x32_bf16 v[12:15], v[200:203], v[220:223], v[12:15]
	v_mfma_f32_16x16x32_bf16 v[8:11], v[200:203], v[228:231], v[8:11]
	v_mfma_f32_16x16x32_bf16 v[4:7], v[212:215], v[220:223], v[4:7]
	v_mfma_f32_16x16x32_bf16 v[0:3], v[212:215], v[228:231], v[0:3]
	s_barrier
	s_setprio 0
	s_cmp_lt_u32 s56, 28
	s_cbranch_scc1 .LBB0_1562
	s_add_u32 s4, s60, s4
	s_addc_u32 s5, s61, s5
	v_lshl_add_u64 v[150:151], s[4:5], 0, v[136:137]
	v_readfirstlane_b32 s4, v159
	s_mov_b32 m0, s4
	s_add_u32 s4, s60, s6
	v_lshl_add_u64 v[150:151], v[150:151], 0, s[28:29]
	s_addc_u32 s5, s61, s7
	ds_read_b128 v[128:131], v154
	ds_read_b128 v[132:135], v154 offset:1024
	ds_read_b128 v[146:149], v154 offset:2048
	ds_read_b128 v[162:165], v154 offset:3072
	ds_read_b128 v[166:169], v141
	ds_read_b128 v[170:173], v141 offset:1024
	ds_read_b128 v[174:177], v155
	ds_read_b128 v[178:181], v155 offset:1024
	ds_read_b128 v[182:185], v156
	ds_read_b128 v[186:189], v156 offset:1024
	ds_read_b128 v[190:193], v157
	ds_read_b128 v[196:199], v157 offset:1024
	global_load_lds_dwordx4 v[150:151], off
	v_lshl_add_u64 v[150:151], s[4:5], 0, v[136:137]
	v_readfirstlane_b32 s4, v158
	v_lshl_add_u64 v[150:151], v[150:151], 0, s[28:29]
	s_mov_b32 m0, s4
	s_nop 0
	global_load_lds_dwordx4 v[150:151], off
	s_setprio 1
	s_barrier
	s_waitcnt lgkmcnt(0)
	v_mfma_f32_16x16x32_bf16 v[124:127], v[166:169], v[128:131], v[124:127]
	v_mfma_f32_16x16x32_bf16 v[120:123], v[166:169], v[146:149], v[120:123]
	v_mfma_f32_16x16x32_bf16 v[116:119], v[174:177], v[128:131], v[116:119]
	v_mfma_f32_16x16x32_bf16 v[112:115], v[174:177], v[146:149], v[112:115]
	v_mfma_f32_16x16x32_bf16 v[108:111], v[182:185], v[128:131], v[108:111]
	v_mfma_f32_16x16x32_bf16 v[104:107], v[182:185], v[146:149], v[104:107]
	v_mfma_f32_16x16x32_bf16 v[124:127], v[170:173], v[132:135], v[124:127]
	v_mfma_f32_16x16x32_bf16 v[120:123], v[170:173], v[162:165], v[120:123]
	v_mfma_f32_16x16x32_bf16 v[116:119], v[178:181], v[132:135], v[116:119]
	v_mfma_f32_16x16x32_bf16 v[112:115], v[178:181], v[162:165], v[112:115]
	v_mfma_f32_16x16x32_bf16 v[108:111], v[186:189], v[132:135], v[108:111]
	v_mfma_f32_16x16x32_bf16 v[104:107], v[186:189], v[162:165], v[104:107]
	v_mfma_f32_16x16x32_bf16 v[100:103], v[190:193], v[128:131], v[100:103]
	v_mfma_f32_16x16x32_bf16 v[96:99], v[190:193], v[146:149], v[96:99]
	v_mfma_f32_16x16x32_bf16 v[100:103], v[196:199], v[132:135], v[100:103]
	v_mfma_f32_16x16x32_bf16 v[96:99], v[196:199], v[162:165], v[96:99]
	s_barrier
	s_setprio 0
	ds_read_b128 v[200:203], v152
	ds_read_b128 v[208:211], v152 offset:1024
	ds_read_b128 v[212:215], v152 offset:2048
	ds_read_b128 v[150:153], v152 offset:3072
	s_setprio 1
	s_barrier
; #define WAIT_V(n) asm volatile("s_waitcnt vmcnt(" #n ")" ::: "memory")
; #define WAIT_L(n) asm volatile("s_waitcnt lgkmcnt(" #n ")" ::: "memory")
; #define BAR __builtin_amdgcn_s_barrier()
; template <int EPI>
; __device__ __forceinline__ void gemm_tile(const Params& p, const bf16* __restrict__ A, const bf16* __restrict__ Bt, const int K,
;                                           const int nt, const int brow, const int bcol, int pm, int pn) {
;     ...
;     LDB(B1, 0, 1); BAR; WAIT_L(0); MMA(0, 1, At, B1); BAR;
;     LDA(At, 0, 1); WAIT_V(4); BAR; WAIT_L(0); MMA(1, 0, At, B0); MMA(1, 1, At, B1); BAR; }
;   { LDB(B0, 1, 0); LDA(At, 1, 0); WAIT_V(2); BAR; WAIT_L(0); MMA(0, 0, At, B0); BAR;
	s_waitcnt lgkmcnt(0)
	v_mfma_f32_16x16x32_bf16 v[92:95], v[166:169], v[200:203], v[92:95]
	v_mfma_f32_16x16x32_bf16 v[88:91], v[166:169], v[212:215], v[88:91]
	v_mfma_f32_16x16x32_bf16 v[68:71], v[190:193], v[200:203], v[68:71]
	v_mfma_f32_16x16x32_bf16 v[92:95], v[170:173], v[208:211], v[92:95]
	v_mfma_f32_16x16x32_bf16 v[88:91], v[170:173], v[150:153], v[88:91]
	v_mfma_f32_16x16x32_bf16 v[84:87], v[174:177], v[200:203], v[84:87]
	v_mfma_f32_16x16x32_bf16 v[80:83], v[174:177], v[212:215], v[80:83]
	v_mfma_f32_16x16x32_bf16 v[76:79], v[182:185], v[200:203], v[76:79]
	v_mfma_f32_16x16x32_bf16 v[72:75], v[182:185], v[212:215], v[72:75]
	v_mfma_f32_16x16x32_bf16 v[68:71], v[196:199], v[208:211], v[68:71]
	v_mfma_f32_16x16x32_bf16 v[64:67], v[190:193], v[212:215], v[64:67]
	v_mfma_f32_16x16x32_bf16 v[166:169], v[178:181], v[208:211], v[84:87]
	v_mfma_f32_16x16x32_bf16 v[170:173], v[178:181], v[150:153], v[80:83]
	v_mfma_f32_16x16x32_bf16 v[174:177], v[186:189], v[208:211], v[76:79]
	v_mfma_f32_16x16x32_bf16 v[178:181], v[186:189], v[150:153], v[72:75]
	v_mfma_f32_16x16x32_bf16 v[182:185], v[196:199], v[150:153], v[64:67]
	s_barrier
	s_setprio 0
	s_nop 0
	ds_read_b128 v[64:67], v141 offset:16384
	ds_read_b128 v[72:75], v141 offset:17408
	ds_read_b128 v[76:79], v155 offset:16384
	ds_read_b128 v[80:83], v155 offset:17408
	ds_read_b128 v[84:87], v156 offset:16384
	ds_read_b128 v[186:189], v156 offset:17408
	ds_read_b128 v[190:193], v157 offset:16384
	ds_read_b128 v[196:199], v157 offset:17408
	s_waitcnt vmcnt(4)
	s_setprio 1
	s_barrier
	s_waitcnt lgkmcnt(0)
	v_mfma_f32_16x16x32_bf16 v[60:63], v[64:67], v[128:131], v[60:63]
	v_mfma_f32_16x16x32_bf16 v[52:55], v[76:79], v[128:131], v[52:55]
	v_mfma_f32_16x16x32_bf16 v[44:47], v[84:87], v[128:131], v[44:47]
	v_mfma_f32_16x16x32_bf16 v[36:39], v[190:193], v[128:131], v[36:39]
	v_mfma_f32_16x16x32_bf16 v[32:35], v[190:193], v[146:149], v[32:35]
	v_mfma_f32_16x16x32_bf16 v[60:63], v[72:75], v[132:135], v[60:63]
	v_mfma_f32_16x16x32_bf16 v[56:59], v[64:67], v[146:149], v[56:59]
	v_mfma_f32_16x16x32_bf16 v[52:55], v[80:83], v[132:135], v[52:55]
	v_mfma_f32_16x16x32_bf16 v[48:51], v[76:79], v[146:149], v[48:51]
	v_mfma_f32_16x16x32_bf16 v[44:47], v[186:189], v[132:135], v[44:47]
	v_mfma_f32_16x16x32_bf16 v[40:43], v[84:87], v[146:149], v[40:43]
	v_mfma_f32_16x16x32_bf16 v[36:39], v[196:199], v[132:135], v[36:39]
	v_mfma_f32_16x16x32_bf16 v[32:35], v[196:199], v[162:165], v[32:35]
	v_mfma_f32_16x16x32_bf16 v[216:219], v[72:75], v[162:165], v[56:59]
	v_mfma_f32_16x16x32_bf16 v[220:223], v[80:83], v[162:165], v[48:51]
	v_mfma_f32_16x16x32_bf16 v[224:227], v[186:189], v[162:165], v[40:43]
	s_setprio 0
	s_setprio 1
	v_mfma_f32_16x16x32_bf16 v[28:31], v[64:67], v[200:203], v[28:31]
	v_mfma_f32_16x16x32_bf16 v[24:27], v[64:67], v[212:215], v[24:27]
	v_mfma_f32_16x16x32_bf16 v[20:23], v[76:79], v[200:203], v[20:23]
	v_mfma_f32_16x16x32_bf16 v[16:19], v[76:79], v[212:215], v[16:19]
	v_mfma_f32_16x16x32_bf16 v[4:7], v[190:193], v[200:203], v[4:7]
	v_mfma_f32_16x16x32_bf16 v[28:31], v[72:75], v[208:211], v[28:31]
	v_mfma_f32_16x16x32_bf16 v[24:27], v[72:75], v[150:153], v[24:27]
	v_mfma_f32_16x16x32_bf16 v[20:23], v[80:83], v[208:211], v[20:23]
	v_mfma_f32_16x16x32_bf16 v[16:19], v[80:83], v[150:153], v[16:19]
	v_mfma_f32_16x16x32_bf16 v[12:15], v[84:87], v[200:203], v[12:15]
	v_mfma_f32_16x16x32_bf16 v[8:11], v[84:87], v[212:215], v[8:11]
	v_mfma_f32_16x16x32_bf16 v[4:7], v[196:199], v[208:211], v[4:7]
	v_mfma_f32_16x16x32_bf16 v[0:3], v[190:193], v[212:215], v[0:3]
	v_mfma_f32_16x16x32_bf16 v[146:149], v[186:189], v[208:211], v[12:15]
	v_mfma_f32_16x16x32_bf16 v[162:165], v[186:189], v[150:153], v[8:11]
	v_mfma_f32_16x16x32_bf16 v[150:153], v[196:199], v[150:153], v[0:3]
	s_barrier
	s_setprio 0
	s_nop 2
	ds_read_b128 v[0:3], v145
	ds_read_b128 v[8:11], v145 offset:1024
	ds_read_b128 v[12:15], v145 offset:2048
	ds_read_b128 v[186:189], v145 offset:3072
	ds_read_b128 v[40:43], v141 offset:32768
	ds_read_b128 v[48:51], v141 offset:33792
	ds_read_b128 v[56:59], v155 offset:32768
	ds_read_b128 v[64:67], v155 offset:33792
	ds_read_b128 v[190:193], v156 offset:32768
	ds_read_b128 v[196:199], v156 offset:33792
	ds_read_b128 v[200:203], v157 offset:32768
	ds_read_b128 v[208:211], v157 offset:33792
	s_waitcnt vmcnt(2)
	s_setprio 1
	s_barrier
; #define WAIT_V(n) asm volatile("s_waitcnt vmcnt(" #n ")" ::: "memory")
; #define WAIT_L(n) asm volatile("s_waitcnt lgkmcnt(" #n ")" ::: "memory")
; #define BAR __builtin_amdgcn_s_barrier()
; template <int EPI>
; __device__ __forceinline__ void gemm_tile(const Params& p, const bf16* __restrict__ A, const bf16* __restrict__ Bt, const int K,
;                                           const int nt, const int brow, const int bcol, int pm, int pn) {
;     ...
;     LDB(B1, 1, 1); WAIT_V(0); BAR; WAIT_L(0); MMA(0, 1, At, B1); BAR;
;     LDA(At, 1, 1); BAR; WAIT_L(0); MMA(1, 0, At, B0); MMA(1, 1, At, B1); BAR; }
;   if (wr == 0) BAR;
	s_waitcnt lgkmcnt(0)
	v_mfma_f32_16x16x32_bf16 v[72:75], v[40:43], v[0:3], v[124:127]
	v_mfma_f32_16x16x32_bf16 v[80:83], v[48:51], v[8:11], v[72:75]
	v_mfma_f32_16x16x32_bf16 v[72:75], v[40:43], v[12:15], v[120:123]
	v_mfma_f32_16x16x32_bf16 v[132:135], v[48:51], v[186:189], v[72:75]
	v_mfma_f32_16x16x32_bf16 v[72:75], v[56:59], v[0:3], v[116:119]
	v_mfma_f32_16x16x32_bf16 v[84:87], v[64:67], v[8:11], v[72:75]
	v_mfma_f32_16x16x32_bf16 v[72:75], v[56:59], v[12:15], v[112:115]
	v_mfma_f32_16x16x32_bf16 v[128:131], v[64:67], v[186:189], v[72:75]
	v_mfma_f32_16x16x32_bf16 v[72:75], v[190:193], v[0:3], v[108:111]
	v_mfma_f32_16x16x32_bf16 v[120:123], v[196:199], v[8:11], v[72:75]
	v_mfma_f32_16x16x32_bf16 v[72:75], v[190:193], v[12:15], v[104:107]
	v_mfma_f32_16x16x32_bf16 v[124:127], v[196:199], v[186:189], v[72:75]
	v_mfma_f32_16x16x32_bf16 v[72:75], v[200:203], v[0:3], v[100:103]
	v_mfma_f32_16x16x32_bf16 v[116:119], v[208:211], v[8:11], v[72:75]
	v_mfma_f32_16x16x32_bf16 v[72:75], v[200:203], v[12:15], v[96:99]
	v_mfma_f32_16x16x32_bf16 v[112:115], v[208:211], v[186:189], v[72:75]
	s_barrier
	s_setprio 0
	ds_read_b128 v[96:99], v142
	ds_read_b128 v[100:103], v142 offset:1024
	ds_read_b128 v[212:215], v142 offset:2048
	ds_read_b128 v[142:145], v142 offset:3072
	s_waitcnt vmcnt(0)
	s_setprio 1
	s_barrier
	s_waitcnt lgkmcnt(0)
	v_mfma_f32_16x16x32_bf16 v[72:75], v[40:43], v[96:99], v[92:95]
	v_mfma_f32_16x16x32_bf16 v[40:43], v[40:43], v[212:215], v[88:91]
	v_mfma_f32_16x16x32_bf16 v[108:111], v[48:51], v[142:145], v[40:43]
	v_mfma_f32_16x16x32_bf16 v[40:43], v[56:59], v[96:99], v[166:169]
	v_mfma_f32_16x16x32_bf16 v[76:79], v[64:67], v[100:103], v[40:43]
	v_mfma_f32_16x16x32_bf16 v[40:43], v[56:59], v[212:215], v[170:173]
	v_mfma_f32_16x16x32_bf16 v[104:107], v[64:67], v[142:145], v[40:43]
	v_mfma_f32_16x16x32_bf16 v[40:43], v[190:193], v[96:99], v[174:177]
	v_mfma_f32_16x16x32_bf16 v[92:95], v[196:199], v[100:103], v[40:43]
	v_mfma_f32_16x16x32_bf16 v[40:43], v[190:193], v[212:215], v[178:181]
	v_mfma_f32_16x16x32_bf16 v[64:67], v[196:199], v[142:145], v[40:43]
	v_mfma_f32_16x16x32_bf16 v[40:43], v[200:203], v[96:99], v[68:71]
	v_mfma_f32_16x16x32_bf16 v[88:91], v[208:211], v[100:103], v[40:43]
	v_mfma_f32_16x16x32_bf16 v[40:43], v[200:203], v[212:215], v[182:185]
	v_mfma_f32_16x16x32_bf16 v[72:75], v[48:51], v[100:103], v[72:75]
	v_mfma_f32_16x16x32_bf16 v[68:71], v[208:211], v[142:145], v[40:43]
	s_barrier
	s_setprio 0
	ds_read_b128 v[166:169], v141 offset:49152
	ds_read_b128 v[170:173], v141 offset:50176
	ds_read_b128 v[174:177], v155 offset:49152
	ds_read_b128 v[178:181], v155 offset:50176
	ds_read_b128 v[182:185], v156 offset:49152
	ds_read_b128 v[190:193], v156 offset:50176
	ds_read_b128 v[196:199], v157 offset:49152
	ds_read_b128 v[154:157], v157 offset:50176
	s_setprio 1
	s_barrier
	s_waitcnt lgkmcnt(0)
	v_mfma_f32_16x16x32_bf16 v[40:43], v[166:169], v[0:3], v[60:63]
	v_mfma_f32_16x16x32_bf16 v[56:59], v[170:173], v[8:11], v[40:43]
	v_mfma_f32_16x16x32_bf16 v[40:43], v[166:169], v[12:15], v[216:219]
	v_mfma_f32_16x16x32_bf16 v[60:63], v[170:173], v[186:189], v[40:43]
	v_mfma_f32_16x16x32_bf16 v[40:43], v[174:177], v[0:3], v[52:55]
	v_mfma_f32_16x16x32_bf16 v[48:51], v[178:181], v[8:11], v[40:43]
	v_mfma_f32_16x16x32_bf16 v[40:43], v[174:177], v[12:15], v[220:223]
	v_mfma_f32_16x16x32_bf16 v[52:55], v[178:181], v[186:189], v[40:43]
	v_mfma_f32_16x16x32_bf16 v[40:43], v[182:185], v[0:3], v[44:47]
	v_mfma_f32_16x16x32_bf16 v[0:3], v[196:199], v[0:3], v[36:39]
	v_mfma_f32_16x16x32_bf16 v[44:47], v[182:185], v[12:15], v[224:227]
	v_mfma_f32_16x16x32_bf16 v[36:39], v[154:157], v[8:11], v[0:3]
	v_mfma_f32_16x16x32_bf16 v[0:3], v[196:199], v[12:15], v[32:35]
	v_mfma_f32_16x16x32_bf16 v[40:43], v[190:193], v[8:11], v[40:43]
	v_mfma_f32_16x16x32_bf16 v[44:47], v[190:193], v[186:189], v[44:47]
	v_mfma_f32_16x16x32_bf16 v[32:35], v[154:157], v[186:189], v[0:3]
	s_setprio 0
	s_setprio 1
	v_mfma_f32_16x16x32_bf16 v[0:3], v[166:169], v[96:99], v[28:31]
	v_mfma_f32_16x16x32_bf16 v[8:11], v[170:173], v[100:103], v[0:3]
	v_mfma_f32_16x16x32_bf16 v[0:3], v[166:169], v[212:215], v[24:27]
	v_mfma_f32_16x16x32_bf16 v[28:31], v[170:173], v[142:145], v[0:3]
	v_mfma_f32_16x16x32_bf16 v[0:3], v[174:177], v[96:99], v[20:23]
	v_mfma_f32_16x16x32_bf16 v[12:15], v[178:181], v[100:103], v[0:3]
	v_mfma_f32_16x16x32_bf16 v[0:3], v[174:177], v[212:215], v[16:19]
	v_mfma_f32_16x16x32_bf16 v[24:27], v[178:181], v[142:145], v[0:3]
	v_mfma_f32_16x16x32_bf16 v[0:3], v[182:185], v[96:99], v[146:149]
	v_mfma_f32_16x16x32_bf16 v[4:7], v[196:199], v[96:99], v[4:7]
	v_mfma_f32_16x16x32_bf16 v[20:23], v[190:193], v[100:103], v[0:3]
	v_mfma_f32_16x16x32_bf16 v[0:3], v[182:185], v[212:215], v[162:165]
	v_mfma_f32_16x16x32_bf16 v[16:19], v[154:157], v[100:103], v[4:7]
	v_mfma_f32_16x16x32_bf16 v[4:7], v[196:199], v[212:215], v[150:153]
	v_mfma_f32_16x16x32_bf16 v[0:3], v[190:193], v[142:145], v[0:3]
	v_mfma_f32_16x16x32_bf16 v[4:7], v[154:157], v[142:145], v[4:7]
	s_barrier
	s_setprio 0
	s_cmpk_gt_u32 s94, 0xff
	s_cbranch_scc1 .LBB0_1565
	s_barrier

; #define WAIT_L(n) asm volatile("s_waitcnt lgkmcnt(" #n ")" ::: "memory")
; #define BAR __builtin_amdgcn_s_barrier()
; #define SCHED __builtin_amdgcn_sched_barrier(0)
; template <int EPI>
; __device__ __forceinline__ void gemm_tile(const Params& p, const bf16* __restrict__ A, const bf16* __restrict__ Bt, const int K,
;                                           const int nt, const int brow, const int bcol, int pm, int pn) {
;     ...
;     LDB(B0, 0, 0); SCHED; LDA(At, 0, 0); STAGE(SA(1, 1), A, brow + HALF, t + 1);
;     WAIT_L(8); BAR; WAIT_L(0); MMA(0, 0, At, B0); BAR; SCHED;
;     LDB(B1, 0, 1); STAGE(SB(0, 0), Bt, bcol, t + 2);
;     BAR; WAIT_L(0); MMA(0, 1, At, B1); BAR;
;     LDA(At, 0, 1); STAGE(SA(0, 0), A, brow, t + 2);
;     BAR; WAIT_L(0); MMA(1, 0, At, B0); BAR; SCHED;
.LBB0_1690:
	ds_read_b128 v[156:159], v153
	ds_read_b128 v[160:163], v153 offset:1024
	ds_read_b128 v[164:167], v153 offset:2048
	ds_read_b128 v[168:171], v153 offset:3072
	v_readfirstlane_b32 s42, v154
	v_lshl_add_u64 v[192:193], v[130:131], 0, s[6:7]
	s_mov_b32 m0, s42
	v_readfirstlane_b32 s42, v155
	ds_read_b128 v[172:175], v135
	ds_read_b128 v[176:179], v135 offset:1024
	ds_read_b128 v[180:183], v134
	ds_read_b128 v[184:187], v134 offset:1024
	ds_read_b128 v[188:191], v133
	ds_read_b128 v[196:199], v133 offset:1024
	ds_read_b128 v[200:203], v132
	ds_read_b128 v[208:211], v132 offset:1024
	global_load_lds_dwordx4 v[192:193], off
	v_lshl_add_u64 v[192:193], v[130:131], 0, s[8:9]
	s_mov_b32 m0, s42
	s_nop 0
	global_load_lds_dwordx4 v[192:193], off
	s_waitcnt lgkmcnt(8)
	s_setprio 1
	s_barrier
	s_waitcnt lgkmcnt(0)
	v_mfma_f32_16x16x32_bf16 v[124:127], v[172:175], v[156:159], v[124:127]
	v_mfma_f32_16x16x32_bf16 v[120:123], v[172:175], v[164:167], v[120:123]
	v_mfma_f32_16x16x32_bf16 v[116:119], v[180:183], v[156:159], v[116:119]
	v_mfma_f32_16x16x32_bf16 v[112:115], v[180:183], v[164:167], v[112:115]
	v_mfma_f32_16x16x32_bf16 v[108:111], v[188:191], v[156:159], v[108:111]
	v_mfma_f32_16x16x32_bf16 v[104:107], v[188:191], v[164:167], v[104:107]
	v_mfma_f32_16x16x32_bf16 v[100:103], v[200:203], v[156:159], v[100:103]
	v_mfma_f32_16x16x32_bf16 v[96:99], v[200:203], v[164:167], v[96:99]
	v_mfma_f32_16x16x32_bf16 v[124:127], v[176:179], v[160:163], v[124:127]
	v_mfma_f32_16x16x32_bf16 v[120:123], v[176:179], v[168:171], v[120:123]
	v_mfma_f32_16x16x32_bf16 v[116:119], v[184:187], v[160:163], v[116:119]
	v_mfma_f32_16x16x32_bf16 v[112:115], v[184:187], v[168:171], v[112:115]
	v_mfma_f32_16x16x32_bf16 v[108:111], v[196:199], v[160:163], v[108:111]
	v_mfma_f32_16x16x32_bf16 v[104:107], v[196:199], v[168:171], v[104:107]
	v_mfma_f32_16x16x32_bf16 v[100:103], v[208:211], v[160:163], v[100:103]
	v_mfma_f32_16x16x32_bf16 v[96:99], v[208:211], v[168:171], v[96:99]
	s_barrier
	s_setprio 0
	v_lshl_add_u64 v[192:193], v[130:131], 0, s[4:5]
	v_readfirstlane_b32 s42, v137
	v_lshl_add_u64 v[204:205], v[192:193], 0, s[10:11]
	s_mov_b32 m0, s42
	v_readfirstlane_b32 s42, v138
	ds_read_b128 v[212:215], v152
	ds_read_b128 v[216:219], v152 offset:1024
	ds_read_b128 v[220:223], v152 offset:2048
	ds_read_b128 v[224:227], v152 offset:3072
	global_load_lds_dwordx4 v[204:205], off
	v_lshl_add_u64 v[204:205], v[192:193], 0, s[12:13]
	s_mov_b32 m0, s42
	s_nop 0
	global_load_lds_dwordx4 v[204:205], off
	s_setprio 1
	s_barrier
	s_waitcnt lgkmcnt(0)
	v_mfma_f32_16x16x32_bf16 v[92:95], v[172:175], v[212:215], v[92:95]
	v_mfma_f32_16x16x32_bf16 v[88:91], v[172:175], v[220:223], v[88:91]
	v_mfma_f32_16x16x32_bf16 v[84:87], v[180:183], v[212:215], v[84:87]
	v_mfma_f32_16x16x32_bf16 v[80:83], v[180:183], v[220:223], v[80:83]
	v_mfma_f32_16x16x32_bf16 v[76:79], v[188:191], v[212:215], v[76:79]
	v_mfma_f32_16x16x32_bf16 v[72:75], v[188:191], v[220:223], v[72:75]
	v_mfma_f32_16x16x32_bf16 v[68:71], v[200:203], v[212:215], v[68:71]
	v_mfma_f32_16x16x32_bf16 v[64:67], v[200:203], v[220:223], v[64:67]
	v_mfma_f32_16x16x32_bf16 v[92:95], v[176:179], v[216:219], v[92:95]
	v_mfma_f32_16x16x32_bf16 v[88:91], v[176:179], v[224:227], v[88:91]
	v_mfma_f32_16x16x32_bf16 v[84:87], v[184:187], v[216:219], v[84:87]
	v_mfma_f32_16x16x32_bf16 v[80:83], v[184:187], v[224:227], v[80:83]
	v_mfma_f32_16x16x32_bf16 v[76:79], v[196:199], v[216:219], v[76:79]
	v_mfma_f32_16x16x32_bf16 v[72:75], v[196:199], v[224:227], v[72:75]
	v_mfma_f32_16x16x32_bf16 v[68:71], v[208:211], v[216:219], v[68:71]
	v_mfma_f32_16x16x32_bf16 v[64:67], v[208:211], v[224:227], v[64:67]
	s_barrier
	s_setprio 0
	v_readfirstlane_b32 s42, v136
	v_lshl_add_u64 v[204:205], v[130:131], 0, s[14:15]
	s_mov_b32 m0, s42
	v_readfirstlane_b32 s42, v139
	ds_read_b128 v[172:175], v135 offset:16384
	ds_read_b128 v[176:179], v135 offset:17408
	ds_read_b128 v[180:183], v134 offset:16384
	ds_read_b128 v[184:187], v134 offset:17408
	ds_read_b128 v[188:191], v133 offset:16384
	ds_read_b128 v[196:199], v133 offset:17408
	ds_read_b128 v[200:203], v132 offset:16384
	ds_read_b128 v[208:211], v132 offset:17408
	global_load_lds_dwordx4 v[204:205], off
	v_lshl_add_u64 v[204:205], v[130:131], 0, s[16:17]
	s_mov_b32 m0, s42
	s_nop 0
	global_load_lds_dwordx4 v[204:205], off
	s_setprio 1
	s_barrier
	s_waitcnt lgkmcnt(0)
	v_mfma_f32_16x16x32_bf16 v[60:63], v[172:175], v[156:159], v[60:63]
	v_mfma_f32_16x16x32_bf16 v[56:59], v[172:175], v[164:167], v[56:59]
	v_mfma_f32_16x16x32_bf16 v[52:55], v[180:183], v[156:159], v[52:55]
	v_mfma_f32_16x16x32_bf16 v[48:51], v[180:183], v[164:167], v[48:51]
	v_mfma_f32_16x16x32_bf16 v[44:47], v[188:191], v[156:159], v[44:47]
	v_mfma_f32_16x16x32_bf16 v[40:43], v[188:191], v[164:167], v[40:43]
	v_mfma_f32_16x16x32_bf16 v[36:39], v[200:203], v[156:159], v[36:39]
	v_mfma_f32_16x16x32_bf16 v[32:35], v[200:203], v[164:167], v[32:35]
	v_mfma_f32_16x16x32_bf16 v[60:63], v[176:179], v[160:163], v[60:63]
	v_mfma_f32_16x16x32_bf16 v[56:59], v[176:179], v[168:171], v[56:59]
	v_mfma_f32_16x16x32_bf16 v[52:55], v[184:187], v[160:163], v[52:55]
	v_mfma_f32_16x16x32_bf16 v[48:51], v[184:187], v[168:171], v[48:51]
	v_mfma_f32_16x16x32_bf16 v[44:47], v[196:199], v[160:163], v[44:47]
	v_mfma_f32_16x16x32_bf16 v[40:43], v[196:199], v[168:171], v[40:43]
	v_mfma_f32_16x16x32_bf16 v[36:39], v[208:211], v[160:163], v[36:39]
	v_mfma_f32_16x16x32_bf16 v[32:35], v[208:211], v[168:171], v[32:35]
	s_barrier
; #define WAIT_V(n) asm volatile("s_waitcnt vmcnt(" #n ")" ::: "memory")
; #define WAIT_L(n) asm volatile("s_waitcnt lgkmcnt(" #n ")" ::: "memory")
; #define BAR __builtin_amdgcn_s_barrier()
; #define SCHED __builtin_amdgcn_sched_barrier(0)
; template <int EPI>
; __device__ __forceinline__ void gemm_tile(const Params& p, const bf16* __restrict__ A, const bf16* __restrict__ Bt, const int K,
;                                           const int nt, const int brow, const int bcol, int pm, int pn) {
;     ...
;     STAGE(SB(0, 1), Bt, bcol + HALF, t + 2);
;     WAIT_V(6); BAR; MMA(1, 1, At, B1); BAR;
;     LDB(B0, 1, 0); SCHED; LDA(At, 1, 0); STAGE(SA(0, 1), A, brow + HALF, t + 2);
;     WAIT_L(8); BAR; WAIT_L(0); MMA(0, 0, At, B0); BAR; SCHED;
;     LDB(B1, 1, 1); STAGE(SB(1, 0), Bt, bcol, t + 3);
;     BAR; WAIT_L(0); MMA(0, 1, At, B1); BAR;
;     LDA(At, 1, 1); STAGE(SA(1, 0), A, brow, t + 3);
	s_setprio 0
	v_readfirstlane_b32 s42, v140
	v_lshl_add_u64 v[156:157], v[192:193], 0, s[18:19]
	s_mov_b32 m0, s42
	v_readfirstlane_b32 s42, v142
	global_load_lds_dwordx4 v[156:157], off
	v_lshl_add_u64 v[156:157], v[192:193], 0, s[20:21]
	s_mov_b32 m0, s42
	s_nop 0
	global_load_lds_dwordx4 v[156:157], off
	s_waitcnt vmcnt(6)
	s_setprio 1
	s_barrier
	v_mfma_f32_16x16x32_bf16 v[28:31], v[172:175], v[212:215], v[28:31]
	v_mfma_f32_16x16x32_bf16 v[24:27], v[172:175], v[220:223], v[24:27]
	v_mfma_f32_16x16x32_bf16 v[20:23], v[180:183], v[212:215], v[20:23]
	v_mfma_f32_16x16x32_bf16 v[16:19], v[180:183], v[220:223], v[16:19]
	v_mfma_f32_16x16x32_bf16 v[12:15], v[188:191], v[212:215], v[12:15]
	v_mfma_f32_16x16x32_bf16 v[8:11], v[188:191], v[220:223], v[8:11]
	v_mfma_f32_16x16x32_bf16 v[4:7], v[200:203], v[212:215], v[4:7]
	v_mfma_f32_16x16x32_bf16 v[0:3], v[200:203], v[220:223], v[0:3]
	v_mfma_f32_16x16x32_bf16 v[28:31], v[176:179], v[216:219], v[28:31]
	v_mfma_f32_16x16x32_bf16 v[24:27], v[176:179], v[224:227], v[24:27]
	v_mfma_f32_16x16x32_bf16 v[20:23], v[184:187], v[216:219], v[20:23]
	v_mfma_f32_16x16x32_bf16 v[16:19], v[184:187], v[224:227], v[16:19]
	v_mfma_f32_16x16x32_bf16 v[12:15], v[196:199], v[216:219], v[12:15]
	v_mfma_f32_16x16x32_bf16 v[8:11], v[196:199], v[224:227], v[8:11]
	v_mfma_f32_16x16x32_bf16 v[4:7], v[208:211], v[216:219], v[4:7]
	v_mfma_f32_16x16x32_bf16 v[0:3], v[208:211], v[224:227], v[0:3]
	s_barrier
	s_setprio 0
	ds_read_b128 v[156:159], v145
	ds_read_b128 v[160:163], v145 offset:1024
	ds_read_b128 v[164:167], v145 offset:2048
	ds_read_b128 v[168:171], v145 offset:3072
	v_readfirstlane_b32 s42, v143
	v_lshl_add_u64 v[204:205], v[130:131], 0, s[22:23]
	s_mov_b32 m0, s42
	v_readfirstlane_b32 s42, v144
	ds_read_b128 v[172:175], v135 offset:32768
	ds_read_b128 v[176:179], v135 offset:33792
	ds_read_b128 v[180:183], v134 offset:32768
	ds_read_b128 v[184:187], v134 offset:33792
	ds_read_b128 v[188:191], v133 offset:32768
	ds_read_b128 v[196:199], v133 offset:33792
	ds_read_b128 v[200:203], v132 offset:32768
	ds_read_b128 v[208:211], v132 offset:33792
	global_load_lds_dwordx4 v[204:205], off
	s_mov_b32 m0, s42
	s_nop 0
	global_load_lds_dwordx4 v[130:131], off
	s_waitcnt lgkmcnt(8)
	s_setprio 1
	s_barrier
	s_waitcnt lgkmcnt(0)
	v_mfma_f32_16x16x32_bf16 v[124:127], v[172:175], v[156:159], v[124:127]
	v_mfma_f32_16x16x32_bf16 v[120:123], v[172:175], v[164:167], v[120:123]
	v_mfma_f32_16x16x32_bf16 v[116:119], v[180:183], v[156:159], v[116:119]
	v_mfma_f32_16x16x32_bf16 v[112:115], v[180:183], v[164:167], v[112:115]
	v_mfma_f32_16x16x32_bf16 v[108:111], v[188:191], v[156:159], v[108:111]
	v_mfma_f32_16x16x32_bf16 v[104:107], v[188:191], v[164:167], v[104:107]
	v_mfma_f32_16x16x32_bf16 v[100:103], v[200:203], v[156:159], v[100:103]
	v_mfma_f32_16x16x32_bf16 v[96:99], v[200:203], v[164:167], v[96:99]
	v_mfma_f32_16x16x32_bf16 v[124:127], v[176:179], v[160:163], v[124:127]
	v_mfma_f32_16x16x32_bf16 v[120:123], v[176:179], v[168:171], v[120:123]
	v_mfma_f32_16x16x32_bf16 v[116:119], v[184:187], v[160:163], v[116:119]
	v_mfma_f32_16x16x32_bf16 v[112:115], v[184:187], v[168:171], v[112:115]
	v_mfma_f32_16x16x32_bf16 v[108:111], v[196:199], v[160:163], v[108:111]
	v_mfma_f32_16x16x32_bf16 v[104:107], v[196:199], v[168:171], v[104:107]
	v_mfma_f32_16x16x32_bf16 v[100:103], v[208:211], v[160:163], v[100:103]
	v_mfma_f32_16x16x32_bf16 v[96:99], v[208:211], v[168:171], v[96:99]
	s_barrier
	s_setprio 0
	v_readfirstlane_b32 s42, v146
	v_lshl_add_u64 v[204:205], v[192:193], 0, s[24:25]
	s_mov_b32 m0, s42
	v_readfirstlane_b32 s42, v147
	ds_read_b128 v[212:215], v141
	ds_read_b128 v[216:219], v141 offset:1024
	ds_read_b128 v[220:223], v141 offset:2048
	ds_read_b128 v[224:227], v141 offset:3072
	global_load_lds_dwordx4 v[204:205], off
	v_lshl_add_u64 v[204:205], v[192:193], 0, s[26:27]
	s_mov_b32 m0, s42
	s_nop 0
	global_load_lds_dwordx4 v[204:205], off
	s_setprio 1
	s_barrier
	s_waitcnt lgkmcnt(0)
	v_mfma_f32_16x16x32_bf16 v[92:95], v[172:175], v[212:215], v[92:95]
	v_mfma_f32_16x16x32_bf16 v[88:91], v[172:175], v[220:223], v[88:91]
	v_mfma_f32_16x16x32_bf16 v[84:87], v[180:183], v[212:215], v[84:87]
	v_mfma_f32_16x16x32_bf16 v[80:83], v[180:183], v[220:223], v[80:83]
	v_mfma_f32_16x16x32_bf16 v[76:79], v[188:191], v[212:215], v[76:79]
	v_mfma_f32_16x16x32_bf16 v[72:75], v[188:191], v[220:223], v[72:75]
	v_mfma_f32_16x16x32_bf16 v[68:71], v[200:203], v[212:215], v[68:71]
	v_mfma_f32_16x16x32_bf16 v[64:67], v[200:203], v[220:223], v[64:67]
	v_mfma_f32_16x16x32_bf16 v[92:95], v[176:179], v[216:219], v[92:95]
	v_mfma_f32_16x16x32_bf16 v[88:91], v[176:179], v[224:227], v[88:91]
	v_mfma_f32_16x16x32_bf16 v[84:87], v[184:187], v[216:219], v[84:87]
	v_mfma_f32_16x16x32_bf16 v[80:83], v[184:187], v[224:227], v[80:83]
	v_mfma_f32_16x16x32_bf16 v[76:79], v[196:199], v[216:219], v[76:79]
	v_mfma_f32_16x16x32_bf16 v[72:75], v[196:199], v[224:227], v[72:75]
	v_mfma_f32_16x16x32_bf16 v[68:71], v[208:211], v[216:219], v[68:71]
	v_mfma_f32_16x16x32_bf16 v[64:67], v[208:211], v[224:227], v[64:67]
	s_barrier
	s_setprio 0
	v_readfirstlane_b32 s42, v148
	v_lshl_add_u64 v[204:205], v[130:131], 0, s[28:29]
	s_mov_b32 m0, s42
	v_readfirstlane_b32 s42, v149
	ds_read_b128 v[172:175], v135 offset:49152
	ds_read_b128 v[176:179], v135 offset:50176
	ds_read_b128 v[180:183], v134 offset:49152
	ds_read_b128 v[184:187], v134 offset:50176
	ds_read_b128 v[188:191], v133 offset:49152
	ds_read_b128 v[196:199], v133 offset:50176
	ds_read_b128 v[200:203], v132 offset:49152
	ds_read_b128 v[208:211], v132 offset:50176
	global_load_lds_dwordx4 v[204:205], off
	v_lshl_add_u64 v[204:205], v[130:131], 0, s[30:31]
	s_mov_b32 m0, s42
	s_nop 0
	global_load_lds_dwordx4 v[204:205], off
	s_setprio 1
	s_barrier
; #define WAIT_V(n) asm volatile("s_waitcnt vmcnt(" #n ")" ::: "memory")
; #define WAIT_L(n) asm volatile("s_waitcnt lgkmcnt(" #n ")" ::: "memory")
; #define BAR __builtin_amdgcn_s_barrier()
; #define SCHED __builtin_amdgcn_sched_barrier(0)
; template <int EPI>
; __device__ __forceinline__ void gemm_tile(const Params& p, const bf16* __restrict__ A, const bf16* __restrict__ Bt, const int K,
;                                           const int nt, const int brow, const int bcol, int pm, int pn) {
;     ...
;     BAR; WAIT_L(0); MMA(1, 0, At, B0); BAR; SCHED;
;     STAGE(SB(1, 1), Bt, bcol + HALF, t + 3);
;     WAIT_V(6); BAR; MMA(1, 1, At, B1); BAR;
;   }
;   { LDB(B0, 0, 0); LDA(At, 0, 0); STAGE(SA(1, 1), A, brow + HALF, nt - 1);
;     BAR; WAIT_L(0); MMA(0, 0, At, B0); BAR;
;     LDB(B1, 0, 1); BAR; WAIT_L(0); MMA(0, 1, At, B1); BAR;
	s_waitcnt lgkmcnt(0)
	v_mfma_f32_16x16x32_bf16 v[60:63], v[172:175], v[156:159], v[60:63]
	v_mfma_f32_16x16x32_bf16 v[56:59], v[172:175], v[164:167], v[56:59]
	v_mfma_f32_16x16x32_bf16 v[52:55], v[180:183], v[156:159], v[52:55]
	v_mfma_f32_16x16x32_bf16 v[48:51], v[180:183], v[164:167], v[48:51]
	v_mfma_f32_16x16x32_bf16 v[44:47], v[188:191], v[156:159], v[44:47]
	v_mfma_f32_16x16x32_bf16 v[40:43], v[188:191], v[164:167], v[40:43]
	v_mfma_f32_16x16x32_bf16 v[36:39], v[200:203], v[156:159], v[36:39]
	v_mfma_f32_16x16x32_bf16 v[32:35], v[200:203], v[164:167], v[32:35]
	v_mfma_f32_16x16x32_bf16 v[60:63], v[176:179], v[160:163], v[60:63]
	v_mfma_f32_16x16x32_bf16 v[56:59], v[176:179], v[168:171], v[56:59]
	v_mfma_f32_16x16x32_bf16 v[52:55], v[184:187], v[160:163], v[52:55]
	v_mfma_f32_16x16x32_bf16 v[48:51], v[184:187], v[168:171], v[48:51]
	v_mfma_f32_16x16x32_bf16 v[44:47], v[196:199], v[160:163], v[44:47]
	v_mfma_f32_16x16x32_bf16 v[40:43], v[196:199], v[168:171], v[40:43]
	v_mfma_f32_16x16x32_bf16 v[36:39], v[208:211], v[160:163], v[36:39]
	v_mfma_f32_16x16x32_bf16 v[32:35], v[208:211], v[168:171], v[32:35]
	s_barrier
	s_setprio 0
	v_readfirstlane_b32 s42, v150
	v_lshl_add_u64 v[156:157], v[192:193], 0, s[34:35]
	s_mov_b32 m0, s42
	v_readfirstlane_b32 s42, v151
	global_load_lds_dwordx4 v[156:157], off
	v_lshl_add_u64 v[156:157], v[192:193], 0, s[36:37]
	s_mov_b32 m0, s42
	s_nop 0
	global_load_lds_dwordx4 v[156:157], off
	s_waitcnt vmcnt(6)
	s_setprio 1
	s_barrier
	v_mfma_f32_16x16x32_bf16 v[28:31], v[172:175], v[212:215], v[28:31]
	v_mfma_f32_16x16x32_bf16 v[24:27], v[172:175], v[220:223], v[24:27]
	v_mfma_f32_16x16x32_bf16 v[20:23], v[180:183], v[212:215], v[20:23]
	v_mfma_f32_16x16x32_bf16 v[16:19], v[180:183], v[220:223], v[16:19]
	v_mfma_f32_16x16x32_bf16 v[12:15], v[188:191], v[212:215], v[12:15]
	v_mfma_f32_16x16x32_bf16 v[8:11], v[188:191], v[220:223], v[8:11]
	v_mfma_f32_16x16x32_bf16 v[4:7], v[200:203], v[212:215], v[4:7]
	v_mfma_f32_16x16x32_bf16 v[0:3], v[200:203], v[220:223], v[0:3]
	v_mfma_f32_16x16x32_bf16 v[28:31], v[176:179], v[216:219], v[28:31]
	v_mfma_f32_16x16x32_bf16 v[24:27], v[176:179], v[224:227], v[24:27]
	v_mfma_f32_16x16x32_bf16 v[20:23], v[184:187], v[216:219], v[20:23]
	v_mfma_f32_16x16x32_bf16 v[16:19], v[184:187], v[224:227], v[16:19]
	v_mfma_f32_16x16x32_bf16 v[12:15], v[196:199], v[216:219], v[12:15]
	v_mfma_f32_16x16x32_bf16 v[8:11], v[196:199], v[224:227], v[8:11]
	v_mfma_f32_16x16x32_bf16 v[4:7], v[208:211], v[216:219], v[4:7]
	v_mfma_f32_16x16x32_bf16 v[0:3], v[208:211], v[224:227], v[0:3]
	s_barrier
	s_setprio 0
	s_add_i32 s41, s41, 2
	s_cmp_lt_u32 s41, 4
	v_lshl_add_u64 v[130:131], v[130:131], 0, s[38:39]
	s_cbranch_scc1 .LBB0_1690
	s_mov_b64 s[4:5], 0xb160380
	v_add_u32_e32 v137, 0xc000, v136
	v_lshl_add_u64 v[130:131], v[128:129], 0, s[4:5]
	v_readfirstlane_b32 s4, v137
	s_mov_b32 m0, s4
	ds_read_b128 v[146:149], v153
	ds_read_b128 v[154:157], v153 offset:1024
	ds_read_b128 v[158:161], v153 offset:2048
	ds_read_b128 v[162:165], v153 offset:3072
	ds_read_b128 v[166:169], v135
	ds_read_b128 v[170:173], v135 offset:1024
	ds_read_b128 v[174:177], v134
	ds_read_b128 v[178:181], v134 offset:1024
	ds_read_b128 v[182:185], v133
	ds_read_b128 v[186:189], v133 offset:1024
	ds_read_b128 v[190:193], v132
	ds_read_b128 v[196:199], v132 offset:1024
	global_load_lds_dwordx4 v[130:131], off
	s_mov_b64 s[4:5], 0xb210380
	v_add_u32_e32 v130, 0xe000, v136
	v_lshl_add_u64 v[128:129], v[128:129], 0, s[4:5]
	v_readfirstlane_b32 s4, v130
	s_mov_b32 m0, s4
	s_nop 0
	global_load_lds_dwordx4 v[128:129], off
	s_setprio 1
	s_barrier
	s_waitcnt lgkmcnt(0)
	v_mfma_f32_16x16x32_bf16 v[124:127], v[166:169], v[146:149], v[124:127]
	v_mfma_f32_16x16x32_bf16 v[120:123], v[166:169], v[158:161], v[120:123]
	v_mfma_f32_16x16x32_bf16 v[108:111], v[182:185], v[146:149], v[108:111]
	v_mfma_f32_16x16x32_bf16 v[100:103], v[190:193], v[146:149], v[100:103]
	v_mfma_f32_16x16x32_bf16 v[124:127], v[170:173], v[154:157], v[124:127]
	v_mfma_f32_16x16x32_bf16 v[120:123], v[170:173], v[162:165], v[120:123]
	v_mfma_f32_16x16x32_bf16 v[116:119], v[174:177], v[146:149], v[116:119]
	v_mfma_f32_16x16x32_bf16 v[112:115], v[174:177], v[158:161], v[112:115]
	v_mfma_f32_16x16x32_bf16 v[108:111], v[186:189], v[154:157], v[108:111]
	v_mfma_f32_16x16x32_bf16 v[104:107], v[182:185], v[158:161], v[104:107]
	v_mfma_f32_16x16x32_bf16 v[100:103], v[196:199], v[154:157], v[100:103]
	v_mfma_f32_16x16x32_bf16 v[96:99], v[190:193], v[158:161], v[96:99]
	v_mfma_f32_16x16x32_bf16 v[128:131], v[178:181], v[154:157], v[116:119]
	v_mfma_f32_16x16x32_bf16 v[136:139], v[178:181], v[162:165], v[112:115]
	v_mfma_f32_16x16x32_bf16 v[200:203], v[186:189], v[162:165], v[104:107]
	v_mfma_f32_16x16x32_bf16 v[208:211], v[196:199], v[162:165], v[96:99]
	s_barrier
	s_setprio 0
	s_nop 1
	ds_read_b128 v[96:99], v152
	ds_read_b128 v[104:107], v152 offset:1024
	ds_read_b128 v[112:115], v152 offset:2048
	ds_read_b128 v[116:119], v152 offset:3072
	s_setprio 1
	s_barrier
	s_waitcnt lgkmcnt(0)
	v_mfma_f32_16x16x32_bf16 v[92:95], v[166:169], v[96:99], v[92:95]
	v_mfma_f32_16x16x32_bf16 v[88:91], v[166:169], v[112:115], v[88:91]
	v_mfma_f32_16x16x32_bf16 v[84:87], v[174:177], v[96:99], v[84:87]
	v_mfma_f32_16x16x32_bf16 v[76:79], v[182:185], v[96:99], v[76:79]
	v_mfma_f32_16x16x32_bf16 v[92:95], v[170:173], v[104:107], v[92:95]
	v_mfma_f32_16x16x32_bf16 v[88:91], v[170:173], v[116:119], v[88:91]
	v_mfma_f32_16x16x32_bf16 v[84:87], v[178:181], v[104:107], v[84:87]
	v_mfma_f32_16x16x32_bf16 v[80:83], v[174:177], v[112:115], v[80:83]
	v_mfma_f32_16x16x32_bf16 v[76:79], v[186:189], v[104:107], v[76:79]
	v_mfma_f32_16x16x32_bf16 v[72:75], v[182:185], v[112:115], v[72:75]
	v_mfma_f32_16x16x32_bf16 v[68:71], v[190:193], v[96:99], v[68:71]
	v_mfma_f32_16x16x32_bf16 v[64:67], v[190:193], v[112:115], v[64:67]
	v_mfma_f32_16x16x32_bf16 v[150:153], v[178:181], v[116:119], v[80:83]
	v_mfma_f32_16x16x32_bf16 v[166:169], v[186:189], v[116:119], v[72:75]
	v_mfma_f32_16x16x32_bf16 v[170:173], v[196:199], v[104:107], v[68:71]
	v_mfma_f32_16x16x32_bf16 v[174:177], v[196:199], v[116:119], v[64:67]
	s_barrier
; #define WAIT_V(n) asm volatile("s_waitcnt vmcnt(" #n ")" ::: "memory")
; #define WAIT_L(n) asm volatile("s_waitcnt lgkmcnt(" #n ")" ::: "memory")
; #define BAR __builtin_amdgcn_s_barrier()
; template <int EPI>
; __device__ __forceinline__ void gemm_tile(const Params& p, const bf16* __restrict__ A, const bf16* __restrict__ Bt, const int K,
;                                           const int nt, const int brow, const int bcol, int pm, int pn) {
;     ...
;     LDA(At, 0, 1); WAIT_V(4); BAR; WAIT_L(0); MMA(1, 0, At, B0); MMA(1, 1, At, B1); BAR; }
;   { LDB(B0, 1, 0); LDA(At, 1, 0); WAIT_V(2); BAR; WAIT_L(0); MMA(0, 0, At, B0); BAR;
	s_setprio 0
	s_nop 1
	ds_read_b128 v[64:67], v135 offset:16384
	ds_read_b128 v[68:71], v135 offset:17408
	ds_read_b128 v[72:75], v134 offset:16384
	ds_read_b128 v[80:83], v134 offset:17408
	ds_read_b128 v[178:181], v133 offset:16384
	ds_read_b128 v[182:185], v133 offset:17408
	ds_read_b128 v[186:189], v132 offset:16384
	ds_read_b128 v[190:193], v132 offset:17408
	s_waitcnt vmcnt(4)
	s_setprio 1
	s_barrier
	s_waitcnt lgkmcnt(0)
	v_mfma_f32_16x16x32_bf16 v[60:63], v[64:67], v[146:149], v[60:63]
	v_mfma_f32_16x16x32_bf16 v[56:59], v[64:67], v[158:161], v[56:59]
	v_mfma_f32_16x16x32_bf16 v[52:55], v[72:75], v[146:149], v[52:55]
	v_mfma_f32_16x16x32_bf16 v[44:47], v[178:181], v[146:149], v[44:47]
	v_mfma_f32_16x16x32_bf16 v[60:63], v[68:71], v[154:157], v[60:63]
	v_mfma_f32_16x16x32_bf16 v[56:59], v[68:71], v[162:165], v[56:59]
	v_mfma_f32_16x16x32_bf16 v[52:55], v[80:83], v[154:157], v[52:55]
	v_mfma_f32_16x16x32_bf16 v[48:51], v[72:75], v[158:161], v[48:51]
	v_mfma_f32_16x16x32_bf16 v[44:47], v[182:185], v[154:157], v[44:47]
	v_mfma_f32_16x16x32_bf16 v[40:43], v[178:181], v[158:161], v[40:43]
	v_mfma_f32_16x16x32_bf16 v[36:39], v[186:189], v[146:149], v[36:39]
	v_mfma_f32_16x16x32_bf16 v[32:35], v[186:189], v[158:161], v[32:35]
	v_mfma_f32_16x16x32_bf16 v[196:199], v[80:83], v[162:165], v[48:51]
	v_mfma_f32_16x16x32_bf16 v[212:215], v[182:185], v[162:165], v[40:43]
	v_mfma_f32_16x16x32_bf16 v[146:149], v[190:193], v[154:157], v[36:39]
	v_mfma_f32_16x16x32_bf16 v[154:157], v[190:193], v[162:165], v[32:35]
	s_setprio 0
	s_setprio 1
	v_mfma_f32_16x16x32_bf16 v[28:31], v[64:67], v[96:99], v[28:31]
	v_mfma_f32_16x16x32_bf16 v[24:27], v[64:67], v[112:115], v[24:27]
	v_mfma_f32_16x16x32_bf16 v[20:23], v[72:75], v[96:99], v[20:23]
	v_mfma_f32_16x16x32_bf16 v[12:15], v[178:181], v[96:99], v[12:15]
	v_mfma_f32_16x16x32_bf16 v[28:31], v[68:71], v[104:107], v[28:31]
	v_mfma_f32_16x16x32_bf16 v[24:27], v[68:71], v[116:119], v[24:27]
	v_mfma_f32_16x16x32_bf16 v[20:23], v[80:83], v[104:107], v[20:23]
	v_mfma_f32_16x16x32_bf16 v[16:19], v[72:75], v[112:115], v[16:19]
	v_mfma_f32_16x16x32_bf16 v[12:15], v[182:185], v[104:107], v[12:15]
	v_mfma_f32_16x16x32_bf16 v[8:11], v[178:181], v[112:115], v[8:11]
	v_mfma_f32_16x16x32_bf16 v[4:7], v[186:189], v[96:99], v[4:7]
	v_mfma_f32_16x16x32_bf16 v[0:3], v[186:189], v[112:115], v[0:3]
	v_mfma_f32_16x16x32_bf16 v[158:161], v[80:83], v[116:119], v[16:19]
	v_mfma_f32_16x16x32_bf16 v[162:165], v[182:185], v[116:119], v[8:11]
	v_mfma_f32_16x16x32_bf16 v[178:181], v[190:193], v[104:107], v[4:7]
	v_mfma_f32_16x16x32_bf16 v[182:185], v[190:193], v[116:119], v[0:3]
	s_barrier
	s_setprio 0
	s_nop 1
	ds_read_b128 v[0:3], v145
	ds_read_b128 v[4:7], v145 offset:1024
	ds_read_b128 v[8:11], v145 offset:2048
	ds_read_b128 v[16:19], v145 offset:3072
	ds_read_b128 v[32:35], v135 offset:32768
	ds_read_b128 v[36:39], v135 offset:33792
	ds_read_b128 v[40:43], v134 offset:32768
	ds_read_b128 v[48:51], v134 offset:33792
	ds_read_b128 v[142:145], v133 offset:32768
	ds_read_b128 v[186:189], v133 offset:33792
	ds_read_b128 v[190:193], v132 offset:32768
	ds_read_b128 v[216:219], v132 offset:33792
	s_waitcnt vmcnt(2)
	s_setprio 1
	s_barrier
	s_waitcnt lgkmcnt(0)
	v_mfma_f32_16x16x32_bf16 v[64:67], v[32:35], v[0:3], v[124:127]
	v_mfma_f32_16x16x32_bf16 v[116:119], v[36:39], v[4:7], v[64:67]
	v_mfma_f32_16x16x32_bf16 v[64:67], v[32:35], v[8:11], v[120:123]
	v_mfma_f32_16x16x32_bf16 v[124:127], v[36:39], v[16:19], v[64:67]
	v_mfma_f32_16x16x32_bf16 v[64:67], v[40:43], v[0:3], v[128:131]
	v_mfma_f32_16x16x32_bf16 v[112:115], v[48:51], v[4:7], v[64:67]
	v_mfma_f32_16x16x32_bf16 v[64:67], v[40:43], v[8:11], v[136:139]
	v_mfma_f32_16x16x32_bf16 v[120:123], v[48:51], v[16:19], v[64:67]
	v_mfma_f32_16x16x32_bf16 v[64:67], v[142:145], v[0:3], v[108:111]
	v_mfma_f32_16x16x32_bf16 v[104:107], v[186:189], v[4:7], v[64:67]
	v_mfma_f32_16x16x32_bf16 v[64:67], v[142:145], v[8:11], v[200:203]
	v_mfma_f32_16x16x32_bf16 v[108:111], v[186:189], v[16:19], v[64:67]
	v_mfma_f32_16x16x32_bf16 v[64:67], v[190:193], v[0:3], v[100:103]
	v_mfma_f32_16x16x32_bf16 v[96:99], v[216:219], v[4:7], v[64:67]
	v_mfma_f32_16x16x32_bf16 v[64:67], v[190:193], v[8:11], v[208:211]
	v_mfma_f32_16x16x32_bf16 v[100:103], v[216:219], v[16:19], v[64:67]
	s_barrier
; #define WAIT_V(n) asm volatile("s_waitcnt vmcnt(" #n ")" ::: "memory")
; #define WAIT_L(n) asm volatile("s_waitcnt lgkmcnt(" #n ")" ::: "memory")
; #define BAR __builtin_amdgcn_s_barrier()
; template <int EPI>
; __device__ __forceinline__ void gemm_tile(const Params& p, const bf16* __restrict__ A, const bf16* __restrict__ Bt, const int K,
;                                           const int nt, const int brow, const int bcol, int pm, int pn) {
;     ...
;     LDB(B1, 1, 1); WAIT_V(0); BAR; WAIT_L(0); MMA(0, 1, At, B1); BAR;
;     LDA(At, 1, 1); BAR; WAIT_L(0); MMA(1, 0, At, B0); MMA(1, 1, At, B1); BAR; }
;   if (wr == 0) BAR;
	s_setprio 0
	ds_read_b128 v[128:131], v141
	ds_read_b128 v[136:139], v141 offset:1024
	ds_read_b128 v[200:203], v141 offset:2048
	ds_read_b128 v[208:211], v141 offset:3072
	s_waitcnt vmcnt(0)
	s_setprio 1
	s_barrier
	s_waitcnt lgkmcnt(0)
	v_mfma_f32_16x16x32_bf16 v[64:67], v[32:35], v[128:131], v[92:95]
	v_mfma_f32_16x16x32_bf16 v[32:35], v[32:35], v[200:203], v[88:91]
	v_mfma_f32_16x16x32_bf16 v[80:83], v[36:39], v[208:211], v[32:35]
	v_mfma_f32_16x16x32_bf16 v[32:35], v[40:43], v[128:131], v[84:87]
	v_mfma_f32_16x16x32_bf16 v[68:71], v[48:51], v[136:139], v[32:35]
	v_mfma_f32_16x16x32_bf16 v[32:35], v[40:43], v[200:203], v[150:153]
	v_mfma_f32_16x16x32_bf16 v[84:87], v[48:51], v[208:211], v[32:35]
	v_mfma_f32_16x16x32_bf16 v[32:35], v[142:145], v[128:131], v[76:79]
	v_mfma_f32_16x16x32_bf16 v[72:75], v[186:189], v[136:139], v[32:35]
	v_mfma_f32_16x16x32_bf16 v[32:35], v[142:145], v[200:203], v[166:169]
	v_mfma_f32_16x16x32_bf16 v[88:91], v[186:189], v[208:211], v[32:35]
	v_mfma_f32_16x16x32_bf16 v[32:35], v[190:193], v[128:131], v[170:173]
	v_mfma_f32_16x16x32_bf16 v[76:79], v[216:219], v[136:139], v[32:35]
	v_mfma_f32_16x16x32_bf16 v[32:35], v[190:193], v[200:203], v[174:177]
	v_mfma_f32_16x16x32_bf16 v[64:67], v[36:39], v[136:139], v[64:67]
	v_mfma_f32_16x16x32_bf16 v[92:95], v[216:219], v[208:211], v[32:35]
	s_barrier
	s_setprio 0
	ds_read_b128 v[140:143], v135 offset:49152
	ds_read_b128 v[150:153], v135 offset:50176
	ds_read_b128 v[166:169], v134 offset:49152
	ds_read_b128 v[170:173], v134 offset:50176
	ds_read_b128 v[174:177], v133 offset:49152
	ds_read_b128 v[186:189], v133 offset:50176
	ds_read_b128 v[190:193], v132 offset:49152
	ds_read_b128 v[132:135], v132 offset:50176
	s_setprio 1
	s_barrier
	s_waitcnt lgkmcnt(0)
	v_mfma_f32_16x16x32_bf16 v[36:39], v[140:143], v[8:11], v[56:59]
	v_mfma_f32_16x16x32_bf16 v[40:43], v[166:169], v[8:11], v[196:199]
	v_mfma_f32_16x16x32_bf16 v[32:35], v[140:143], v[0:3], v[60:63]
	v_mfma_f32_16x16x32_bf16 v[48:51], v[150:153], v[16:19], v[36:39]
	v_mfma_f32_16x16x32_bf16 v[36:39], v[166:169], v[0:3], v[52:55]
	v_mfma_f32_16x16x32_bf16 v[52:55], v[170:173], v[16:19], v[40:43]
	v_mfma_f32_16x16x32_bf16 v[40:43], v[174:177], v[0:3], v[44:47]
	v_mfma_f32_16x16x32_bf16 v[44:47], v[174:177], v[8:11], v[212:215]
	v_mfma_f32_16x16x32_bf16 v[0:3], v[190:193], v[0:3], v[146:149]
	v_mfma_f32_16x16x32_bf16 v[56:59], v[186:189], v[16:19], v[44:47]
	v_mfma_f32_16x16x32_bf16 v[44:47], v[132:135], v[4:7], v[0:3]
	v_mfma_f32_16x16x32_bf16 v[0:3], v[190:193], v[8:11], v[154:157]
	v_mfma_f32_16x16x32_bf16 v[32:35], v[150:153], v[4:7], v[32:35]
	v_mfma_f32_16x16x32_bf16 v[36:39], v[170:173], v[4:7], v[36:39]
	v_mfma_f32_16x16x32_bf16 v[40:43], v[186:189], v[4:7], v[40:43]
	v_mfma_f32_16x16x32_bf16 v[60:63], v[132:135], v[16:19], v[0:3]
	s_setprio 0
	s_setprio 1
	v_mfma_f32_16x16x32_bf16 v[4:7], v[140:143], v[200:203], v[24:27]
	v_mfma_f32_16x16x32_bf16 v[8:11], v[166:169], v[200:203], v[158:161]
	v_mfma_f32_16x16x32_bf16 v[16:19], v[150:153], v[208:211], v[4:7]
	v_mfma_f32_16x16x32_bf16 v[4:7], v[166:169], v[128:131], v[20:23]
	v_mfma_f32_16x16x32_bf16 v[20:23], v[170:173], v[208:211], v[8:11]
	v_mfma_f32_16x16x32_bf16 v[8:11], v[174:177], v[128:131], v[12:15]
	v_mfma_f32_16x16x32_bf16 v[12:15], v[174:177], v[200:203], v[162:165]
	v_mfma_f32_16x16x32_bf16 v[0:3], v[140:143], v[128:131], v[28:31]
	v_mfma_f32_16x16x32_bf16 v[24:27], v[186:189], v[208:211], v[12:15]
	v_mfma_f32_16x16x32_bf16 v[12:15], v[190:193], v[128:131], v[178:181]
	v_mfma_f32_16x16x32_bf16 v[28:31], v[190:193], v[200:203], v[182:185]
	v_mfma_f32_16x16x32_bf16 v[0:3], v[150:153], v[136:139], v[0:3]
	v_mfma_f32_16x16x32_bf16 v[4:7], v[170:173], v[136:139], v[4:7]
	v_mfma_f32_16x16x32_bf16 v[8:11], v[186:189], v[136:139], v[8:11]
	v_mfma_f32_16x16x32_bf16 v[12:15], v[132:135], v[136:139], v[12:15]
	v_mfma_f32_16x16x32_bf16 v[28:31], v[132:135], v[208:211], v[28:31]
	s_barrier
	s_setprio 0
	s_cmpk_gt_u32 s40, 0xff
	s_cbranch_scc1 .LBB0_1693
	s_barrier

; #define WAIT_L(n) asm volatile("s_waitcnt lgkmcnt(" #n ")" ::: "memory")
; #define BAR __builtin_amdgcn_s_barrier()
; #define SCHED __builtin_amdgcn_sched_barrier(0)
; template <int EPI>
; __device__ __forceinline__ void gemm_tile(const Params& p, const bf16* __restrict__ A, const bf16* __restrict__ Bt, const int K,
;                                           const int nt, const int brow, const int bcol, int pm, int pn) {
;     ...
;     LDB(B0, 0, 0); SCHED; LDA(At, 0, 0); STAGE(SA(1, 1), A, brow + HALF, t + 1);
;     WAIT_L(8); BAR; WAIT_L(0); MMA(0, 0, At, B0); BAR; SCHED;
;     LDB(B1, 0, 1); STAGE(SB(0, 0), Bt, bcol, t + 2);
;     BAR; WAIT_L(0); MMA(0, 1, At, B1); BAR;
;     LDA(At, 0, 1); STAGE(SA(0, 0), A, brow, t + 2);
;     BAR; WAIT_L(0); MMA(1, 0, At, B0); BAR; SCHED;
.LBB0_1704:
	ds_read_b128 v[158:161], v155
	ds_read_b128 v[162:165], v155 offset:1024
	ds_read_b128 v[166:169], v155 offset:2048
	ds_read_b128 v[170:173], v155 offset:3072
	v_lshl_add_u64 v[204:205], s[70:71], 0, v[130:131]
	s_mov_b64 s[84:85], 0x12662080
	v_lshl_add_u64 v[212:213], v[204:205], 0, s[84:85]
	v_readfirstlane_b32 s84, v154
	s_mov_b32 m0, s84
	s_mov_b64 s[84:85], 0x12712080
	ds_read_b128 v[174:177], v137
	ds_read_b128 v[178:181], v137 offset:1024
	ds_read_b128 v[182:185], v136
	ds_read_b128 v[186:189], v136 offset:1024
	ds_read_b128 v[190:193], v135
	ds_read_b128 v[196:199], v135 offset:1024
	ds_read_b128 v[200:203], v133
	ds_read_b128 v[208:211], v133 offset:1024
	global_load_lds_dwordx4 v[212:213], off
	v_lshl_add_u64 v[212:213], v[204:205], 0, s[84:85]
	v_readfirstlane_b32 s84, v153
	s_mov_b32 m0, s84
	s_nop 0
	global_load_lds_dwordx4 v[212:213], off
	s_waitcnt lgkmcnt(8)
	s_setprio 1
	s_barrier
	s_waitcnt lgkmcnt(0)
	v_mfma_f32_16x16x32_bf16 v[124:127], v[174:177], v[158:161], v[124:127]
	v_mfma_f32_16x16x32_bf16 v[120:123], v[174:177], v[166:169], v[120:123]
	v_mfma_f32_16x16x32_bf16 v[116:119], v[182:185], v[158:161], v[116:119]
	v_mfma_f32_16x16x32_bf16 v[112:115], v[182:185], v[166:169], v[112:115]
	v_mfma_f32_16x16x32_bf16 v[108:111], v[190:193], v[158:161], v[108:111]
	v_mfma_f32_16x16x32_bf16 v[104:107], v[190:193], v[166:169], v[104:107]
	v_mfma_f32_16x16x32_bf16 v[100:103], v[200:203], v[158:161], v[100:103]
	v_mfma_f32_16x16x32_bf16 v[96:99], v[200:203], v[166:169], v[96:99]
	v_mfma_f32_16x16x32_bf16 v[124:127], v[178:181], v[162:165], v[124:127]
	v_mfma_f32_16x16x32_bf16 v[120:123], v[178:181], v[170:173], v[120:123]
	v_mfma_f32_16x16x32_bf16 v[116:119], v[186:189], v[162:165], v[116:119]
	v_mfma_f32_16x16x32_bf16 v[112:115], v[186:189], v[170:173], v[112:115]
	v_mfma_f32_16x16x32_bf16 v[108:111], v[196:199], v[162:165], v[108:111]
	v_mfma_f32_16x16x32_bf16 v[104:107], v[196:199], v[170:173], v[104:107]
	v_mfma_f32_16x16x32_bf16 v[100:103], v[208:211], v[162:165], v[100:103]
	v_mfma_f32_16x16x32_bf16 v[96:99], v[208:211], v[170:173], v[96:99]
	s_barrier
	s_setprio 0
	v_lshl_add_u64 v[228:229], s[68:69], 0, v[130:131]
	s_mov_b64 s[84:85], 0x4c00100
	v_lshl_add_u64 v[230:231], v[228:229], 0, s[84:85]
	v_readfirstlane_b32 s84, v132
	s_mov_b32 m0, s84
	s_mov_b64 s[84:85], 0x4cb0100
	ds_read_b128 v[212:215], v151
	ds_read_b128 v[216:219], v151 offset:1024
	ds_read_b128 v[220:223], v151 offset:2048
	ds_read_b128 v[224:227], v151 offset:3072
	global_load_lds_dwordx4 v[230:231], off
	v_lshl_add_u64 v[230:231], v[228:229], 0, s[84:85]
	v_readfirstlane_b32 s84, v134
	s_mov_b32 m0, s84
	s_nop 0
	global_load_lds_dwordx4 v[230:231], off
	s_setprio 1
	s_barrier
	s_waitcnt lgkmcnt(0)
	v_mfma_f32_16x16x32_bf16 v[92:95], v[174:177], v[212:215], v[92:95]
	v_mfma_f32_16x16x32_bf16 v[88:91], v[174:177], v[220:223], v[88:91]
	v_mfma_f32_16x16x32_bf16 v[84:87], v[182:185], v[212:215], v[84:87]
	v_mfma_f32_16x16x32_bf16 v[80:83], v[182:185], v[220:223], v[80:83]
	v_mfma_f32_16x16x32_bf16 v[76:79], v[190:193], v[212:215], v[76:79]
	v_mfma_f32_16x16x32_bf16 v[72:75], v[190:193], v[220:223], v[72:75]
	v_mfma_f32_16x16x32_bf16 v[68:71], v[200:203], v[212:215], v[68:71]
	v_mfma_f32_16x16x32_bf16 v[64:67], v[200:203], v[220:223], v[64:67]
	v_mfma_f32_16x16x32_bf16 v[92:95], v[178:181], v[216:219], v[92:95]
	v_mfma_f32_16x16x32_bf16 v[88:91], v[178:181], v[224:227], v[88:91]
	v_mfma_f32_16x16x32_bf16 v[84:87], v[186:189], v[216:219], v[84:87]
	v_mfma_f32_16x16x32_bf16 v[80:83], v[186:189], v[224:227], v[80:83]
	v_mfma_f32_16x16x32_bf16 v[76:79], v[196:199], v[216:219], v[76:79]
	v_mfma_f32_16x16x32_bf16 v[72:75], v[196:199], v[224:227], v[72:75]
	v_mfma_f32_16x16x32_bf16 v[68:71], v[208:211], v[216:219], v[68:71]
	v_mfma_f32_16x16x32_bf16 v[64:67], v[208:211], v[224:227], v[64:67]
	s_barrier
	s_setprio 0
	s_mov_b64 s[84:85], 0x12502100
	v_lshl_add_u64 v[230:231], v[204:205], 0, s[84:85]
	v_readfirstlane_b32 s84, v138
	s_mov_b32 m0, s84
	s_mov_b64 s[84:85], 0x125b2100
	ds_read_b128 v[174:177], v137 offset:16384
	ds_read_b128 v[178:181], v137 offset:17408
	ds_read_b128 v[182:185], v136 offset:16384
	ds_read_b128 v[186:189], v136 offset:17408
	ds_read_b128 v[190:193], v135 offset:16384
	ds_read_b128 v[196:199], v135 offset:17408
	ds_read_b128 v[200:203], v133 offset:16384
	ds_read_b128 v[208:211], v133 offset:17408
	global_load_lds_dwordx4 v[230:231], off
	v_lshl_add_u64 v[230:231], v[204:205], 0, s[84:85]
	v_readfirstlane_b32 s84, v139
	s_mov_b32 m0, s84
	s_nop 0
	global_load_lds_dwordx4 v[230:231], off
	s_setprio 1
	s_barrier
	s_waitcnt lgkmcnt(0)
	v_mfma_f32_16x16x32_bf16 v[60:63], v[174:177], v[158:161], v[60:63]
	v_mfma_f32_16x16x32_bf16 v[56:59], v[174:177], v[166:169], v[56:59]
	v_mfma_f32_16x16x32_bf16 v[52:55], v[182:185], v[158:161], v[52:55]
	v_mfma_f32_16x16x32_bf16 v[48:51], v[182:185], v[166:169], v[48:51]
	v_mfma_f32_16x16x32_bf16 v[44:47], v[190:193], v[158:161], v[44:47]
	v_mfma_f32_16x16x32_bf16 v[40:43], v[190:193], v[166:169], v[40:43]
	v_mfma_f32_16x16x32_bf16 v[36:39], v[200:203], v[158:161], v[36:39]
	v_mfma_f32_16x16x32_bf16 v[32:35], v[200:203], v[166:169], v[32:35]
	v_mfma_f32_16x16x32_bf16 v[60:63], v[178:181], v[162:165], v[60:63]
	v_mfma_f32_16x16x32_bf16 v[56:59], v[178:181], v[170:173], v[56:59]
	v_mfma_f32_16x16x32_bf16 v[52:55], v[186:189], v[162:165], v[52:55]
	v_mfma_f32_16x16x32_bf16 v[48:51], v[186:189], v[170:173], v[48:51]
	v_mfma_f32_16x16x32_bf16 v[44:47], v[196:199], v[162:165], v[44:47]
	v_mfma_f32_16x16x32_bf16 v[40:43], v[196:199], v[170:173], v[40:43]
	v_mfma_f32_16x16x32_bf16 v[36:39], v[208:211], v[162:165], v[36:39]
	v_mfma_f32_16x16x32_bf16 v[32:35], v[208:211], v[170:173], v[32:35]
	s_barrier
; #define WAIT_V(n) asm volatile("s_waitcnt vmcnt(" #n ")" ::: "memory")
; #define WAIT_L(n) asm volatile("s_waitcnt lgkmcnt(" #n ")" ::: "memory")
; #define BAR __builtin_amdgcn_s_barrier()
; #define SCHED __builtin_amdgcn_sched_barrier(0)
; template <int EPI>
; __device__ __forceinline__ void gemm_tile(const Params& p, const bf16* __restrict__ A, const bf16* __restrict__ Bt, const int K,
;                                           const int nt, const int brow, const int bcol, int pm, int pn) {
;     ...
;     STAGE(SB(0, 1), Bt, bcol + HALF, t + 2);
;     WAIT_V(6); BAR; MMA(1, 1, At, B1); BAR;
;     LDB(B0, 1, 0); SCHED; LDA(At, 1, 0); STAGE(SA(0, 1), A, brow + HALF, t + 2);
;     WAIT_L(8); BAR; WAIT_L(0); MMA(0, 0, At, B0); BAR; SCHED;
;     LDB(B1, 1, 1); STAGE(SB(1, 0), Bt, bcol, t + 3);
;     BAR; WAIT_L(0); MMA(0, 1, At, B1); BAR;
;     LDA(At, 1, 1); STAGE(SA(1, 0), A, brow, t + 3);
	s_setprio 0
	s_mov_b64 s[84:85], 0x4d60100
	v_lshl_add_u64 v[158:159], v[228:229], 0, s[84:85]
	v_readfirstlane_b32 s84, v140
	s_mov_b32 m0, s84
	s_mov_b64 s[84:85], 0x4e10100
	global_load_lds_dwordx4 v[158:159], off
	v_lshl_add_u64 v[158:159], v[228:229], 0, s[84:85]
	v_readfirstlane_b32 s84, v141
	s_mov_b32 m0, s84
	s_nop 0
	global_load_lds_dwordx4 v[158:159], off
	s_waitcnt vmcnt(6)
	s_setprio 1
	s_barrier
	v_mfma_f32_16x16x32_bf16 v[28:31], v[174:177], v[212:215], v[28:31]
	v_mfma_f32_16x16x32_bf16 v[24:27], v[174:177], v[220:223], v[24:27]
	v_mfma_f32_16x16x32_bf16 v[20:23], v[182:185], v[212:215], v[20:23]
	v_mfma_f32_16x16x32_bf16 v[16:19], v[182:185], v[220:223], v[16:19]
	v_mfma_f32_16x16x32_bf16 v[12:15], v[190:193], v[212:215], v[12:15]
	v_mfma_f32_16x16x32_bf16 v[8:11], v[190:193], v[220:223], v[8:11]
	v_mfma_f32_16x16x32_bf16 v[4:7], v[200:203], v[212:215], v[4:7]
	v_mfma_f32_16x16x32_bf16 v[0:3], v[200:203], v[220:223], v[0:3]
	v_mfma_f32_16x16x32_bf16 v[28:31], v[178:181], v[216:219], v[28:31]
	v_mfma_f32_16x16x32_bf16 v[24:27], v[178:181], v[224:227], v[24:27]
	v_mfma_f32_16x16x32_bf16 v[20:23], v[186:189], v[216:219], v[20:23]
	v_mfma_f32_16x16x32_bf16 v[16:19], v[186:189], v[224:227], v[16:19]
	v_mfma_f32_16x16x32_bf16 v[12:15], v[196:199], v[216:219], v[12:15]
	v_mfma_f32_16x16x32_bf16 v[8:11], v[196:199], v[224:227], v[8:11]
	v_mfma_f32_16x16x32_bf16 v[4:7], v[208:211], v[216:219], v[4:7]
	v_mfma_f32_16x16x32_bf16 v[0:3], v[208:211], v[224:227], v[0:3]
	s_barrier
	s_setprio 0
	ds_read_b128 v[158:161], v145
	ds_read_b128 v[162:165], v145 offset:1024
	ds_read_b128 v[166:169], v145 offset:2048
	ds_read_b128 v[170:173], v145 offset:3072
	s_mov_b64 s[84:85], 0x12662100
	v_lshl_add_u64 v[212:213], v[204:205], 0, s[84:85]
	v_readfirstlane_b32 s84, v143
	s_mov_b32 m0, s84
	s_mov_b64 s[84:85], 0x12712100
	ds_read_b128 v[174:177], v137 offset:32768
	ds_read_b128 v[178:181], v137 offset:33792
	ds_read_b128 v[182:185], v136 offset:32768
	ds_read_b128 v[186:189], v136 offset:33792
	ds_read_b128 v[190:193], v135 offset:32768
	ds_read_b128 v[196:199], v135 offset:33792
	ds_read_b128 v[200:203], v133 offset:32768
	ds_read_b128 v[208:211], v133 offset:33792
	global_load_lds_dwordx4 v[212:213], off
	v_lshl_add_u64 v[212:213], v[204:205], 0, s[84:85]
	v_readfirstlane_b32 s84, v144
	s_mov_b32 m0, s84
	s_nop 0
	global_load_lds_dwordx4 v[212:213], off
	s_waitcnt lgkmcnt(8)
	s_setprio 1
	s_barrier
	s_waitcnt lgkmcnt(0)
	v_mfma_f32_16x16x32_bf16 v[124:127], v[174:177], v[158:161], v[124:127]
	v_mfma_f32_16x16x32_bf16 v[120:123], v[174:177], v[166:169], v[120:123]
	v_mfma_f32_16x16x32_bf16 v[116:119], v[182:185], v[158:161], v[116:119]
	v_mfma_f32_16x16x32_bf16 v[112:115], v[182:185], v[166:169], v[112:115]
	v_mfma_f32_16x16x32_bf16 v[108:111], v[190:193], v[158:161], v[108:111]
	v_mfma_f32_16x16x32_bf16 v[104:107], v[190:193], v[166:169], v[104:107]
	v_mfma_f32_16x16x32_bf16 v[100:103], v[200:203], v[158:161], v[100:103]
	v_mfma_f32_16x16x32_bf16 v[96:99], v[200:203], v[166:169], v[96:99]
	v_mfma_f32_16x16x32_bf16 v[124:127], v[178:181], v[162:165], v[124:127]
	v_mfma_f32_16x16x32_bf16 v[120:123], v[178:181], v[170:173], v[120:123]
	v_mfma_f32_16x16x32_bf16 v[116:119], v[186:189], v[162:165], v[116:119]
	v_mfma_f32_16x16x32_bf16 v[112:115], v[186:189], v[170:173], v[112:115]
	v_mfma_f32_16x16x32_bf16 v[108:111], v[196:199], v[162:165], v[108:111]
	v_mfma_f32_16x16x32_bf16 v[104:107], v[196:199], v[170:173], v[104:107]
	v_mfma_f32_16x16x32_bf16 v[100:103], v[208:211], v[162:165], v[100:103]
	v_mfma_f32_16x16x32_bf16 v[96:99], v[208:211], v[170:173], v[96:99]
	s_barrier
	s_setprio 0
	s_mov_b64 s[84:85], 0x4c00180
	v_lshl_add_u64 v[230:231], v[228:229], 0, s[84:85]
	v_readfirstlane_b32 s84, v146
	s_mov_b32 m0, s84
	v_readfirstlane_b32 s84, v147
	ds_read_b128 v[212:215], v142
	ds_read_b128 v[216:219], v142 offset:1024
	ds_read_b128 v[220:223], v142 offset:2048
	ds_read_b128 v[224:227], v142 offset:3072
	global_load_lds_dwordx4 v[230:231], off
	v_lshl_add_u64 v[230:231], v[228:229], 0, s[10:11]
	s_mov_b32 m0, s84
	s_nop 0
	global_load_lds_dwordx4 v[230:231], off
	s_setprio 1
	s_barrier
	s_waitcnt lgkmcnt(0)
	v_mfma_f32_16x16x32_bf16 v[92:95], v[174:177], v[212:215], v[92:95]
	v_mfma_f32_16x16x32_bf16 v[88:91], v[174:177], v[220:223], v[88:91]
	v_mfma_f32_16x16x32_bf16 v[84:87], v[182:185], v[212:215], v[84:87]
	v_mfma_f32_16x16x32_bf16 v[80:83], v[182:185], v[220:223], v[80:83]
	v_mfma_f32_16x16x32_bf16 v[76:79], v[190:193], v[212:215], v[76:79]
	v_mfma_f32_16x16x32_bf16 v[72:75], v[190:193], v[220:223], v[72:75]
	v_mfma_f32_16x16x32_bf16 v[68:71], v[200:203], v[212:215], v[68:71]
	v_mfma_f32_16x16x32_bf16 v[64:67], v[200:203], v[220:223], v[64:67]
	v_mfma_f32_16x16x32_bf16 v[92:95], v[178:181], v[216:219], v[92:95]
	v_mfma_f32_16x16x32_bf16 v[88:91], v[178:181], v[224:227], v[88:91]
	v_mfma_f32_16x16x32_bf16 v[84:87], v[186:189], v[216:219], v[84:87]
	v_mfma_f32_16x16x32_bf16 v[80:83], v[186:189], v[224:227], v[80:83]
	v_mfma_f32_16x16x32_bf16 v[76:79], v[196:199], v[216:219], v[76:79]
	v_mfma_f32_16x16x32_bf16 v[72:75], v[196:199], v[224:227], v[72:75]
	v_mfma_f32_16x16x32_bf16 v[68:71], v[208:211], v[216:219], v[68:71]
	v_mfma_f32_16x16x32_bf16 v[64:67], v[208:211], v[224:227], v[64:67]
	s_barrier
	s_setprio 0
	v_readfirstlane_b32 s84, v148
	v_lshl_add_u64 v[230:231], v[204:205], 0, s[12:13]
	s_mov_b32 m0, s84
	v_readfirstlane_b32 s84, v149
	ds_read_b128 v[174:177], v137 offset:49152
	ds_read_b128 v[178:181], v137 offset:50176
	ds_read_b128 v[182:185], v136 offset:49152
	ds_read_b128 v[186:189], v136 offset:50176
	ds_read_b128 v[190:193], v135 offset:49152
	ds_read_b128 v[196:199], v135 offset:50176
	ds_read_b128 v[200:203], v133 offset:49152
	ds_read_b128 v[208:211], v133 offset:50176
	global_load_lds_dwordx4 v[230:231], off
	v_lshl_add_u64 v[204:205], v[204:205], 0, s[14:15]
	s_mov_b32 m0, s84
	s_nop 0
	global_load_lds_dwordx4 v[204:205], off
	s_setprio 1
	s_barrier
; #define WAIT_V(n) asm volatile("s_waitcnt vmcnt(" #n ")" ::: "memory")
; #define WAIT_L(n) asm volatile("s_waitcnt lgkmcnt(" #n ")" ::: "memory")
; #define BAR __builtin_amdgcn_s_barrier()
; #define SCHED __builtin_amdgcn_sched_barrier(0)
; template <int EPI>
; __device__ __forceinline__ void gemm_tile(const Params& p, const bf16* __restrict__ A, const bf16* __restrict__ Bt, const int K,
;                                           const int nt, const int brow, const int bcol, int pm, int pn) {
;     ...
;     BAR; WAIT_L(0); MMA(1, 0, At, B0); BAR; SCHED;
;     STAGE(SB(1, 1), Bt, bcol + HALF, t + 3);
;     WAIT_V(6); BAR; MMA(1, 1, At, B1); BAR;
;   }
;   { LDB(B0, 0, 0); LDA(At, 0, 0); STAGE(SA(1, 1), A, brow + HALF, nt - 1);
;     BAR; WAIT_L(0); MMA(0, 0, At, B0); BAR;
;     LDB(B1, 0, 1); BAR; WAIT_L(0); MMA(0, 1, At, B1); BAR;
	s_waitcnt lgkmcnt(0)
	v_mfma_f32_16x16x32_bf16 v[60:63], v[174:177], v[158:161], v[60:63]
	v_mfma_f32_16x16x32_bf16 v[56:59], v[174:177], v[166:169], v[56:59]
	v_mfma_f32_16x16x32_bf16 v[52:55], v[182:185], v[158:161], v[52:55]
	v_mfma_f32_16x16x32_bf16 v[48:51], v[182:185], v[166:169], v[48:51]
	v_mfma_f32_16x16x32_bf16 v[44:47], v[190:193], v[158:161], v[44:47]
	v_mfma_f32_16x16x32_bf16 v[40:43], v[190:193], v[166:169], v[40:43]
	v_mfma_f32_16x16x32_bf16 v[36:39], v[200:203], v[158:161], v[36:39]
	v_mfma_f32_16x16x32_bf16 v[32:35], v[200:203], v[166:169], v[32:35]
	v_mfma_f32_16x16x32_bf16 v[60:63], v[178:181], v[162:165], v[60:63]
	v_mfma_f32_16x16x32_bf16 v[56:59], v[178:181], v[170:173], v[56:59]
	v_mfma_f32_16x16x32_bf16 v[52:55], v[186:189], v[162:165], v[52:55]
	v_mfma_f32_16x16x32_bf16 v[48:51], v[186:189], v[170:173], v[48:51]
	v_mfma_f32_16x16x32_bf16 v[44:47], v[196:199], v[162:165], v[44:47]
	v_mfma_f32_16x16x32_bf16 v[40:43], v[196:199], v[170:173], v[40:43]
	v_mfma_f32_16x16x32_bf16 v[36:39], v[208:211], v[162:165], v[36:39]
	v_mfma_f32_16x16x32_bf16 v[32:35], v[208:211], v[170:173], v[32:35]
	s_barrier
	s_setprio 0
	v_readfirstlane_b32 s84, v150
	v_lshl_add_u64 v[158:159], v[228:229], 0, s[16:17]
	s_mov_b32 m0, s84
	v_readfirstlane_b32 s84, v152
	global_load_lds_dwordx4 v[158:159], off
	v_lshl_add_u64 v[158:159], v[228:229], 0, s[18:19]
	s_mov_b32 m0, s84
	s_nop 0
	global_load_lds_dwordx4 v[158:159], off
	s_waitcnt vmcnt(6)
	s_setprio 1
	s_barrier
	v_mfma_f32_16x16x32_bf16 v[28:31], v[174:177], v[212:215], v[28:31]
	v_mfma_f32_16x16x32_bf16 v[24:27], v[174:177], v[220:223], v[24:27]
	v_mfma_f32_16x16x32_bf16 v[20:23], v[182:185], v[212:215], v[20:23]
	v_mfma_f32_16x16x32_bf16 v[16:19], v[182:185], v[220:223], v[16:19]
	v_mfma_f32_16x16x32_bf16 v[12:15], v[190:193], v[212:215], v[12:15]
	v_mfma_f32_16x16x32_bf16 v[8:11], v[190:193], v[220:223], v[8:11]
	v_mfma_f32_16x16x32_bf16 v[4:7], v[200:203], v[212:215], v[4:7]
	v_mfma_f32_16x16x32_bf16 v[0:3], v[200:203], v[220:223], v[0:3]
	v_mfma_f32_16x16x32_bf16 v[28:31], v[178:181], v[216:219], v[28:31]
	v_mfma_f32_16x16x32_bf16 v[24:27], v[178:181], v[224:227], v[24:27]
	v_mfma_f32_16x16x32_bf16 v[20:23], v[186:189], v[216:219], v[20:23]
	v_mfma_f32_16x16x32_bf16 v[16:19], v[186:189], v[224:227], v[16:19]
	v_mfma_f32_16x16x32_bf16 v[12:15], v[196:199], v[216:219], v[12:15]
	v_mfma_f32_16x16x32_bf16 v[8:11], v[196:199], v[224:227], v[8:11]
	v_mfma_f32_16x16x32_bf16 v[4:7], v[208:211], v[216:219], v[4:7]
	v_mfma_f32_16x16x32_bf16 v[0:3], v[208:211], v[224:227], v[0:3]
	s_barrier
	s_setprio 0
	s_add_i32 s88, s88, 2
	s_add_u32 s68, s68, 0x100
	s_addc_u32 s69, s69, 0
	s_add_u32 s70, s70, 0x100
	s_addc_u32 s71, s71, 0
	s_cmpk_lt_u32 s88, 0x54
	s_cbranch_scc1 .LBB0_1704
	s_add_u32 s68, s62, s87
	s_addc_u32 s69, s63, s86
	v_lshl_add_u64 v[130:131], s[68:69], 0, v[128:129]
	v_readfirstlane_b32 s68, v154
	s_mov_b32 m0, s68
	s_add_u32 s68, s62, s79
	v_lshl_add_u64 v[130:131], v[130:131], 0, s[20:21]
	s_addc_u32 s69, s63, s78
	ds_read_b128 v[138:141], v155
	ds_read_b128 v[146:149], v155 offset:1024
	ds_read_b128 v[158:161], v155 offset:2048
	ds_read_b128 v[162:165], v155 offset:3072
	ds_read_b128 v[166:169], v137
	ds_read_b128 v[170:173], v137 offset:1024
	ds_read_b128 v[174:177], v136
	ds_read_b128 v[178:181], v136 offset:1024
	ds_read_b128 v[182:185], v135
	ds_read_b128 v[186:189], v135 offset:1024
	ds_read_b128 v[190:193], v133
	ds_read_b128 v[196:199], v133 offset:1024
	global_load_lds_dwordx4 v[130:131], off
	v_lshl_add_u64 v[130:131], s[68:69], 0, v[128:129]
	v_readfirstlane_b32 s68, v153
	v_lshl_add_u64 v[130:131], v[130:131], 0, s[20:21]
	s_mov_b32 m0, s68
	s_nop 0
	global_load_lds_dwordx4 v[130:131], off
	s_setprio 1
	s_barrier
	s_waitcnt lgkmcnt(0)
	v_mfma_f32_16x16x32_bf16 v[124:127], v[166:169], v[138:141], v[124:127]
	v_mfma_f32_16x16x32_bf16 v[120:123], v[166:169], v[158:161], v[120:123]
	v_mfma_f32_16x16x32_bf16 v[116:119], v[174:177], v[138:141], v[116:119]
	v_mfma_f32_16x16x32_bf16 v[108:111], v[182:185], v[138:141], v[108:111]
	v_mfma_f32_16x16x32_bf16 v[124:127], v[170:173], v[146:149], v[124:127]
	v_mfma_f32_16x16x32_bf16 v[120:123], v[170:173], v[162:165], v[120:123]
	v_mfma_f32_16x16x32_bf16 v[116:119], v[178:181], v[146:149], v[116:119]
	v_mfma_f32_16x16x32_bf16 v[112:115], v[174:177], v[158:161], v[112:115]
	v_mfma_f32_16x16x32_bf16 v[108:111], v[186:189], v[146:149], v[108:111]
	v_mfma_f32_16x16x32_bf16 v[104:107], v[182:185], v[158:161], v[104:107]
	v_mfma_f32_16x16x32_bf16 v[100:103], v[190:193], v[138:141], v[100:103]
	v_mfma_f32_16x16x32_bf16 v[96:99], v[190:193], v[158:161], v[96:99]
	v_mfma_f32_16x16x32_bf16 v[152:155], v[178:181], v[162:165], v[112:115]
	v_mfma_f32_16x16x32_bf16 v[200:203], v[186:189], v[162:165], v[104:107]
	v_mfma_f32_16x16x32_bf16 v[208:211], v[196:199], v[146:149], v[100:103]
	v_mfma_f32_16x16x32_bf16 v[212:215], v[196:199], v[162:165], v[96:99]
	s_barrier
	s_setprio 0
	s_nop 1
	ds_read_b128 v[96:99], v151
	ds_read_b128 v[100:103], v151 offset:1024
	ds_read_b128 v[104:107], v151 offset:2048
	ds_read_b128 v[112:115], v151 offset:3072
	s_setprio 1
	s_barrier
; #define WAIT_V(n) asm volatile("s_waitcnt vmcnt(" #n ")" ::: "memory")
; #define WAIT_L(n) asm volatile("s_waitcnt lgkmcnt(" #n ")" ::: "memory")
; #define BAR __builtin_amdgcn_s_barrier()
; template <int EPI>
; __device__ __forceinline__ void gemm_tile(const Params& p, const bf16* __restrict__ A, const bf16* __restrict__ Bt, const int K,
;                                           const int nt, const int brow, const int bcol, int pm, int pn) {
;     ...
;     LDB(B1, 0, 1); BAR; WAIT_L(0); MMA(0, 1, At, B1); BAR;
;     LDA(At, 0, 1); WAIT_V(4); BAR; WAIT_L(0); MMA(1, 0, At, B0); MMA(1, 1, At, B1); BAR; }
;   { LDB(B0, 1, 0); LDA(At, 1, 0); WAIT_V(2); BAR; WAIT_L(0); MMA(0, 0, At, B0); BAR;
	s_waitcnt lgkmcnt(0)
	v_mfma_f32_16x16x32_bf16 v[92:95], v[166:169], v[96:99], v[92:95]
	v_mfma_f32_16x16x32_bf16 v[88:91], v[166:169], v[104:107], v[88:91]
	v_mfma_f32_16x16x32_bf16 v[84:87], v[174:177], v[96:99], v[84:87]
	v_mfma_f32_16x16x32_bf16 v[76:79], v[182:185], v[96:99], v[76:79]
	v_mfma_f32_16x16x32_bf16 v[92:95], v[170:173], v[100:103], v[92:95]
	v_mfma_f32_16x16x32_bf16 v[88:91], v[170:173], v[112:115], v[88:91]
	v_mfma_f32_16x16x32_bf16 v[84:87], v[178:181], v[100:103], v[84:87]
	v_mfma_f32_16x16x32_bf16 v[80:83], v[174:177], v[104:107], v[80:83]
	v_mfma_f32_16x16x32_bf16 v[76:79], v[186:189], v[100:103], v[76:79]
	v_mfma_f32_16x16x32_bf16 v[72:75], v[182:185], v[104:107], v[72:75]
	v_mfma_f32_16x16x32_bf16 v[68:71], v[190:193], v[96:99], v[68:71]
	v_mfma_f32_16x16x32_bf16 v[64:67], v[190:193], v[104:107], v[64:67]
	v_mfma_f32_16x16x32_bf16 v[166:169], v[178:181], v[112:115], v[80:83]
	v_mfma_f32_16x16x32_bf16 v[170:173], v[186:189], v[112:115], v[72:75]
	v_mfma_f32_16x16x32_bf16 v[174:177], v[196:199], v[100:103], v[68:71]
	v_mfma_f32_16x16x32_bf16 v[178:181], v[196:199], v[112:115], v[64:67]
	s_barrier
	s_setprio 0
	s_nop 1
	ds_read_b128 v[64:67], v137 offset:16384
	ds_read_b128 v[68:71], v137 offset:17408
	ds_read_b128 v[72:75], v136 offset:16384
	ds_read_b128 v[80:83], v136 offset:17408
	ds_read_b128 v[182:185], v135 offset:16384
	ds_read_b128 v[186:189], v135 offset:17408
	ds_read_b128 v[190:193], v133 offset:16384
	ds_read_b128 v[196:199], v133 offset:17408
	s_waitcnt vmcnt(4)
	s_setprio 1
	s_barrier
	s_waitcnt lgkmcnt(0)
	v_mfma_f32_16x16x32_bf16 v[60:63], v[64:67], v[138:141], v[60:63]
	v_mfma_f32_16x16x32_bf16 v[56:59], v[64:67], v[158:161], v[56:59]
	v_mfma_f32_16x16x32_bf16 v[52:55], v[72:75], v[138:141], v[52:55]
	v_mfma_f32_16x16x32_bf16 v[44:47], v[182:185], v[138:141], v[44:47]
	v_mfma_f32_16x16x32_bf16 v[60:63], v[68:71], v[146:149], v[60:63]
	v_mfma_f32_16x16x32_bf16 v[56:59], v[68:71], v[162:165], v[56:59]
	v_mfma_f32_16x16x32_bf16 v[52:55], v[80:83], v[146:149], v[52:55]
	v_mfma_f32_16x16x32_bf16 v[48:51], v[72:75], v[158:161], v[48:51]
	v_mfma_f32_16x16x32_bf16 v[44:47], v[186:189], v[146:149], v[44:47]
	v_mfma_f32_16x16x32_bf16 v[40:43], v[182:185], v[158:161], v[40:43]
	v_mfma_f32_16x16x32_bf16 v[36:39], v[190:193], v[138:141], v[36:39]
	v_mfma_f32_16x16x32_bf16 v[32:35], v[190:193], v[158:161], v[32:35]
	v_mfma_f32_16x16x32_bf16 v[216:219], v[80:83], v[162:165], v[48:51]
	v_mfma_f32_16x16x32_bf16 v[220:223], v[186:189], v[162:165], v[40:43]
	v_mfma_f32_16x16x32_bf16 v[138:141], v[196:199], v[146:149], v[36:39]
	v_mfma_f32_16x16x32_bf16 v[146:149], v[196:199], v[162:165], v[32:35]
	s_setprio 0
	s_setprio 1
	v_mfma_f32_16x16x32_bf16 v[28:31], v[64:67], v[96:99], v[28:31]
	v_mfma_f32_16x16x32_bf16 v[24:27], v[64:67], v[104:107], v[24:27]
	v_mfma_f32_16x16x32_bf16 v[20:23], v[72:75], v[96:99], v[20:23]
	v_mfma_f32_16x16x32_bf16 v[12:15], v[182:185], v[96:99], v[12:15]
	v_mfma_f32_16x16x32_bf16 v[28:31], v[68:71], v[100:103], v[28:31]
	v_mfma_f32_16x16x32_bf16 v[24:27], v[68:71], v[112:115], v[24:27]
	v_mfma_f32_16x16x32_bf16 v[20:23], v[80:83], v[100:103], v[20:23]
	v_mfma_f32_16x16x32_bf16 v[16:19], v[72:75], v[104:107], v[16:19]
	v_mfma_f32_16x16x32_bf16 v[12:15], v[186:189], v[100:103], v[12:15]
	v_mfma_f32_16x16x32_bf16 v[8:11], v[182:185], v[104:107], v[8:11]
	v_mfma_f32_16x16x32_bf16 v[4:7], v[190:193], v[96:99], v[4:7]
	v_mfma_f32_16x16x32_bf16 v[0:3], v[190:193], v[104:107], v[0:3]
	v_mfma_f32_16x16x32_bf16 v[158:161], v[80:83], v[112:115], v[16:19]
	v_mfma_f32_16x16x32_bf16 v[162:165], v[186:189], v[112:115], v[8:11]
	v_mfma_f32_16x16x32_bf16 v[182:185], v[196:199], v[100:103], v[4:7]
	v_mfma_f32_16x16x32_bf16 v[186:189], v[196:199], v[112:115], v[0:3]
	s_barrier
	s_setprio 0
	s_nop 1
	ds_read_b128 v[0:3], v145
	ds_read_b128 v[4:7], v145 offset:1024
	ds_read_b128 v[8:11], v145 offset:2048
	ds_read_b128 v[16:19], v145 offset:3072
	ds_read_b128 v[32:35], v137 offset:32768
	ds_read_b128 v[36:39], v137 offset:33792
	ds_read_b128 v[40:43], v136 offset:32768
	ds_read_b128 v[48:51], v136 offset:33792
	ds_read_b128 v[190:193], v135 offset:32768
	ds_read_b128 v[196:199], v135 offset:33792
	ds_read_b128 v[224:227], v133 offset:32768
	ds_read_b128 v[228:231], v133 offset:33792
	s_waitcnt vmcnt(2)
	s_setprio 1
	s_barrier
; #define WAIT_V(n) asm volatile("s_waitcnt vmcnt(" #n ")" ::: "memory")
; #define WAIT_L(n) asm volatile("s_waitcnt lgkmcnt(" #n ")" ::: "memory")
; #define BAR __builtin_amdgcn_s_barrier()
; template <int EPI>
; __device__ __forceinline__ void gemm_tile(const Params& p, const bf16* __restrict__ A, const bf16* __restrict__ Bt, const int K,
;                                           const int nt, const int brow, const int bcol, int pm, int pn) {
;     ...
;     LDB(B1, 1, 1); WAIT_V(0); BAR; WAIT_L(0); MMA(0, 1, At, B1); BAR;
;     LDA(At, 1, 1); BAR; WAIT_L(0); MMA(1, 0, At, B0); MMA(1, 1, At, B1); BAR; }
;   if (wr == 0) BAR;
	s_waitcnt lgkmcnt(0)
	v_mfma_f32_16x16x32_bf16 v[64:67], v[32:35], v[0:3], v[124:127]
	v_mfma_f32_16x16x32_bf16 v[96:99], v[36:39], v[4:7], v[64:67]
	v_mfma_f32_16x16x32_bf16 v[64:67], v[32:35], v[8:11], v[120:123]
	v_mfma_f32_16x16x32_bf16 v[112:115], v[36:39], v[16:19], v[64:67]
	v_mfma_f32_16x16x32_bf16 v[64:67], v[40:43], v[0:3], v[116:119]
	v_mfma_f32_16x16x32_bf16 v[100:103], v[48:51], v[4:7], v[64:67]
	v_mfma_f32_16x16x32_bf16 v[64:67], v[40:43], v[8:11], v[152:155]
	v_mfma_f32_16x16x32_bf16 v[116:119], v[48:51], v[16:19], v[64:67]
	v_mfma_f32_16x16x32_bf16 v[64:67], v[190:193], v[0:3], v[108:111]
	v_mfma_f32_16x16x32_bf16 v[104:107], v[196:199], v[4:7], v[64:67]
	v_mfma_f32_16x16x32_bf16 v[64:67], v[190:193], v[8:11], v[200:203]
	v_mfma_f32_16x16x32_bf16 v[120:123], v[196:199], v[16:19], v[64:67]
	v_mfma_f32_16x16x32_bf16 v[64:67], v[224:227], v[0:3], v[208:211]
	v_mfma_f32_16x16x32_bf16 v[108:111], v[228:231], v[4:7], v[64:67]
	v_mfma_f32_16x16x32_bf16 v[64:67], v[224:227], v[8:11], v[212:215]
	v_mfma_f32_16x16x32_bf16 v[124:127], v[228:231], v[16:19], v[64:67]
	s_barrier
	s_setprio 0
	ds_read_b128 v[150:153], v142
	ds_read_b128 v[200:203], v142 offset:1024
	ds_read_b128 v[208:211], v142 offset:2048
	ds_read_b128 v[142:145], v142 offset:3072
	s_waitcnt vmcnt(0)
	s_setprio 1
	s_barrier
	s_waitcnt lgkmcnt(0)
	v_mfma_f32_16x16x32_bf16 v[64:67], v[32:35], v[150:153], v[92:95]
	v_mfma_f32_16x16x32_bf16 v[32:35], v[32:35], v[208:211], v[88:91]
	v_mfma_f32_16x16x32_bf16 v[80:83], v[36:39], v[142:145], v[32:35]
	v_mfma_f32_16x16x32_bf16 v[32:35], v[40:43], v[150:153], v[84:87]
	v_mfma_f32_16x16x32_bf16 v[68:71], v[48:51], v[200:203], v[32:35]
	v_mfma_f32_16x16x32_bf16 v[32:35], v[40:43], v[208:211], v[166:169]
	v_mfma_f32_16x16x32_bf16 v[84:87], v[48:51], v[142:145], v[32:35]
	v_mfma_f32_16x16x32_bf16 v[32:35], v[190:193], v[150:153], v[76:79]
	v_mfma_f32_16x16x32_bf16 v[72:75], v[196:199], v[200:203], v[32:35]
	v_mfma_f32_16x16x32_bf16 v[32:35], v[190:193], v[208:211], v[170:173]
	v_mfma_f32_16x16x32_bf16 v[88:91], v[196:199], v[142:145], v[32:35]
	v_mfma_f32_16x16x32_bf16 v[32:35], v[224:227], v[150:153], v[174:177]
	v_mfma_f32_16x16x32_bf16 v[76:79], v[228:231], v[200:203], v[32:35]
	v_mfma_f32_16x16x32_bf16 v[32:35], v[224:227], v[208:211], v[178:181]
	v_mfma_f32_16x16x32_bf16 v[64:67], v[36:39], v[200:203], v[64:67]
	v_mfma_f32_16x16x32_bf16 v[92:95], v[228:231], v[142:145], v[32:35]
	s_barrier
	s_setprio 0
	ds_read_b128 v[166:169], v137 offset:49152
	ds_read_b128 v[170:173], v137 offset:50176
	ds_read_b128 v[174:177], v136 offset:49152
	ds_read_b128 v[178:181], v136 offset:50176
	ds_read_b128 v[190:193], v135 offset:49152
	ds_read_b128 v[134:137], v135 offset:50176
	ds_read_b128 v[196:199], v133 offset:49152
	ds_read_b128 v[130:133], v133 offset:50176
	s_setprio 1
	s_barrier
	s_waitcnt lgkmcnt(0)
	v_mfma_f32_16x16x32_bf16 v[36:39], v[166:169], v[8:11], v[56:59]
	v_mfma_f32_16x16x32_bf16 v[40:43], v[174:177], v[8:11], v[216:219]
	v_mfma_f32_16x16x32_bf16 v[32:35], v[166:169], v[0:3], v[60:63]
	v_mfma_f32_16x16x32_bf16 v[48:51], v[170:173], v[16:19], v[36:39]
	v_mfma_f32_16x16x32_bf16 v[36:39], v[174:177], v[0:3], v[52:55]
	v_mfma_f32_16x16x32_bf16 v[52:55], v[178:181], v[16:19], v[40:43]
	v_mfma_f32_16x16x32_bf16 v[40:43], v[190:193], v[0:3], v[44:47]
	v_mfma_f32_16x16x32_bf16 v[44:47], v[190:193], v[8:11], v[220:223]
	v_mfma_f32_16x16x32_bf16 v[0:3], v[196:199], v[0:3], v[138:141]
	v_mfma_f32_16x16x32_bf16 v[56:59], v[134:137], v[16:19], v[44:47]
	v_mfma_f32_16x16x32_bf16 v[44:47], v[130:133], v[4:7], v[0:3]
	v_mfma_f32_16x16x32_bf16 v[0:3], v[196:199], v[8:11], v[146:149]
	v_mfma_f32_16x16x32_bf16 v[32:35], v[170:173], v[4:7], v[32:35]
	v_mfma_f32_16x16x32_bf16 v[36:39], v[178:181], v[4:7], v[36:39]
	v_mfma_f32_16x16x32_bf16 v[40:43], v[134:137], v[4:7], v[40:43]
	v_mfma_f32_16x16x32_bf16 v[60:63], v[130:133], v[16:19], v[0:3]
	s_setprio 0
	s_setprio 1
	v_mfma_f32_16x16x32_bf16 v[4:7], v[166:169], v[208:211], v[24:27]
	v_mfma_f32_16x16x32_bf16 v[8:11], v[174:177], v[208:211], v[158:161]
	v_mfma_f32_16x16x32_bf16 v[16:19], v[170:173], v[142:145], v[4:7]
	v_mfma_f32_16x16x32_bf16 v[4:7], v[174:177], v[150:153], v[20:23]
	v_mfma_f32_16x16x32_bf16 v[20:23], v[178:181], v[142:145], v[8:11]
	v_mfma_f32_16x16x32_bf16 v[8:11], v[190:193], v[150:153], v[12:15]
	v_mfma_f32_16x16x32_bf16 v[12:15], v[190:193], v[208:211], v[162:165]
	v_mfma_f32_16x16x32_bf16 v[0:3], v[166:169], v[150:153], v[28:31]
	v_mfma_f32_16x16x32_bf16 v[24:27], v[134:137], v[142:145], v[12:15]
	v_mfma_f32_16x16x32_bf16 v[12:15], v[196:199], v[150:153], v[182:185]
	v_mfma_f32_16x16x32_bf16 v[28:31], v[196:199], v[208:211], v[186:189]
	v_mfma_f32_16x16x32_bf16 v[0:3], v[170:173], v[200:203], v[0:3]
	v_mfma_f32_16x16x32_bf16 v[4:7], v[178:181], v[200:203], v[4:7]
	v_mfma_f32_16x16x32_bf16 v[8:11], v[134:137], v[200:203], v[8:11]
	v_mfma_f32_16x16x32_bf16 v[12:15], v[130:133], v[200:203], v[12:15]
	v_mfma_f32_16x16x32_bf16 v[28:31], v[130:133], v[142:145], v[28:31]
	s_barrier
	s_setprio 0
	s_cmpk_gt_u32 s77, 0xff
	s_cbranch_scc1 .LBB0_1696
	s_barrier
	s_branch .LBB0_1696
